# speedup vs baseline: 1.0364x; 1.0066x over previous
.LBB0_347:
	s_or_b64 exec, exec, s[90:91]
	v_mov_b32_e32 v0, v180
	s_waitcnt lgkmcnt(0)
	s_barrier
	s_nop 0
	v_cmp_gt_i32_e32 vcc, s56, v0
	s_and_saveexec_b64 s[90:91], vcc
	s_cbranch_execz .LBB0_349
	v_ashrrev_i32_e32 v5, 31, v0
	v_add_u32_sdwa v5, v0, v5 dst_sel:DWORD dst_unused:UNUSED_PAD src0_sel:DWORD src1_sel:BYTE_3
	v_ashrrev_i32_e32 v5, 8, v5
	v_mul_i32_i24_e32 v7, 0x100, v5
	v_sub_u32_e32 v0, v0, v7
	v_mul_i32_i24_e32 v5, 0x1100, v5
	v_lshlrev_b32_e32 v5, 3, v5
	v_ashrrev_i32_e32 v13, 4, v0
	v_add_u32_e32 v7, 0, v5
	v_lshlrev_b32_e32 v11, 3, v0
	v_lshlrev_b32_e32 v13, 3, v13
	v_add3_u32 v7, v7, v11, v13
	ds_read_b64 v[26:27], v7 offset:6272
	ds_read_b64 v[28:29], v7 offset:8448
	ds_read_b64 v[82:83], v7 offset:10624
	ds_read_b64 v[96:97], v7 offset:12800
	ds_read_b64 v[106:107], v7 offset:14976
	ds_read_b64 v[108:109], v7 offset:17152
	ds_read_b64 v[110:111], v7 offset:19328
	ds_read_b64 v[114:115], v7 offset:21504
	ds_read_b64 v[116:117], v7 offset:23680
	ds_read_b64 v[118:119], v7 offset:25856
	ds_read_b64 v[120:121], v7 offset:28032
	ds_read_b64 v[122:123], v7 offset:30208
	ds_read_b64 v[124:125], v7 offset:32384
	ds_read_b64 v[126:127], v7 offset:34560
	ds_read_b64 v[128:129], v7 offset:36736
	ds_read_b64 v[130:131], v7 offset:38912
	s_waitcnt lgkmcnt(7)
	v_pk_add_f32 v[132:133], v[26:27], v[116:117]
	v_pk_add_f32 v[26:27], v[26:27], v[116:117] neg_lo:[0,1] neg_hi:[0,1]
	s_waitcnt lgkmcnt(3)
	v_pk_add_f32 v[116:117], v[106:107], v[124:125]
	v_pk_add_f32 v[106:107], v[106:107], v[124:125] neg_lo:[0,1] neg_hi:[0,1]
	s_mov_b32 s61, s34
	v_xor_b32_e32 v125, 0x80000000, v106
	v_mov_b32_e32 v124, v107
	v_pk_add_f32 v[134:135], v[26:27], v[124:125]
	v_pk_add_f32 v[26:27], v[26:27], v[124:125] neg_lo:[0,1] neg_hi:[0,1]
	v_pk_add_f32 v[124:125], v[28:29], v[118:119]
	v_pk_add_f32 v[28:29], v[28:29], v[118:119] neg_lo:[0,1] neg_hi:[0,1]
	s_waitcnt lgkmcnt(2)
	v_pk_add_f32 v[118:119], v[108:109], v[126:127]
	v_pk_add_f32 v[108:109], v[108:109], v[126:127] neg_lo:[0,1] neg_hi:[0,1]
	v_pk_add_f32 v[106:107], v[132:133], v[116:117]
	v_xor_b32_e32 v127, 0x80000000, v108
	v_mov_b32_e32 v126, v109
	v_pk_add_f32 v[108:109], v[124:125], v[118:119]
	v_pk_add_f32 v[118:119], v[124:125], v[118:119] neg_lo:[0,1] neg_hi:[0,1]
	v_pk_add_f32 v[124:125], v[82:83], v[120:121]
	v_pk_add_f32 v[82:83], v[82:83], v[120:121] neg_lo:[0,1] neg_hi:[0,1]
	s_waitcnt lgkmcnt(1)
	v_pk_add_f32 v[120:121], v[110:111], v[128:129]
	v_pk_add_f32 v[110:111], v[110:111], v[128:129] neg_lo:[0,1] neg_hi:[0,1]
	v_pk_add_f32 v[116:117], v[132:133], v[116:117] neg_lo:[0,1] neg_hi:[0,1]
	v_pk_add_f32 v[132:133], v[28:29], v[126:127]
	v_pk_add_f32 v[28:29], v[28:29], v[126:127] neg_lo:[0,1] neg_hi:[0,1]
	v_xor_b32_e32 v127, 0x80000000, v110
	v_mov_b32_e32 v126, v111
	v_pk_add_f32 v[110:111], v[124:125], v[120:121]
	v_pk_add_f32 v[120:121], v[124:125], v[120:121] neg_lo:[0,1] neg_hi:[0,1]
	v_pk_add_f32 v[124:125], v[96:97], v[122:123]
	v_pk_add_f32 v[96:97], v[96:97], v[122:123] neg_lo:[0,1] neg_hi:[0,1]
	s_waitcnt lgkmcnt(0)
	v_pk_add_f32 v[122:123], v[114:115], v[130:131]
	v_pk_add_f32 v[114:115], v[114:115], v[130:131] neg_lo:[0,1] neg_hi:[0,1]
	v_pk_add_f32 v[128:129], v[82:83], v[126:127]
	v_pk_add_f32 v[82:83], v[82:83], v[126:127] neg_lo:[0,1] neg_hi:[0,1]
	v_xor_b32_e32 v127, 0x80000000, v114
	v_mov_b32_e32 v126, v115
	v_pk_add_f32 v[114:115], v[124:125], v[122:123]
	v_pk_add_f32 v[122:123], v[124:125], v[122:123] neg_lo:[0,1] neg_hi:[0,1]
	v_pk_mul_f32 v[124:125], v[132:133], s[24:25] op_sel_hi:[1,0]
	v_pk_add_f32 v[130:131], v[96:97], v[126:127]
	v_pk_add_f32 v[96:97], v[96:97], v[126:127] neg_lo:[0,1] neg_hi:[0,1]
	v_pk_fma_f32 v[126:127], v[132:133], s[26:27], v[124:125] op_sel:[0,0,1] op_sel_hi:[1,0,0] neg_hi:[0,0,1]
	s_mov_b32 s35, s24
	v_pk_mul_f32 v[124:125], v[118:119], s[28:29] op_sel_hi:[1,0]
	v_add_u32_e32 v5, s57, v5
	v_pk_fma_f32 v[132:133], v[118:119], s[28:29], v[124:125] op_sel:[0,0,1] op_sel_hi:[1,0,0] neg_hi:[0,0,1]
	v_pk_mul_f32 v[124:125], v[28:29], s[26:27] op_sel_hi:[1,0]
	v_pk_fma_f32 v[136:137], v[28:29], s[24:25], v[124:125] op_sel:[0,0,1] op_sel_hi:[1,0,0] neg_hi:[0,0,1]
	v_lshlrev_b32_e32 v0, 7, v0
	v_pk_mul_f32 v[28:29], v[128:129], s[28:29] op_sel_hi:[1,0]
	v_add3_u32 v0, v5, v0, v11
	v_pk_fma_f32 v[124:125], v[128:129], s[28:29], v[28:29] op_sel:[0,0,1] op_sel_hi:[1,0,0] neg_hi:[0,0,1]
	s_nop 0
	v_pk_fma_f32 v[28:29], v[120:121], 0, v[120:121] op_sel:[0,0,1] op_sel_hi:[1,0,0] neg_hi:[0,0,1]
	s_nop 0
	v_pk_mul_f32 v[120:121], v[82:83], s[30:31] op_sel_hi:[1,0]
	s_nop 0
	v_pk_fma_f32 v[128:129], v[82:83], s[30:31], v[120:121] op_sel:[0,0,1] op_sel_hi:[1,0,0] neg_lo:[0,0,1]
	v_pk_mul_f32 v[120:121], v[130:131], s[26:27] op_sel_hi:[1,0]
	v_pk_fma_f32 v[138:139], v[130:131], s[24:25], v[120:121] op_sel:[0,0,1] op_sel_hi:[1,0,0] neg_hi:[0,0,1]
	v_pk_add_f32 v[82:83], v[26:27], v[128:129]
	v_pk_mul_f32 v[120:121], v[122:123], s[30:31] op_sel_hi:[1,0]
	v_pk_add_f32 v[26:27], v[26:27], v[128:129] neg_lo:[0,1] neg_hi:[0,1]
	v_pk_fma_f32 v[130:131], v[122:123], s[30:31], v[120:121] op_sel:[0,0,1] op_sel_hi:[1,0,0] neg_lo:[0,0,1]
	s_nop 0
	v_pk_mul_f32 v[120:121], v[96:97], s[60:61] op_sel:[1,0]
	v_pk_add_f32 v[118:119], v[132:133], v[130:131] neg_lo:[0,1] neg_hi:[0,1]
	v_pk_fma_f32 v[96:97], v[96:97], s[34:35], v[120:121] op_sel_hi:[0,1,1]
	v_pk_add_f32 v[120:121], v[106:107], v[110:111]
	v_pk_add_f32 v[106:107], v[106:107], v[110:111] neg_lo:[0,1] neg_hi:[0,1]
	v_pk_add_f32 v[110:111], v[108:109], v[114:115]
	v_pk_add_f32 v[108:109], v[108:109], v[114:115] neg_lo:[0,1] neg_hi:[0,1]
	s_nop 0
	v_xor_b32_e32 v115, 0x80000000, v108
	v_mov_b32_e32 v114, v109
	v_pk_add_f32 v[108:109], v[120:121], v[110:111]
	v_pk_add_f32 v[122:123], v[106:107], v[114:115]
	v_pk_add_f32 v[110:111], v[120:121], v[110:111] neg_lo:[0,1] neg_hi:[0,1]
	v_pk_add_f32 v[106:107], v[106:107], v[114:115] neg_lo:[0,1] neg_hi:[0,1]
	v_pk_add_f32 v[114:115], v[134:135], v[124:125]
	v_pk_add_f32 v[120:121], v[134:135], v[124:125] neg_lo:[0,1] neg_hi:[0,1]
	v_pk_add_f32 v[124:125], v[126:127], v[138:139]
	v_pk_add_f32 v[126:127], v[126:127], v[138:139] neg_lo:[0,1] neg_hi:[0,1]
	s_nop 0
	v_xor_b32_e32 v135, 0x80000000, v126
	v_mov_b32_e32 v134, v127
	v_pk_add_f32 v[126:127], v[114:115], v[124:125]
	v_pk_add_f32 v[114:115], v[114:115], v[124:125] neg_lo:[0,1] neg_hi:[0,1]
	v_pk_add_f32 v[124:125], v[116:117], v[28:29]
	v_pk_add_f32 v[28:29], v[116:117], v[28:29] neg_lo:[0,1] neg_hi:[0,1]
	v_pk_add_f32 v[116:117], v[132:133], v[130:131]
	v_xor_b32_e32 v131, 0x80000000, v118
	v_mov_b32_e32 v130, v119
	v_pk_add_f32 v[118:119], v[124:125], v[116:117]
	v_pk_add_f32 v[116:117], v[124:125], v[116:117] neg_lo:[0,1] neg_hi:[0,1]
	v_pk_add_f32 v[124:125], v[136:137], v[96:97]
	v_pk_add_f32 v[96:97], v[136:137], v[96:97] neg_lo:[0,1] neg_hi:[0,1]
	v_pk_add_f32 v[138:139], v[120:121], v[134:135]
	v_xor_b32_e32 v129, 0x80000000, v96
	v_mov_b32_e32 v128, v97
	v_pk_add_f32 v[120:121], v[120:121], v[134:135] neg_lo:[0,1] neg_hi:[0,1]
	v_pk_add_f32 v[132:133], v[28:29], v[130:131]
	v_pk_add_f32 v[28:29], v[28:29], v[130:131] neg_lo:[0,1] neg_hi:[0,1]
	v_pk_add_f32 v[96:97], v[82:83], v[124:125]
	v_pk_add_f32 v[130:131], v[26:27], v[128:129]
	v_pk_add_f32 v[82:83], v[82:83], v[124:125] neg_lo:[0,1] neg_hi:[0,1]
	v_pk_add_f32 v[26:27], v[26:27], v[128:129] neg_lo:[0,1] neg_hi:[0,1]
	ds_write2_b64 v0, v[108:109], v[126:127] offset1:1
	ds_write2_b64 v0, v[118:119], v[96:97] offset0:2 offset1:3
	ds_write2_b64 v0, v[122:123], v[138:139] offset0:4 offset1:5
	ds_write2_b64 v0, v[132:133], v[130:131] offset0:6 offset1:7
	ds_write2_b64 v0, v[110:111], v[114:115] offset0:8 offset1:9
	ds_write2_b64 v0, v[116:117], v[82:83] offset0:10 offset1:11
	ds_write2_b64 v0, v[106:107], v[120:121] offset0:12 offset1:13
	ds_write2_b64 v0, v[28:29], v[26:27] offset0:14 offset1:15
.LBB0_349:
	s_or_b64 exec, exec, s[90:91]
	v_mov_b32_e32 v0, v180
	s_waitcnt lgkmcnt(0)
	s_barrier
	s_nop 0
	v_cmp_gt_i32_e32 vcc, s56, v0
	s_and_saveexec_b64 s[90:91], vcc
	s_cbranch_execz .LBB0_351
	v_ashrrev_i32_e32 v5, 31, v0
	v_add_u32_sdwa v5, v0, v5 dst_sel:DWORD dst_unused:UNUSED_PAD src0_sel:DWORD src1_sel:BYTE_3
	v_ashrrev_i32_e32 v5, 8, v5
	v_mul_i32_i24_e32 v7, 0x100, v5
	v_sub_u32_e32 v7, v0, v7
	v_ashrrev_i16_e32 v0, 15, v7
	v_lshrrev_b16_e32 v0, 12, v0
	v_add_u16_e32 v11, v7, v0
	v_ashrrev_i16_e32 v0, 4, v11
	v_and_b32_e32 v11, -16, v11
	v_mul_i32_i24_e32 v5, 0x1100, v5
	v_sub_u16_e32 v11, v7, v11
	v_lshlrev_b32_e32 v5, 3, v5
	v_lshlrev_b32_e32 v17, 3, v7
	v_ashrrev_i32_e32 v7, 4, v7
	v_add_u32_e32 v13, s57, v5
	v_lshlrev_b32_e32 v7, 3, v7
	v_add3_u32 v7, v13, v17, v7
	ds_read_b64 v[26:27], v7
	ds_read_b64 v[28:29], v7 offset:2176
	ds_read_b64 v[114:115], v7 offset:4352
	ds_read_b64 v[116:117], v7 offset:6528
	ds_read_b64 v[118:119], v7 offset:8704
	ds_read_b64 v[122:123], v7 offset:10880
	ds_read_b64 v[124:125], v7 offset:13056
	ds_read_b64 v[126:127], v7 offset:15232
	ds_read_b64 v[128:129], v7 offset:17408
	ds_read_b64 v[130:131], v7 offset:19584
	ds_read_b64 v[132:133], v7 offset:21760
	ds_read_b64 v[134:135], v7 offset:23936
	ds_read_b64 v[136:137], v7 offset:26112
	ds_read_b64 v[138:139], v7 offset:28288
	ds_read_b64 v[140:141], v7 offset:30464
	ds_read_b64 v[96:97], v7 offset:32640
	v_bfe_i32 v7, v11, 0, 16
	v_mad_i32_i24 v11, v7, s27, 0
	v_add_u32_e32 v13, 0x808, v11
	ds_read2_b64 v[108:111], v13 offset1:1
	v_add_u32_e32 v13, 0x818, v11
	s_mov_b32 s61, s34
	s_mov_b32 s35, s24
	v_bfe_i32 v0, v0, 0, 16
	s_waitcnt lgkmcnt(0)
	v_pk_mul_f32 v[82:83], v[28:29], v[108:109] op_sel:[1,1] op_sel_hi:[1,0]
	v_lshl_add_u32 v0, v0, 8, v7
	v_pk_fma_f32 v[106:107], v[28:29], v[108:109], v[82:83] op_sel_hi:[0,1,1] neg_lo:[0,0,1]
	v_pk_mul_f32 v[28:29], v[114:115], v[110:111] op_sel:[1,1] op_sel_hi:[1,0]
	v_lshlrev_b32_e32 v7, 3, v0
	v_pk_fma_f32 v[82:83], v[114:115], v[110:111], v[28:29] op_sel_hi:[0,1,1] neg_lo:[0,0,1]
	ds_read2_b64 v[108:111], v13 offset1:1
	v_add_u32_e32 v13, 0x828, v11
	v_ashrrev_i32_e32 v0, 4, v0
	v_add_u32_e32 v5, 0, v5
	s_waitcnt lgkmcnt(0)
	v_pk_mul_f32 v[114:115], v[116:117], v[108:109] op_sel:[1,1] op_sel_hi:[1,0]
	v_lshlrev_b32_e32 v0, 3, v0
	v_pk_fma_f32 v[28:29], v[116:117], v[108:109], v[114:115] op_sel_hi:[0,1,1] neg_lo:[0,0,1]
	v_pk_mul_f32 v[108:109], v[118:119], v[110:111] op_sel:[1,1] op_sel_hi:[1,0]
	v_add3_u32 v0, v5, v7, v0
	v_pk_fma_f32 v[116:117], v[118:119], v[110:111], v[108:109] op_sel_hi:[0,1,1] neg_lo:[0,0,1]
	ds_read2_b64 v[118:121], v13 offset1:1
	v_add_u32_e32 v13, 0x838, v11
	v_add_u32_e32 v5, 0x1800, v0
	v_add_u32_e32 v0, 0x1c00, v0
	s_waitcnt lgkmcnt(0)
	v_pk_mul_f32 v[108:109], v[122:123], v[118:119] op_sel:[1,1] op_sel_hi:[1,0]
	s_nop 0
	v_pk_fma_f32 v[114:115], v[122:123], v[118:119], v[108:109] op_sel_hi:[0,1,1] neg_lo:[0,0,1]
	v_pk_mul_f32 v[108:109], v[124:125], v[120:121] op_sel:[1,1] op_sel_hi:[1,0]
	s_nop 0
	v_pk_fma_f32 v[110:111], v[124:125], v[120:121], v[108:109] op_sel_hi:[0,1,1] neg_lo:[0,0,1]
	ds_read2_b64 v[118:121], v13 offset1:1
	v_add_u32_e32 v13, 0x848, v11
	s_waitcnt lgkmcnt(0)
	v_pk_mul_f32 v[122:123], v[126:127], v[118:119] op_sel:[1,1] op_sel_hi:[1,0]
	s_nop 0
	v_pk_fma_f32 v[108:109], v[126:127], v[118:119], v[122:123] op_sel_hi:[0,1,1] neg_lo:[0,0,1]
	v_pk_mul_f32 v[118:119], v[128:129], v[120:121] op_sel:[1,1] op_sel_hi:[1,0]
	s_nop 0
	v_pk_fma_f32 v[124:125], v[128:129], v[120:121], v[118:119] op_sel_hi:[0,1,1] neg_lo:[0,0,1]
	ds_read2_b64 v[126:129], v13 offset1:1
	v_add_u32_e32 v13, 0x858, v11
	s_waitcnt lgkmcnt(0)
	v_pk_mul_f32 v[118:119], v[130:131], v[126:127] op_sel:[1,1] op_sel_hi:[1,0]
	s_nop 0
	v_pk_fma_f32 v[122:123], v[130:131], v[126:127], v[118:119] op_sel_hi:[0,1,1] neg_lo:[0,0,1]
	v_pk_mul_f32 v[118:119], v[132:133], v[128:129] op_sel:[1,1] op_sel_hi:[1,0]
	s_nop 0
	v_pk_fma_f32 v[120:121], v[132:133], v[128:129], v[118:119] op_sel_hi:[0,1,1] neg_lo:[0,0,1]
	ds_read2_b64 v[126:129], v13 offset1:1
	v_add_u32_e32 v13, 0x868, v11
	s_waitcnt lgkmcnt(0)
	v_pk_mul_f32 v[130:131], v[134:135], v[126:127] op_sel:[1,1] op_sel_hi:[1,0]
	s_nop 0
	v_pk_fma_f32 v[118:119], v[134:135], v[126:127], v[130:131] op_sel_hi:[0,1,1] neg_lo:[0,0,1]
	ds_read2_b64 v[132:135], v13 offset1:1
	v_pk_mul_f32 v[126:127], v[136:137], v[128:129] op_sel:[1,1] op_sel_hi:[1,0]
	s_nop 0
	v_pk_fma_f32 v[130:131], v[136:137], v[128:129], v[126:127] op_sel_hi:[0,1,1] neg_lo:[0,0,1]
	s_waitcnt lgkmcnt(0)
	v_pk_mul_f32 v[126:127], v[138:139], v[132:133] op_sel:[1,1] op_sel_hi:[1,0]
	s_nop 0
	v_pk_fma_f32 v[128:129], v[138:139], v[132:133], v[126:127] op_sel_hi:[0,1,1] neg_lo:[0,0,1]
	v_pk_mul_f32 v[132:133], v[140:141], v[134:135] op_sel:[1,1] op_sel_hi:[1,0]
	v_pk_fma_f32 v[126:127], v[140:141], v[134:135], v[132:133] op_sel_hi:[0,1,1] neg_lo:[0,0,1]
	ds_read_b64 v[132:133], v11 offset:2168
	s_waitcnt lgkmcnt(0)
	v_pk_mul_f32 v[134:135], v[96:97], v[132:133] op_sel:[1,1] op_sel_hi:[1,0]
	s_nop 0
	v_pk_fma_f32 v[136:137], v[96:97], v[132:133], v[134:135] op_sel_hi:[0,1,1] neg_lo:[0,0,1]
	v_pk_add_f32 v[96:97], v[26:27], v[124:125]
	v_pk_add_f32 v[26:27], v[26:27], v[124:125] neg_lo:[0,1] neg_hi:[0,1]
	v_pk_add_f32 v[124:125], v[116:117], v[130:131]
	v_pk_add_f32 v[116:117], v[116:117], v[130:131] neg_lo:[0,1] neg_hi:[0,1]
	s_nop 0
	v_xor_b32_e32 v131, 0x80000000, v116
	v_mov_b32_e32 v130, v117
	v_pk_add_f32 v[116:117], v[96:97], v[124:125]
	v_pk_add_f32 v[96:97], v[96:97], v[124:125] neg_lo:[0,1] neg_hi:[0,1]
	v_pk_add_f32 v[124:125], v[106:107], v[122:123]
	v_pk_add_f32 v[106:107], v[106:107], v[122:123] neg_lo:[0,1] neg_hi:[0,1]
	v_pk_add_f32 v[122:123], v[114:115], v[128:129]
	v_pk_add_f32 v[114:115], v[114:115], v[128:129] neg_lo:[0,1] neg_hi:[0,1]
	v_pk_add_f32 v[132:133], v[26:27], v[130:131]
	v_xor_b32_e32 v129, 0x80000000, v114
	v_mov_b32_e32 v128, v115
	v_pk_add_f32 v[114:115], v[124:125], v[122:123]
	v_pk_add_f32 v[122:123], v[124:125], v[122:123] neg_lo:[0,1] neg_hi:[0,1]
	v_pk_add_f32 v[124:125], v[82:83], v[120:121]
	v_pk_add_f32 v[82:83], v[82:83], v[120:121] neg_lo:[0,1] neg_hi:[0,1]
	v_pk_add_f32 v[120:121], v[110:111], v[126:127]
	v_pk_add_f32 v[110:111], v[110:111], v[126:127] neg_lo:[0,1] neg_hi:[0,1]
	v_pk_add_f32 v[26:27], v[26:27], v[130:131] neg_lo:[0,1] neg_hi:[0,1]
	v_pk_add_f32 v[130:131], v[106:107], v[128:129]
	v_xor_b32_e32 v127, 0x80000000, v110
	v_mov_b32_e32 v126, v111
	v_pk_add_f32 v[110:111], v[124:125], v[120:121]
	v_pk_add_f32 v[120:121], v[124:125], v[120:121] neg_lo:[0,1] neg_hi:[0,1]
	v_pk_add_f32 v[124:125], v[28:29], v[118:119]
	v_pk_add_f32 v[28:29], v[28:29], v[118:119] neg_lo:[0,1] neg_hi:[0,1]
	v_pk_add_f32 v[118:119], v[108:109], v[136:137]
	v_pk_add_f32 v[108:109], v[108:109], v[136:137] neg_lo:[0,1] neg_hi:[0,1]
	v_pk_add_f32 v[106:107], v[106:107], v[128:129] neg_lo:[0,1] neg_hi:[0,1]
	v_pk_add_f32 v[128:129], v[82:83], v[126:127]
	v_pk_add_f32 v[82:83], v[82:83], v[126:127] neg_lo:[0,1] neg_hi:[0,1]
	v_xor_b32_e32 v127, 0x80000000, v108
	v_mov_b32_e32 v126, v109
	v_pk_add_f32 v[108:109], v[124:125], v[118:119]
	v_pk_add_f32 v[118:119], v[124:125], v[118:119] neg_lo:[0,1] neg_hi:[0,1]
	v_pk_mul_f32 v[124:125], v[130:131], s[24:25] op_sel_hi:[1,0]
	v_pk_add_f32 v[134:135], v[28:29], v[126:127]
	v_pk_add_f32 v[28:29], v[28:29], v[126:127] neg_lo:[0,1] neg_hi:[0,1]
	v_pk_fma_f32 v[126:127], v[130:131], s[26:27], v[124:125] op_sel:[0,0,1] op_sel_hi:[1,0,0] neg_hi:[0,0,1]
	s_nop 0
	v_pk_mul_f32 v[124:125], v[122:123], s[28:29] op_sel_hi:[1,0]
	s_nop 0
	v_pk_fma_f32 v[130:131], v[122:123], s[28:29], v[124:125] op_sel:[0,0,1] op_sel_hi:[1,0,0] neg_hi:[0,0,1]
	v_pk_mul_f32 v[124:125], v[106:107], s[26:27] op_sel_hi:[1,0]
	v_pk_fma_f32 v[136:137], v[106:107], s[24:25], v[124:125] op_sel:[0,0,1] op_sel_hi:[1,0,0] neg_hi:[0,0,1]
	s_nop 0
	v_pk_mul_f32 v[106:107], v[128:129], s[28:29] op_sel_hi:[1,0]
	s_nop 0
	v_pk_fma_f32 v[124:125], v[128:129], s[28:29], v[106:107] op_sel:[0,0,1] op_sel_hi:[1,0,0] neg_hi:[0,0,1]
	s_nop 0
	v_pk_fma_f32 v[106:107], v[120:121], 0, v[120:121] op_sel:[0,0,1] op_sel_hi:[1,0,0] neg_hi:[0,0,1]
	s_nop 0
	v_pk_mul_f32 v[120:121], v[82:83], s[30:31] op_sel_hi:[1,0]
	s_nop 0
	v_pk_fma_f32 v[128:129], v[82:83], s[30:31], v[120:121] op_sel:[0,0,1] op_sel_hi:[1,0,0] neg_lo:[0,0,1]
	v_pk_mul_f32 v[120:121], v[134:135], s[26:27] op_sel_hi:[1,0]
	v_pk_fma_f32 v[138:139], v[134:135], s[24:25], v[120:121] op_sel:[0,0,1] op_sel_hi:[1,0,0] neg_hi:[0,0,1]
	v_pk_add_f32 v[82:83], v[26:27], v[128:129]
	v_pk_mul_f32 v[120:121], v[118:119], s[30:31] op_sel_hi:[1,0]
	v_pk_add_f32 v[26:27], v[26:27], v[128:129] neg_lo:[0,1] neg_hi:[0,1]
	v_pk_fma_f32 v[134:135], v[118:119], s[30:31], v[120:121] op_sel:[0,0,1] op_sel_hi:[1,0,0] neg_lo:[0,0,1]
	s_nop 0
	v_pk_mul_f32 v[118:119], v[28:29], s[60:61] op_sel:[1,0]
	v_pk_add_f32 v[122:123], v[130:131], v[134:135] neg_lo:[0,1] neg_hi:[0,1]
	v_pk_fma_f32 v[28:29], v[28:29], s[34:35], v[118:119] op_sel_hi:[0,1,1]
	v_pk_add_f32 v[118:119], v[116:117], v[110:111]
	v_pk_add_f32 v[110:111], v[116:117], v[110:111] neg_lo:[0,1] neg_hi:[0,1]
	v_pk_add_f32 v[116:117], v[114:115], v[108:109]
	v_pk_add_f32 v[108:109], v[114:115], v[108:109] neg_lo:[0,1] neg_hi:[0,1]
	s_nop 0
	v_xor_b32_e32 v115, 0x80000000, v108
	v_mov_b32_e32 v114, v109
	v_pk_add_f32 v[108:109], v[118:119], v[116:117]
	v_pk_add_f32 v[120:121], v[110:111], v[114:115]
	v_pk_add_f32 v[116:117], v[118:119], v[116:117] neg_lo:[0,1] neg_hi:[0,1]
	v_pk_add_f32 v[110:111], v[110:111], v[114:115] neg_lo:[0,1] neg_hi:[0,1]
	v_pk_add_f32 v[114:115], v[132:133], v[124:125]
	v_pk_add_f32 v[118:119], v[132:133], v[124:125] neg_lo:[0,1] neg_hi:[0,1]
	v_pk_add_f32 v[124:125], v[126:127], v[138:139]
	v_pk_add_f32 v[126:127], v[126:127], v[138:139] neg_lo:[0,1] neg_hi:[0,1]
	s_nop 0
	v_xor_b32_e32 v133, 0x80000000, v126
	v_mov_b32_e32 v132, v127
	v_pk_add_f32 v[126:127], v[114:115], v[124:125]
	v_pk_add_f32 v[114:115], v[114:115], v[124:125] neg_lo:[0,1] neg_hi:[0,1]
	v_pk_add_f32 v[124:125], v[96:97], v[106:107]
	v_pk_add_f32 v[96:97], v[96:97], v[106:107] neg_lo:[0,1] neg_hi:[0,1]
	v_pk_add_f32 v[106:107], v[130:131], v[134:135]
	v_xor_b32_e32 v131, 0x80000000, v122
	v_mov_b32_e32 v130, v123
	v_pk_add_f32 v[122:123], v[124:125], v[106:107]
	v_pk_add_f32 v[106:107], v[124:125], v[106:107] neg_lo:[0,1] neg_hi:[0,1]
	v_pk_add_f32 v[124:125], v[136:137], v[28:29]
	v_pk_add_f32 v[28:29], v[136:137], v[28:29] neg_lo:[0,1] neg_hi:[0,1]
	v_pk_add_f32 v[138:139], v[118:119], v[132:133]
	v_xor_b32_e32 v129, 0x80000000, v28
	v_mov_b32_e32 v128, v29
	v_pk_add_f32 v[118:119], v[118:119], v[132:133] neg_lo:[0,1] neg_hi:[0,1]
	v_pk_add_f32 v[132:133], v[96:97], v[130:131]
	v_pk_add_f32 v[96:97], v[96:97], v[130:131] neg_lo:[0,1] neg_hi:[0,1]
	v_pk_add_f32 v[130:131], v[26:27], v[128:129]
	v_pk_add_f32 v[26:27], v[26:27], v[128:129] neg_lo:[0,1] neg_hi:[0,1]
	v_pk_add_f32 v[28:29], v[82:83], v[124:125]
	v_pk_add_f32 v[82:83], v[82:83], v[124:125] neg_lo:[0,1] neg_hi:[0,1]
	ds_write2_b64 v5, v[108:109], v[126:127] offset0:16 offset1:33
	ds_write2_b64 v5, v[122:123], v[28:29] offset0:50 offset1:67
	ds_write2_b64 v5, v[120:121], v[138:139] offset0:84 offset1:101
	ds_write2_b64 v5, v[132:133], v[130:131] offset0:118 offset1:135
	ds_write2_b64 v5, v[116:117], v[114:115] offset0:152 offset1:169
	ds_write2_b64 v5, v[106:107], v[82:83] offset0:186 offset1:203
	ds_write2_b64 v5, v[110:111], v[118:119] offset0:220 offset1:237
	ds_write2_b64 v0, v[96:97], v[26:27] offset0:126 offset1:143
.LBB0_351:
	s_or_b64 exec, exec, s[90:91]
	v_mov_b32_e32 v0, v180
	s_waitcnt lgkmcnt(0)
	s_barrier
	s_nop 0
	v_cmp_gt_i32_e32 vcc, s56, v0
	s_and_saveexec_b64 s[90:91], vcc
	s_cbranch_execz .LBB0_353
	v_ashrrev_i32_e32 v5, 31, v0
	v_add_u32_sdwa v5, v0, v5 dst_sel:DWORD dst_unused:UNUSED_PAD src0_sel:DWORD src1_sel:BYTE_3
	v_ashrrev_i32_e32 v5, 8, v5
	v_mul_i32_i24_e32 v7, 0x100, v5
	v_sub_u32_e32 v0, v0, v7
	v_mul_i32_i24_e32 v5, 0x1100, v5
	v_lshlrev_b32_e32 v7, 3, v0
	v_ashrrev_i32_e32 v0, 4, v0
	v_lshlrev_b32_e32 v5, 3, v5
	v_lshlrev_b32_e32 v0, 3, v0
	v_add_u32_e32 v11, 0, v7
	v_add3_u32 v13, v11, v5, v0
	ds_read_b64 v[26:27], v13 offset:6272
	ds_read_b64 v[28:29], v13 offset:8448
	ds_read_b64 v[82:83], v13 offset:10624
	ds_read_b64 v[96:97], v13 offset:12800
	ds_read_b64 v[106:107], v13 offset:14976
	ds_read_b64 v[108:109], v13 offset:17152
	ds_read_b64 v[110:111], v13 offset:19328
	ds_read_b64 v[114:115], v13 offset:21504
	ds_read_b64 v[116:117], v13 offset:34560
	ds_read_b64 v[118:119], v13 offset:36736
	ds_read_b64 v[120:121], v13 offset:38912
	ds_read_b64 v[122:123], v11
	ds_read_b64 v[124:125], v13 offset:23680
	ds_read_b64 v[126:127], v13 offset:25856
	ds_read_b64 v[128:129], v13 offset:28032
	ds_read_b64 v[130:131], v13 offset:30208
	ds_read_b64 v[132:133], v13 offset:32384
	s_waitcnt lgkmcnt(5)
	v_pk_mul_f32 v[134:135], v[28:29], v[122:123] op_sel:[1,1] op_sel_hi:[1,0]
	s_mov_b32 s61, s34
	v_pk_fma_f32 v[136:137], v[28:29], v[122:123], v[134:135] op_sel_hi:[0,1,1] neg_lo:[0,0,1]
	v_pk_mul_f32 v[28:29], v[122:123], v[122:123] op_sel:[1,1] op_sel_hi:[1,0]
	s_mov_b32 s35, s24
	v_pk_fma_f32 v[134:135], v[122:123], v[122:123], v[28:29] op_sel_hi:[1,0,1] neg_lo:[0,0,1] neg_hi:[0,0,1]
	v_pk_fma_f32 v[28:29], v[122:123], v[122:123], v[28:29] op_sel_hi:[1,0,1]
	v_mov_b32_e32 v138, v134
	v_mov_b32_e32 v139, v29
	v_pk_mul_f32 v[28:29], v[82:83], v[28:29] op_sel:[1,1] op_sel_hi:[0,1]
	v_pk_fma_f32 v[140:141], v[82:83], v[134:135], v[28:29] op_sel_hi:[1,0,1] neg_lo:[0,0,1]
	v_pk_mul_f32 v[82:83], v[122:123], v[138:139] op_sel:[1,0] op_sel_hi:[0,1]
	v_pk_mul_f32 v[28:29], v[122:123], v[138:139]
	v_pk_add_f32 v[82:83], v[82:83], v[82:83] op_sel:[0,1] op_sel_hi:[0,1]
	v_pk_mul_f32 v[134:135], v[96:97], v[82:83]
	v_pk_add_f32 v[28:29], v[28:29], v[28:29] op_sel:[0,1] op_sel_hi:[0,1] neg_lo:[0,1] neg_hi:[0,1]
	v_pk_fma_f32 v[138:139], v[96:97], v[28:29], v[134:135] op_sel:[0,0,1] op_sel_hi:[1,1,0] neg_lo:[0,0,1]
	v_pk_mul_f32 v[82:83], v[122:123], v[82:83]
	v_pk_fma_f32 v[96:97], v[122:123], v[28:29], v[82:83] op_sel:[0,0,1] op_sel_hi:[1,1,0] neg_lo:[0,0,1] neg_hi:[0,0,1]
	v_pk_fma_f32 v[28:29], v[122:123], v[28:29], v[82:83] op_sel:[0,0,1] op_sel_hi:[1,1,0]
	v_mov_b32_e32 v82, v96
	v_mov_b32_e32 v83, v29
	v_pk_mul_f32 v[28:29], v[106:107], v[28:29] op_sel:[1,1] op_sel_hi:[0,1]
	v_pk_fma_f32 v[134:135], v[106:107], v[96:97], v[28:29] op_sel_hi:[1,0,1] neg_lo:[0,0,1]
	v_add_u32_e32 v5, s57, v5
	v_pk_mul_f32 v[28:29], v[122:123], v[82:83]
	v_pk_mul_f32 v[82:83], v[122:123], v[82:83] op_sel:[1,0] op_sel_hi:[0,1]
	v_pk_add_f32 v[82:83], v[82:83], v[82:83] op_sel:[0,1] op_sel_hi:[0,1]
	v_pk_mul_f32 v[96:97], v[108:109], v[82:83]
	v_pk_add_f32 v[28:29], v[28:29], v[28:29] op_sel:[0,1] op_sel_hi:[0,1] neg_lo:[0,1] neg_hi:[0,1]
	v_pk_fma_f32 v[106:107], v[108:109], v[28:29], v[96:97] op_sel:[0,0,1] op_sel_hi:[1,1,0] neg_lo:[0,0,1]
	v_pk_mul_f32 v[82:83], v[122:123], v[82:83]
	v_pk_fma_f32 v[96:97], v[122:123], v[28:29], v[82:83] op_sel:[0,0,1] op_sel_hi:[1,1,0] neg_lo:[0,0,1] neg_hi:[0,0,1]
	v_pk_fma_f32 v[28:29], v[122:123], v[28:29], v[82:83] op_sel:[0,0,1] op_sel_hi:[1,1,0]
	v_mov_b32_e32 v82, v96
	v_mov_b32_e32 v83, v29
	v_pk_mul_f32 v[28:29], v[110:111], v[28:29] op_sel:[1,1] op_sel_hi:[0,1]
	v_pk_fma_f32 v[108:109], v[110:111], v[96:97], v[28:29] op_sel_hi:[1,0,1] neg_lo:[0,0,1]
	v_add3_u32 v0, v5, v7, v0
	v_pk_mul_f32 v[28:29], v[122:123], v[82:83]
	v_pk_mul_f32 v[82:83], v[122:123], v[82:83] op_sel:[1,0] op_sel_hi:[0,1]
	v_pk_add_f32 v[82:83], v[82:83], v[82:83] op_sel:[0,1] op_sel_hi:[0,1]
	v_pk_mul_f32 v[96:97], v[114:115], v[82:83]
	v_pk_add_f32 v[28:29], v[28:29], v[28:29] op_sel:[0,1] op_sel_hi:[0,1] neg_lo:[0,1] neg_hi:[0,1]
	v_pk_fma_f32 v[110:111], v[114:115], v[28:29], v[96:97] op_sel:[0,0,1] op_sel_hi:[1,1,0] neg_lo:[0,0,1]
	v_pk_mul_f32 v[82:83], v[122:123], v[82:83]
	v_pk_fma_f32 v[96:97], v[122:123], v[28:29], v[82:83] op_sel:[0,0,1] op_sel_hi:[1,1,0] neg_lo:[0,0,1] neg_hi:[0,0,1]
	v_pk_fma_f32 v[28:29], v[122:123], v[28:29], v[82:83] op_sel:[0,0,1] op_sel_hi:[1,1,0]
	v_mov_b32_e32 v82, v96
	v_mov_b32_e32 v83, v29
	s_waitcnt lgkmcnt(4)
	v_pk_mul_f32 v[28:29], v[124:125], v[28:29] op_sel:[1,1] op_sel_hi:[0,1]
	v_pk_fma_f32 v[114:115], v[124:125], v[96:97], v[28:29] op_sel_hi:[1,0,1] neg_lo:[0,0,1]
	s_nop 0
	v_pk_mul_f32 v[28:29], v[122:123], v[82:83]
	v_pk_mul_f32 v[82:83], v[122:123], v[82:83] op_sel:[1,0] op_sel_hi:[0,1]
	v_pk_add_f32 v[82:83], v[82:83], v[82:83] op_sel:[0,1] op_sel_hi:[0,1]
	s_waitcnt lgkmcnt(3)
	v_pk_mul_f32 v[96:97], v[126:127], v[82:83]
	v_pk_add_f32 v[28:29], v[28:29], v[28:29] op_sel:[0,1] op_sel_hi:[0,1] neg_lo:[0,1] neg_hi:[0,1]
	v_pk_fma_f32 v[124:125], v[126:127], v[28:29], v[96:97] op_sel:[0,0,1] op_sel_hi:[1,1,0] neg_lo:[0,0,1]
	v_pk_mul_f32 v[82:83], v[122:123], v[82:83]
	v_pk_fma_f32 v[96:97], v[122:123], v[28:29], v[82:83] op_sel:[0,0,1] op_sel_hi:[1,1,0] neg_lo:[0,0,1] neg_hi:[0,0,1]
	v_pk_fma_f32 v[28:29], v[122:123], v[28:29], v[82:83] op_sel:[0,0,1] op_sel_hi:[1,1,0]
	v_mov_b32_e32 v82, v96
	v_mov_b32_e32 v83, v29
	s_waitcnt lgkmcnt(2)
	v_pk_mul_f32 v[28:29], v[128:129], v[28:29] op_sel:[1,1] op_sel_hi:[0,1]
	v_pk_fma_f32 v[126:127], v[128:129], v[96:97], v[28:29] op_sel_hi:[1,0,1] neg_lo:[0,0,1]
	s_nop 0
	v_pk_mul_f32 v[28:29], v[122:123], v[82:83]
	v_pk_mul_f32 v[82:83], v[122:123], v[82:83] op_sel:[1,0] op_sel_hi:[0,1]
	v_pk_add_f32 v[82:83], v[82:83], v[82:83] op_sel:[0,1] op_sel_hi:[0,1]
	s_waitcnt lgkmcnt(1)
	v_pk_mul_f32 v[96:97], v[130:131], v[82:83]
	v_pk_add_f32 v[28:29], v[28:29], v[28:29] op_sel:[0,1] op_sel_hi:[0,1] neg_lo:[0,1] neg_hi:[0,1]
	v_pk_fma_f32 v[128:129], v[130:131], v[28:29], v[96:97] op_sel:[0,0,1] op_sel_hi:[1,1,0] neg_lo:[0,0,1]
	v_pk_mul_f32 v[82:83], v[122:123], v[82:83]
	v_pk_fma_f32 v[96:97], v[122:123], v[28:29], v[82:83] op_sel:[0,0,1] op_sel_hi:[1,1,0] neg_lo:[0,0,1] neg_hi:[0,0,1]
	v_pk_fma_f32 v[28:29], v[122:123], v[28:29], v[82:83] op_sel:[0,0,1] op_sel_hi:[1,1,0]
	v_mov_b32_e32 v82, v96
	v_mov_b32_e32 v83, v29
	s_waitcnt lgkmcnt(0)
	v_pk_mul_f32 v[28:29], v[132:133], v[28:29] op_sel:[1,1] op_sel_hi:[0,1]
	v_pk_fma_f32 v[130:131], v[132:133], v[96:97], v[28:29] op_sel_hi:[1,0,1] neg_lo:[0,0,1]
	s_nop 0
	v_pk_mul_f32 v[28:29], v[122:123], v[82:83]
	v_pk_mul_f32 v[82:83], v[122:123], v[82:83] op_sel:[1,0] op_sel_hi:[0,1]
	v_pk_add_f32 v[82:83], v[82:83], v[82:83] op_sel:[0,1] op_sel_hi:[0,1]
	v_pk_mul_f32 v[96:97], v[116:117], v[82:83]
	v_pk_add_f32 v[28:29], v[28:29], v[28:29] op_sel:[0,1] op_sel_hi:[0,1] neg_lo:[0,1] neg_hi:[0,1]
	v_pk_fma_f32 v[132:133], v[116:117], v[28:29], v[96:97] op_sel:[0,0,1] op_sel_hi:[1,1,0] neg_lo:[0,0,1]
	v_pk_mul_f32 v[28:29], v[122:123], v[28:29]
	v_pk_fma_f32 v[96:97], v[122:123], v[82:83], v[28:29] op_sel:[0,0,1] op_sel_hi:[1,1,0] neg_lo:[1,0,0] neg_hi:[1,0,0]
	v_pk_fma_f32 v[28:29], v[122:123], v[82:83], v[28:29] op_sel:[0,0,1] op_sel_hi:[1,1,0]
	v_mov_b32_e32 v83, v97
	v_mov_b32_e32 v82, v28
	v_pk_mul_f32 v[116:117], v[118:119], v[28:29] op_sel:[1,0] op_sel_hi:[0,0]
	v_pk_mov_b32 v[28:29], v[96:97], v[28:29] op_sel:[1,0]
	v_pk_mul_f32 v[82:83], v[122:123], v[82:83]
	v_pk_mul_f32 v[28:29], v[122:123], v[28:29]
	v_pk_add_f32 v[82:83], v[82:83], v[82:83] op_sel:[1,0] op_sel_hi:[1,0]
	v_pk_fma_f32 v[142:143], v[118:119], v[96:97], v[116:117] op_sel:[0,1,0] neg_lo:[0,0,1]
	v_pk_mul_f32 v[82:83], v[120:121], v[82:83] op_sel:[1,0] op_sel_hi:[0,1]
	v_pk_add_f32 v[28:29], v[28:29], v[28:29] op_sel:[0,1] op_sel_hi:[0,1] neg_lo:[0,1] neg_hi:[0,1]
	v_pk_fma_f32 v[96:97], v[120:121], v[28:29], v[82:83] neg_lo:[0,0,1]
	v_pk_add_f32 v[82:83], v[134:135], v[130:131]
	v_pk_add_f32 v[28:29], v[26:27], v[114:115]
	v_pk_add_f32 v[26:27], v[26:27], v[114:115] neg_lo:[0,1] neg_hi:[0,1]
	v_pk_add_f32 v[114:115], v[134:135], v[130:131] neg_lo:[0,1] neg_hi:[0,1]
	v_pk_add_f32 v[120:121], v[106:107], v[132:133]
	v_xor_b32_e32 v117, 0x80000000, v114
	v_mov_b32_e32 v116, v115
	v_pk_add_f32 v[106:107], v[106:107], v[132:133] neg_lo:[0,1] neg_hi:[0,1]
	v_pk_add_f32 v[114:115], v[28:29], v[82:83]
	v_pk_add_f32 v[118:119], v[26:27], v[116:117]
	v_pk_add_f32 v[28:29], v[28:29], v[82:83] neg_lo:[0,1] neg_hi:[0,1]
	v_pk_add_f32 v[26:27], v[26:27], v[116:117] neg_lo:[0,1] neg_hi:[0,1]
	v_pk_add_f32 v[82:83], v[136:137], v[124:125]
	v_pk_add_f32 v[116:117], v[136:137], v[124:125] neg_lo:[0,1] neg_hi:[0,1]
	v_xor_b32_e32 v123, 0x80000000, v106
	v_mov_b32_e32 v122, v107
	v_pk_add_f32 v[106:107], v[82:83], v[120:121]
	v_pk_add_f32 v[124:125], v[116:117], v[122:123]
	v_pk_add_f32 v[82:83], v[82:83], v[120:121] neg_lo:[0,1] neg_hi:[0,1]
	v_pk_add_f32 v[116:117], v[116:117], v[122:123] neg_lo:[0,1] neg_hi:[0,1]
	v_pk_add_f32 v[120:121], v[140:141], v[126:127]
	v_pk_add_f32 v[122:123], v[140:141], v[126:127] neg_lo:[0,1] neg_hi:[0,1]
	v_pk_add_f32 v[126:127], v[108:109], v[142:143]
	v_pk_add_f32 v[108:109], v[108:109], v[142:143] neg_lo:[0,1] neg_hi:[0,1]
	s_nop 0
	v_xor_b32_e32 v131, 0x80000000, v108
	v_mov_b32_e32 v130, v109
	v_pk_add_f32 v[132:133], v[122:123], v[130:131]
	v_pk_add_f32 v[122:123], v[122:123], v[130:131] neg_lo:[0,1] neg_hi:[0,1]
	v_pk_add_f32 v[130:131], v[110:111], v[96:97]
	v_pk_add_f32 v[96:97], v[110:111], v[96:97] neg_lo:[0,1] neg_hi:[0,1]
	v_pk_add_f32 v[108:109], v[120:121], v[126:127]
	v_pk_add_f32 v[120:121], v[120:121], v[126:127] neg_lo:[0,1] neg_hi:[0,1]
	v_pk_add_f32 v[126:127], v[138:139], v[128:129]
	v_pk_add_f32 v[128:129], v[138:139], v[128:129] neg_lo:[0,1] neg_hi:[0,1]
	v_xor_b32_e32 v111, 0x80000000, v96
	v_mov_b32_e32 v110, v97
	v_pk_add_f32 v[134:135], v[128:129], v[110:111]
	v_pk_add_f32 v[110:111], v[128:129], v[110:111] neg_lo:[0,1] neg_hi:[0,1]
	v_pk_mul_f32 v[128:129], v[124:125], s[24:25] op_sel_hi:[1,0]
	v_pk_add_f32 v[96:97], v[126:127], v[130:131]
	v_pk_add_f32 v[126:127], v[126:127], v[130:131] neg_lo:[0,1] neg_hi:[0,1]
	v_pk_fma_f32 v[130:131], v[124:125], s[26:27], v[128:129] op_sel:[0,0,1] op_sel_hi:[1,0,0] neg_hi:[0,0,1]
	s_nop 0
	v_pk_mul_f32 v[124:125], v[82:83], s[28:29] op_sel_hi:[1,0]
	s_nop 0
	v_pk_fma_f32 v[128:129], v[82:83], s[28:29], v[124:125] op_sel:[0,0,1] op_sel_hi:[1,0,0] neg_hi:[0,0,1]
	v_pk_mul_f32 v[124:125], v[116:117], s[26:27] op_sel_hi:[1,0]
	v_pk_fma_f32 v[136:137], v[116:117], s[24:25], v[124:125] op_sel:[0,0,1] op_sel_hi:[1,0,0] neg_hi:[0,0,1]
	s_nop 0
	v_pk_mul_f32 v[116:117], v[132:133], s[28:29] op_sel_hi:[1,0]
	s_nop 0
	v_pk_fma_f32 v[124:125], v[132:133], s[28:29], v[116:117] op_sel:[0,0,1] op_sel_hi:[1,0,0] neg_hi:[0,0,1]
	s_nop 0
	v_pk_fma_f32 v[116:117], v[120:121], 0, v[120:121] op_sel:[0,0,1] op_sel_hi:[1,0,0] neg_hi:[0,0,1]
	s_nop 0
	v_pk_mul_f32 v[120:121], v[122:123], s[30:31] op_sel_hi:[1,0]
	s_nop 0
	v_pk_fma_f32 v[132:133], v[122:123], s[30:31], v[120:121] op_sel:[0,0,1] op_sel_hi:[1,0,0] neg_lo:[0,0,1]
	v_pk_mul_f32 v[122:123], v[134:135], s[26:27] op_sel_hi:[1,0]
	v_pk_fma_f32 v[138:139], v[134:135], s[24:25], v[122:123] op_sel:[0,0,1] op_sel_hi:[1,0,0] neg_hi:[0,0,1]
	v_pk_add_f32 v[120:121], v[26:27], v[132:133]
	v_pk_mul_f32 v[122:123], v[126:127], s[30:31] op_sel_hi:[1,0]
	v_pk_add_f32 v[26:27], v[26:27], v[132:133] neg_lo:[0,1] neg_hi:[0,1]
	v_pk_fma_f32 v[134:135], v[126:127], s[30:31], v[122:123] op_sel:[0,0,1] op_sel_hi:[1,0,0] neg_lo:[0,0,1]
	s_nop 0
	v_pk_mul_f32 v[122:123], v[110:111], s[60:61] op_sel:[1,0]
	v_pk_add_f32 v[82:83], v[128:129], v[134:135]
	v_pk_fma_f32 v[110:111], v[110:111], s[34:35], v[122:123] op_sel_hi:[0,1,1]
	v_pk_add_f32 v[122:123], v[114:115], v[108:109]
	v_pk_add_f32 v[108:109], v[114:115], v[108:109] neg_lo:[0,1] neg_hi:[0,1]
	v_pk_add_f32 v[114:115], v[106:107], v[96:97]
	v_pk_add_f32 v[96:97], v[106:107], v[96:97] neg_lo:[0,1] neg_hi:[0,1]
	s_nop 0
	v_xor_b32_e32 v107, 0x80000000, v96
	v_mov_b32_e32 v106, v97
	v_pk_add_f32 v[96:97], v[122:123], v[114:115]
	v_pk_add_f32 v[126:127], v[108:109], v[106:107]
	v_pk_add_f32 v[114:115], v[122:123], v[114:115] neg_lo:[0,1] neg_hi:[0,1]
	v_pk_add_f32 v[106:107], v[108:109], v[106:107] neg_lo:[0,1] neg_hi:[0,1]
	v_pk_add_f32 v[108:109], v[118:119], v[124:125]
	v_pk_add_f32 v[118:119], v[118:119], v[124:125] neg_lo:[0,1] neg_hi:[0,1]
	v_pk_add_f32 v[122:123], v[130:131], v[138:139]
	v_pk_add_f32 v[124:125], v[130:131], v[138:139] neg_lo:[0,1] neg_hi:[0,1]
	s_nop 0
	v_xor_b32_e32 v131, 0x80000000, v124
	v_mov_b32_e32 v130, v125
	v_pk_add_f32 v[124:125], v[108:109], v[122:123]
	v_pk_add_f32 v[108:109], v[108:109], v[122:123] neg_lo:[0,1] neg_hi:[0,1]
	v_pk_add_f32 v[122:123], v[28:29], v[116:117]
	v_pk_add_f32 v[28:29], v[28:29], v[116:117] neg_lo:[0,1] neg_hi:[0,1]
	v_pk_add_f32 v[116:117], v[128:129], v[134:135] neg_lo:[0,1] neg_hi:[0,1]
	v_pk_add_f32 v[138:139], v[118:119], v[130:131]
	v_xor_b32_e32 v129, 0x80000000, v116
	v_mov_b32_e32 v128, v117
	v_pk_add_f32 v[116:117], v[122:123], v[82:83]
	v_pk_add_f32 v[82:83], v[122:123], v[82:83] neg_lo:[0,1] neg_hi:[0,1]
	v_pk_add_f32 v[122:123], v[136:137], v[110:111]
	v_pk_add_f32 v[110:111], v[136:137], v[110:111] neg_lo:[0,1] neg_hi:[0,1]
	v_pk_add_f32 v[118:119], v[118:119], v[130:131] neg_lo:[0,1] neg_hi:[0,1]
	v_pk_add_f32 v[130:131], v[28:29], v[128:129]
	v_pk_add_f32 v[28:29], v[28:29], v[128:129] neg_lo:[0,1] neg_hi:[0,1]
	v_xor_b32_e32 v129, 0x80000000, v110
	v_mov_b32_e32 v128, v111
	v_pk_add_f32 v[110:111], v[120:121], v[122:123]
	v_pk_add_f32 v[132:133], v[26:27], v[128:129]
	v_pk_add_f32 v[120:121], v[120:121], v[122:123] neg_lo:[0,1] neg_hi:[0,1]
	v_pk_add_f32 v[26:27], v[26:27], v[128:129] neg_lo:[0,1] neg_hi:[0,1]
	ds_write_b64 v0, v[96:97]
	ds_write_b64 v0, v[124:125] offset:2176
	ds_write_b64 v0, v[116:117] offset:4352
	ds_write_b64 v0, v[110:111] offset:6528
	ds_write_b64 v0, v[126:127] offset:8704
	ds_write_b64 v0, v[138:139] offset:10880
	ds_write_b64 v0, v[130:131] offset:13056
	ds_write_b64 v0, v[132:133] offset:15232
	ds_write_b64 v0, v[114:115] offset:17408
	ds_write_b64 v0, v[108:109] offset:19584
	ds_write_b64 v0, v[82:83] offset:21760
	ds_write_b64 v0, v[120:121] offset:23936
	ds_write_b64 v0, v[106:107] offset:26112
	ds_write_b64 v0, v[118:119] offset:28288
	ds_write_b64 v0, v[28:29] offset:30464
	ds_write_b64 v0, v[26:27] offset:32640

.LBB0_356:
	v_mov_b32_e32 v200, v197
	v_mov_b32_e32 v201, v193
	ds_write_b64 v0, v[200:201] offset:6272
	ds_write_b64 v232, v[240:241] offset:22656
	v_mov_b32_e32 v200, v196
	v_mov_b32_e32 v201, v192
	ds_write_b64 v0, v[200:201] offset:6280
	ds_write_b64 v232, v[240:241] offset:22664
	v_mov_b32_e32 v200, v198
	v_mov_b32_e32 v201, v194
	ds_write_b64 v0, v[200:201] offset:6288
	ds_write_b64 v232, v[240:241] offset:22672
	v_mov_b32_e32 v200, v199
	v_mov_b32_e32 v201, v195
	ds_write_b64 v0, v[200:201] offset:6296
	ds_write_b64 v232, v[240:241] offset:22680
	v_mov_b32_e32 v200, v189
	v_mov_b32_e32 v201, v185
	ds_write_b64 v0, v[200:201] offset:41088
	ds_write_b64 v232, v[240:241] offset:57472
	v_mov_b32_e32 v200, v188
	v_mov_b32_e32 v201, v184
	ds_write_b64 v0, v[200:201] offset:41096
	ds_write_b64 v232, v[240:241] offset:57480
	v_mov_b32_e32 v200, v190
	v_mov_b32_e32 v201, v186
	ds_write_b64 v0, v[200:201] offset:41104
	ds_write_b64 v232, v[240:241] offset:57488
	v_mov_b32_e32 v200, v191
	v_mov_b32_e32 v201, v187
	ds_write_b64 v0, v[200:201] offset:41112
	ds_write_b64 v232, v[240:241] offset:57496
	v_mov_b32_e32 v200, v180
	s_waitcnt lgkmcnt(0)
	s_barrier
	s_nop 0
	v_cmp_gt_i32_e32 vcc, s56, v200
	s_and_saveexec_b64 s[2:3], vcc
	s_cbranch_execz .LBB0_358
	v_ashrrev_i32_e32 v181, 31, v200
	v_add_u32_sdwa v181, v200, v181 dst_sel:DWORD dst_unused:UNUSED_PAD src0_sel:DWORD src1_sel:BYTE_3
	v_ashrrev_i32_e32 v181, 8, v181
	v_mul_i32_i24_e32 v201, 0x100, v181
	v_sub_u32_e32 v233, v200, v201
	v_mul_i32_i24_e32 v181, 0x1100, v181
	v_lshlrev_b32_e32 v181, 3, v181
	v_ashrrev_i32_e32 v201, 4, v233
	v_add_u32_e32 v200, 0, v181
	v_lshlrev_b32_e32 v244, 3, v233
	v_lshlrev_b32_e32 v201, 3, v201
	v_add3_u32 v230, v200, v244, v201
	ds_read_b64 v[200:201], v230 offset:6272
	ds_read_b64 v[202:203], v230 offset:8448
	ds_read_b64 v[204:205], v230 offset:10624
	ds_read_b64 v[206:207], v230 offset:12800
	ds_read_b64 v[208:209], v230 offset:14976
	ds_read_b64 v[210:211], v230 offset:17152
	ds_read_b64 v[212:213], v230 offset:19328
	ds_read_b64 v[214:215], v230 offset:21504
	ds_read_b64 v[216:217], v230 offset:23680
	ds_read_b64 v[218:219], v230 offset:25856
	ds_read_b64 v[220:221], v230 offset:28032
	ds_read_b64 v[222:223], v230 offset:30208
	ds_read_b64 v[224:225], v230 offset:32384
	ds_read_b64 v[226:227], v230 offset:34560
	ds_read_b64 v[228:229], v230 offset:36736
	ds_read_b64 v[230:231], v230 offset:38912
	s_waitcnt lgkmcnt(7)
	v_pk_add_f32 v[234:235], v[200:201], v[216:217]
	v_pk_add_f32 v[200:201], v[200:201], v[216:217] neg_lo:[0,1] neg_hi:[0,1]
	s_waitcnt lgkmcnt(3)
	v_pk_add_f32 v[216:217], v[208:209], v[224:225]
	v_pk_add_f32 v[208:209], v[208:209], v[224:225] neg_lo:[0,1] neg_hi:[0,1]
	s_mov_b32 s61, s34
	v_xor_b32_e32 v225, 0x80000000, v208
	v_mov_b32_e32 v224, v209
	v_pk_add_f32 v[236:237], v[200:201], v[224:225]
	v_pk_add_f32 v[200:201], v[200:201], v[224:225] neg_lo:[0,1] neg_hi:[0,1]
	v_pk_add_f32 v[224:225], v[202:203], v[218:219]
	v_pk_add_f32 v[202:203], v[202:203], v[218:219] neg_lo:[0,1] neg_hi:[0,1]
	s_waitcnt lgkmcnt(2)
	v_pk_add_f32 v[218:219], v[210:211], v[226:227]
	v_pk_add_f32 v[210:211], v[210:211], v[226:227] neg_lo:[0,1] neg_hi:[0,1]
	v_pk_add_f32 v[208:209], v[234:235], v[216:217]
	v_xor_b32_e32 v227, 0x80000000, v210
	v_mov_b32_e32 v226, v211
	v_pk_add_f32 v[210:211], v[224:225], v[218:219]
	v_pk_add_f32 v[218:219], v[224:225], v[218:219] neg_lo:[0,1] neg_hi:[0,1]
	v_pk_add_f32 v[224:225], v[204:205], v[220:221]
	v_pk_add_f32 v[204:205], v[204:205], v[220:221] neg_lo:[0,1] neg_hi:[0,1]
	s_waitcnt lgkmcnt(1)
	v_pk_add_f32 v[220:221], v[212:213], v[228:229]
	v_pk_add_f32 v[212:213], v[212:213], v[228:229] neg_lo:[0,1] neg_hi:[0,1]
	v_pk_add_f32 v[216:217], v[234:235], v[216:217] neg_lo:[0,1] neg_hi:[0,1]
	v_pk_add_f32 v[234:235], v[202:203], v[226:227]
	v_pk_add_f32 v[202:203], v[202:203], v[226:227] neg_lo:[0,1] neg_hi:[0,1]
	v_xor_b32_e32 v227, 0x80000000, v212
	v_mov_b32_e32 v226, v213
	v_pk_add_f32 v[212:213], v[224:225], v[220:221]
	v_pk_add_f32 v[220:221], v[224:225], v[220:221] neg_lo:[0,1] neg_hi:[0,1]
	v_pk_add_f32 v[224:225], v[206:207], v[222:223]
	v_pk_add_f32 v[206:207], v[206:207], v[222:223] neg_lo:[0,1] neg_hi:[0,1]
	s_waitcnt lgkmcnt(0)
	v_pk_add_f32 v[222:223], v[214:215], v[230:231]
	v_pk_add_f32 v[214:215], v[214:215], v[230:231] neg_lo:[0,1] neg_hi:[0,1]
	v_pk_add_f32 v[228:229], v[204:205], v[226:227]
	v_pk_add_f32 v[204:205], v[204:205], v[226:227] neg_lo:[0,1] neg_hi:[0,1]
	v_xor_b32_e32 v227, 0x80000000, v214
	v_mov_b32_e32 v226, v215
	v_pk_add_f32 v[214:215], v[224:225], v[222:223]
	v_pk_add_f32 v[222:223], v[224:225], v[222:223] neg_lo:[0,1] neg_hi:[0,1]
	v_pk_mul_f32 v[224:225], v[234:235], s[24:25] op_sel_hi:[1,0]
	v_pk_add_f32 v[230:231], v[206:207], v[226:227]
	v_pk_add_f32 v[206:207], v[206:207], v[226:227] neg_lo:[0,1] neg_hi:[0,1]
	v_pk_fma_f32 v[226:227], v[234:235], s[26:27], v[224:225] op_sel:[0,0,1] op_sel_hi:[1,0,0] neg_hi:[0,0,1]
	s_mov_b32 s35, s24
	v_pk_mul_f32 v[224:225], v[218:219], s[28:29] op_sel_hi:[1,0]
	v_add_u32_e32 v181, s57, v181
	v_pk_fma_f32 v[234:235], v[218:219], s[28:29], v[224:225] op_sel:[0,0,1] op_sel_hi:[1,0,0] neg_hi:[0,0,1]
	v_pk_mul_f32 v[224:225], v[202:203], s[26:27] op_sel_hi:[1,0]
	v_pk_fma_f32 v[238:239], v[202:203], s[24:25], v[224:225] op_sel:[0,0,1] op_sel_hi:[1,0,0] neg_hi:[0,0,1]
	s_nop 0
	v_pk_mul_f32 v[202:203], v[228:229], s[28:29] op_sel_hi:[1,0]
	s_nop 0
	v_pk_fma_f32 v[224:225], v[228:229], s[28:29], v[202:203] op_sel:[0,0,1] op_sel_hi:[1,0,0] neg_hi:[0,0,1]
	s_nop 0
	v_pk_fma_f32 v[202:203], v[220:221], 0, v[220:221] op_sel:[0,0,1] op_sel_hi:[1,0,0] neg_hi:[0,0,1]
	s_nop 0
	v_pk_mul_f32 v[220:221], v[204:205], s[30:31] op_sel_hi:[1,0]
	s_nop 0
	v_pk_fma_f32 v[228:229], v[204:205], s[30:31], v[220:221] op_sel:[0,0,1] op_sel_hi:[1,0,0] neg_lo:[0,0,1]
	v_pk_mul_f32 v[220:221], v[230:231], s[26:27] op_sel_hi:[1,0]
	v_pk_fma_f32 v[242:243], v[230:231], s[24:25], v[220:221] op_sel:[0,0,1] op_sel_hi:[1,0,0] neg_hi:[0,0,1]
	v_pk_add_f32 v[204:205], v[200:201], v[228:229]
	v_pk_mul_f32 v[220:221], v[222:223], s[30:31] op_sel_hi:[1,0]
	v_pk_add_f32 v[200:201], v[200:201], v[228:229] neg_lo:[0,1] neg_hi:[0,1]
	v_pk_fma_f32 v[230:231], v[222:223], s[30:31], v[220:221] op_sel:[0,0,1] op_sel_hi:[1,0,0] neg_lo:[0,0,1]
	s_nop 0
	v_pk_mul_f32 v[220:221], v[206:207], s[60:61] op_sel:[1,0]
	v_pk_add_f32 v[218:219], v[234:235], v[230:231] neg_lo:[0,1] neg_hi:[0,1]
	v_pk_fma_f32 v[206:207], v[206:207], s[34:35], v[220:221] op_sel_hi:[0,1,1]
	v_pk_add_f32 v[220:221], v[208:209], v[212:213]
	v_pk_add_f32 v[208:209], v[208:209], v[212:213] neg_lo:[0,1] neg_hi:[0,1]
	v_pk_add_f32 v[212:213], v[210:211], v[214:215]
	v_pk_add_f32 v[210:211], v[210:211], v[214:215] neg_lo:[0,1] neg_hi:[0,1]
	s_nop 0
	v_xor_b32_e32 v215, 0x80000000, v210
	v_mov_b32_e32 v214, v211
	v_pk_add_f32 v[210:211], v[220:221], v[212:213]
	v_pk_add_f32 v[222:223], v[208:209], v[214:215]
	v_pk_add_f32 v[212:213], v[220:221], v[212:213] neg_lo:[0,1] neg_hi:[0,1]
	v_pk_add_f32 v[208:209], v[208:209], v[214:215] neg_lo:[0,1] neg_hi:[0,1]
	v_pk_add_f32 v[214:215], v[236:237], v[224:225]
	v_pk_add_f32 v[220:221], v[236:237], v[224:225] neg_lo:[0,1] neg_hi:[0,1]
	v_pk_add_f32 v[224:225], v[226:227], v[242:243]
	v_pk_add_f32 v[226:227], v[226:227], v[242:243] neg_lo:[0,1] neg_hi:[0,1]
	s_nop 0
	v_xor_b32_e32 v237, 0x80000000, v226
	v_mov_b32_e32 v236, v227
	v_pk_add_f32 v[226:227], v[214:215], v[224:225]
	v_pk_add_f32 v[214:215], v[214:215], v[224:225] neg_lo:[0,1] neg_hi:[0,1]
	v_pk_add_f32 v[224:225], v[216:217], v[202:203]
	v_pk_add_f32 v[202:203], v[216:217], v[202:203] neg_lo:[0,1] neg_hi:[0,1]
	v_pk_add_f32 v[216:217], v[234:235], v[230:231]
	v_xor_b32_e32 v231, 0x80000000, v218
	v_mov_b32_e32 v230, v219
	v_pk_add_f32 v[218:219], v[224:225], v[216:217]
	v_pk_add_f32 v[216:217], v[224:225], v[216:217] neg_lo:[0,1] neg_hi:[0,1]
	v_pk_add_f32 v[224:225], v[238:239], v[206:207]
	v_pk_add_f32 v[206:207], v[238:239], v[206:207] neg_lo:[0,1] neg_hi:[0,1]
	v_pk_add_f32 v[242:243], v[220:221], v[236:237]
	v_xor_b32_e32 v229, 0x80000000, v206
	v_mov_b32_e32 v228, v207
	v_pk_add_f32 v[206:207], v[204:205], v[224:225]
	v_pk_add_f32 v[204:205], v[204:205], v[224:225] neg_lo:[0,1] neg_hi:[0,1]
	v_lshlrev_b32_e32 v224, 7, v233
	v_add3_u32 v181, v181, v224, v244
	v_pk_add_f32 v[220:221], v[220:221], v[236:237] neg_lo:[0,1] neg_hi:[0,1]
	v_pk_add_f32 v[234:235], v[202:203], v[230:231]
	v_pk_add_f32 v[202:203], v[202:203], v[230:231] neg_lo:[0,1] neg_hi:[0,1]
	v_pk_add_f32 v[230:231], v[200:201], v[228:229]
	v_pk_add_f32 v[200:201], v[200:201], v[228:229] neg_lo:[0,1] neg_hi:[0,1]
	ds_write2_b64 v181, v[210:211], v[226:227] offset1:1
	ds_write2_b64 v181, v[218:219], v[206:207] offset0:2 offset1:3
	ds_write2_b64 v181, v[222:223], v[242:243] offset0:4 offset1:5
	ds_write2_b64 v181, v[234:235], v[230:231] offset0:6 offset1:7
	ds_write2_b64 v181, v[212:213], v[214:215] offset0:8 offset1:9
	ds_write2_b64 v181, v[216:217], v[204:205] offset0:10 offset1:11
	ds_write2_b64 v181, v[208:209], v[220:221] offset0:12 offset1:13
	ds_write2_b64 v181, v[202:203], v[200:201] offset0:14 offset1:15
.LBB0_358:
	s_or_b64 exec, exec, s[2:3]
	v_mov_b32_e32 v200, v180
	s_waitcnt lgkmcnt(0)
	s_barrier
	s_nop 0
	v_cmp_gt_i32_e32 vcc, s56, v200
	s_and_saveexec_b64 s[2:3], vcc
	s_cbranch_execz .LBB0_360
	v_ashrrev_i32_e32 v181, 31, v200
	v_add_u32_sdwa v181, v200, v181 dst_sel:DWORD dst_unused:UNUSED_PAD src0_sel:DWORD src1_sel:BYTE_3
	v_ashrrev_i32_e32 v181, 8, v181
	v_mul_i32_i24_e32 v201, 0x100, v181
	v_sub_u32_e32 v200, v200, v201
	v_ashrrev_i16_e32 v201, 15, v200
	v_lshrrev_b16_e32 v201, 12, v201
	v_add_u16_e32 v201, v200, v201
	v_ashrrev_i16_e32 v233, 4, v201
	v_and_b32_e32 v201, -16, v201
	v_mul_i32_i24_e32 v181, 0x1100, v181
	v_sub_u16_e32 v204, v200, v201
	v_lshlrev_b32_e32 v234, 3, v181
	v_lshlrev_b32_e32 v201, 3, v200
	v_ashrrev_i32_e32 v200, 4, v200
	v_add_u32_e32 v181, s57, v234
	v_lshlrev_b32_e32 v200, 3, v200
	v_add3_u32 v181, v181, v201, v200
	v_bfe_i32 v235, v204, 0, 16
	ds_read_b64 v[200:201], v181
	ds_read_b64 v[202:203], v181 offset:2176
	ds_read_b64 v[214:215], v181 offset:4352
	ds_read_b64 v[216:217], v181 offset:6528
	ds_read_b64 v[218:219], v181 offset:8704
	ds_read_b64 v[222:223], v181 offset:10880
	ds_read_b64 v[224:225], v181 offset:13056
	ds_read_b64 v[226:227], v181 offset:15232
	ds_read_b64 v[228:229], v181 offset:17408
	ds_read_b64 v[230:231], v181 offset:19584
	ds_read_b64 v[236:237], v181 offset:21760
	ds_read_b64 v[238:239], v181 offset:23936
	ds_read_b64 v[242:243], v181 offset:26112
	ds_read_b64 v[244:245], v181 offset:28288
	ds_read_b64 v[246:247], v181 offset:30464
	ds_read_b64 v[206:207], v181 offset:32640
	v_mad_i32_i24 v181, v235, s27, 0
	v_add_u32_e32 v204, 0x808, v181
	ds_read2_b64 v[210:213], v204 offset1:1
	s_mov_b32 s61, s34
	s_mov_b32 s35, s24
	s_waitcnt lgkmcnt(0)
	v_pk_mul_f32 v[204:205], v[202:203], v[210:211] op_sel:[1,1] op_sel_hi:[1,0]
	s_nop 0
	v_pk_fma_f32 v[208:209], v[202:203], v[210:211], v[204:205] op_sel_hi:[0,1,1] neg_lo:[0,0,1]
	v_pk_mul_f32 v[202:203], v[214:215], v[212:213] op_sel:[1,1] op_sel_hi:[1,0]
	s_nop 0
	v_pk_fma_f32 v[204:205], v[214:215], v[212:213], v[202:203] neg_lo:[0,0,1] neg_hi:[0,0,1]
	v_pk_fma_f32 v[202:203], v[214:215], v[212:213], v[202:203] op_sel_hi:[0,1,1]
	v_add_u32_e32 v202, 0x818, v181
	ds_read2_b64 v[210:213], v202 offset1:1
	v_mov_b32_e32 v205, v203
	s_waitcnt lgkmcnt(0)
	v_pk_mul_f32 v[214:215], v[216:217], v[210:211] op_sel:[1,1] op_sel_hi:[1,0]
	s_nop 0
	v_pk_fma_f32 v[202:203], v[216:217], v[210:211], v[214:215] op_sel_hi:[0,1,1] neg_lo:[0,0,1]
	v_pk_mul_f32 v[210:211], v[218:219], v[212:213] op_sel:[1,1] op_sel_hi:[1,0]
	s_nop 0
	v_pk_fma_f32 v[216:217], v[218:219], v[212:213], v[210:211] neg_lo:[0,0,1] neg_hi:[0,0,1]
	v_pk_fma_f32 v[210:211], v[218:219], v[212:213], v[210:211] op_sel_hi:[0,1,1]
	v_add_u32_e32 v210, 0x828, v181
	ds_read2_b64 v[218:221], v210 offset1:1
	v_mov_b32_e32 v217, v211
	s_waitcnt lgkmcnt(0)
	v_pk_mul_f32 v[210:211], v[222:223], v[218:219] op_sel:[1,1] op_sel_hi:[1,0]
	s_nop 0
	v_pk_fma_f32 v[214:215], v[222:223], v[218:219], v[210:211] op_sel_hi:[0,1,1] neg_lo:[0,0,1]
	v_pk_mul_f32 v[210:211], v[224:225], v[220:221] op_sel:[1,1] op_sel_hi:[1,0]
	s_nop 0
	v_pk_fma_f32 v[212:213], v[224:225], v[220:221], v[210:211] neg_lo:[0,0,1] neg_hi:[0,0,1]
	v_pk_fma_f32 v[210:211], v[224:225], v[220:221], v[210:211] op_sel_hi:[0,1,1]
	v_add_u32_e32 v210, 0x838, v181
	ds_read2_b64 v[218:221], v210 offset1:1
	v_mov_b32_e32 v213, v211
	s_waitcnt lgkmcnt(0)
	v_pk_mul_f32 v[222:223], v[226:227], v[218:219] op_sel:[1,1] op_sel_hi:[1,0]
	s_nop 0
	v_pk_fma_f32 v[210:211], v[226:227], v[218:219], v[222:223] op_sel_hi:[0,1,1] neg_lo:[0,0,1]
	v_pk_mul_f32 v[218:219], v[228:229], v[220:221] op_sel:[1,1] op_sel_hi:[1,0]
	s_nop 0
	v_pk_fma_f32 v[224:225], v[228:229], v[220:221], v[218:219] neg_lo:[0,0,1] neg_hi:[0,0,1]
	v_pk_fma_f32 v[218:219], v[228:229], v[220:221], v[218:219] op_sel_hi:[0,1,1]
	v_add_u32_e32 v218, 0x848, v181
	ds_read2_b64 v[226:229], v218 offset1:1
	v_mov_b32_e32 v225, v219
	s_waitcnt lgkmcnt(0)
	v_pk_mul_f32 v[218:219], v[230:231], v[226:227] op_sel:[1,1] op_sel_hi:[1,0]
	s_nop 0
	v_pk_fma_f32 v[222:223], v[230:231], v[226:227], v[218:219] op_sel_hi:[0,1,1] neg_lo:[0,0,1]
	v_pk_mul_f32 v[218:219], v[236:237], v[228:229] op_sel:[1,1] op_sel_hi:[1,0]
	s_nop 0
	v_pk_fma_f32 v[220:221], v[236:237], v[228:229], v[218:219] neg_lo:[0,0,1] neg_hi:[0,0,1]
	v_pk_fma_f32 v[218:219], v[236:237], v[228:229], v[218:219] op_sel_hi:[0,1,1]
	v_add_u32_e32 v218, 0x858, v181
	ds_read2_b64 v[226:229], v218 offset1:1
	v_mov_b32_e32 v221, v219
	s_waitcnt lgkmcnt(0)
	v_pk_mul_f32 v[230:231], v[238:239], v[226:227] op_sel:[1,1] op_sel_hi:[1,0]
	s_nop 0
	v_pk_fma_f32 v[218:219], v[238:239], v[226:227], v[230:231] op_sel_hi:[0,1,1] neg_lo:[0,0,1]
	v_pk_mul_f32 v[226:227], v[242:243], v[228:229] op_sel:[1,1] op_sel_hi:[1,0]
	s_nop 0
	v_pk_fma_f32 v[230:231], v[242:243], v[228:229], v[226:227] neg_lo:[0,0,1] neg_hi:[0,0,1]
	v_pk_fma_f32 v[226:227], v[242:243], v[228:229], v[226:227] op_sel_hi:[0,1,1]
	v_add_u32_e32 v226, 0x868, v181
	ds_read2_b64 v[236:239], v226 offset1:1
	v_mov_b32_e32 v231, v227
	s_waitcnt lgkmcnt(0)
	v_pk_mul_f32 v[226:227], v[244:245], v[236:237] op_sel:[1,1] op_sel_hi:[1,0]
	s_nop 0
	v_pk_fma_f32 v[228:229], v[244:245], v[236:237], v[226:227] op_sel_hi:[0,1,1] neg_lo:[0,0,1]
	v_pk_mul_f32 v[236:237], v[246:247], v[238:239] op_sel:[1,1] op_sel_hi:[1,0]
	v_pk_fma_f32 v[226:227], v[246:247], v[238:239], v[236:237] op_sel_hi:[0,1,1] neg_lo:[0,0,1]
	ds_read_b64 v[236:237], v181 offset:2168
	v_bfe_i32 v181, v233, 0, 16
	v_lshl_add_u32 v181, v181, 8, v235
	s_waitcnt lgkmcnt(0)
	v_pk_mul_f32 v[238:239], v[206:207], v[236:237] op_sel:[1,1] op_sel_hi:[1,0]
	s_nop 0
	v_pk_fma_f32 v[242:243], v[206:207], v[236:237], v[238:239] op_sel_hi:[0,1,1] neg_lo:[0,0,1]
	v_pk_add_f32 v[206:207], v[200:201], v[224:225]
	v_pk_add_f32 v[200:201], v[200:201], v[224:225] neg_lo:[0,1] neg_hi:[0,1]
	v_pk_add_f32 v[224:225], v[216:217], v[230:231]
	v_pk_add_f32 v[216:217], v[216:217], v[230:231] neg_lo:[0,1] neg_hi:[0,1]
	s_nop 0
	v_xor_b32_e32 v231, 0x80000000, v216
	v_mov_b32_e32 v230, v217
	v_pk_add_f32 v[216:217], v[206:207], v[224:225]
	v_pk_add_f32 v[206:207], v[206:207], v[224:225] neg_lo:[0,1] neg_hi:[0,1]
	v_pk_add_f32 v[224:225], v[208:209], v[222:223]
	v_pk_add_f32 v[208:209], v[208:209], v[222:223] neg_lo:[0,1] neg_hi:[0,1]
	v_pk_add_f32 v[222:223], v[214:215], v[228:229]
	v_pk_add_f32 v[214:215], v[214:215], v[228:229] neg_lo:[0,1] neg_hi:[0,1]
	v_pk_add_f32 v[236:237], v[200:201], v[230:231]
	v_xor_b32_e32 v229, 0x80000000, v214
	v_mov_b32_e32 v228, v215
	v_pk_add_f32 v[214:215], v[224:225], v[222:223]
	v_pk_add_f32 v[222:223], v[224:225], v[222:223] neg_lo:[0,1] neg_hi:[0,1]
	v_pk_add_f32 v[224:225], v[204:205], v[220:221]
	v_pk_add_f32 v[204:205], v[204:205], v[220:221] neg_lo:[0,1] neg_hi:[0,1]
	v_pk_add_f32 v[220:221], v[212:213], v[226:227]
	v_pk_add_f32 v[212:213], v[212:213], v[226:227] neg_lo:[0,1] neg_hi:[0,1]
	v_pk_add_f32 v[200:201], v[200:201], v[230:231] neg_lo:[0,1] neg_hi:[0,1]
	v_pk_add_f32 v[230:231], v[208:209], v[228:229]
	v_xor_b32_e32 v227, 0x80000000, v212
	v_mov_b32_e32 v226, v213
	v_pk_add_f32 v[212:213], v[224:225], v[220:221]
	v_pk_add_f32 v[220:221], v[224:225], v[220:221] neg_lo:[0,1] neg_hi:[0,1]
	v_pk_add_f32 v[224:225], v[202:203], v[218:219]
	v_pk_add_f32 v[202:203], v[202:203], v[218:219] neg_lo:[0,1] neg_hi:[0,1]
	v_pk_add_f32 v[218:219], v[210:211], v[242:243]
	v_pk_add_f32 v[210:211], v[210:211], v[242:243] neg_lo:[0,1] neg_hi:[0,1]
	v_pk_add_f32 v[208:209], v[208:209], v[228:229] neg_lo:[0,1] neg_hi:[0,1]
	v_pk_add_f32 v[228:229], v[204:205], v[226:227]
	v_pk_add_f32 v[204:205], v[204:205], v[226:227] neg_lo:[0,1] neg_hi:[0,1]
	v_xor_b32_e32 v227, 0x80000000, v210
	v_mov_b32_e32 v226, v211
	v_pk_add_f32 v[210:211], v[224:225], v[218:219]
	v_pk_add_f32 v[218:219], v[224:225], v[218:219] neg_lo:[0,1] neg_hi:[0,1]
	v_pk_mul_f32 v[224:225], v[230:231], s[24:25] op_sel_hi:[1,0]
	v_pk_add_f32 v[238:239], v[202:203], v[226:227]
	v_pk_add_f32 v[202:203], v[202:203], v[226:227] neg_lo:[0,1] neg_hi:[0,1]
	v_pk_fma_f32 v[226:227], v[230:231], s[26:27], v[224:225] op_sel:[0,0,1] op_sel_hi:[1,0,0] neg_hi:[0,0,1]
	s_nop 0
	v_pk_mul_f32 v[224:225], v[222:223], s[28:29] op_sel_hi:[1,0]
	s_nop 0
	v_pk_fma_f32 v[230:231], v[222:223], s[28:29], v[224:225] op_sel:[0,0,1] op_sel_hi:[1,0,0] neg_hi:[0,0,1]
	v_pk_mul_f32 v[224:225], v[208:209], s[26:27] op_sel_hi:[1,0]
	v_pk_fma_f32 v[242:243], v[208:209], s[24:25], v[224:225] op_sel:[0,0,1] op_sel_hi:[1,0,0] neg_hi:[0,0,1]
	s_nop 0
	v_pk_mul_f32 v[208:209], v[228:229], s[28:29] op_sel_hi:[1,0]
	s_nop 0
	v_pk_fma_f32 v[224:225], v[228:229], s[28:29], v[208:209] op_sel:[0,0,1] op_sel_hi:[1,0,0] neg_hi:[0,0,1]
	s_nop 0
	v_pk_fma_f32 v[208:209], v[220:221], 0, v[220:221] op_sel:[0,0,1] op_sel_hi:[1,0,0] neg_hi:[0,0,1]
	s_nop 0
	v_pk_mul_f32 v[220:221], v[204:205], s[30:31] op_sel_hi:[1,0]
	s_nop 0
	v_pk_fma_f32 v[228:229], v[204:205], s[30:31], v[220:221] op_sel:[0,0,1] op_sel_hi:[1,0,0] neg_lo:[0,0,1]
	v_pk_mul_f32 v[220:221], v[238:239], s[26:27] op_sel_hi:[1,0]
	v_pk_fma_f32 v[244:245], v[238:239], s[24:25], v[220:221] op_sel:[0,0,1] op_sel_hi:[1,0,0] neg_hi:[0,0,1]
	v_pk_add_f32 v[204:205], v[200:201], v[228:229]
	v_pk_mul_f32 v[220:221], v[218:219], s[30:31] op_sel_hi:[1,0]
	v_pk_add_f32 v[200:201], v[200:201], v[228:229] neg_lo:[0,1] neg_hi:[0,1]
	v_pk_fma_f32 v[238:239], v[218:219], s[30:31], v[220:221] op_sel:[0,0,1] op_sel_hi:[1,0,0] neg_lo:[0,0,1]
	s_nop 0
	v_pk_mul_f32 v[218:219], v[202:203], s[60:61] op_sel:[1,0]
	v_pk_add_f32 v[222:223], v[230:231], v[238:239] neg_lo:[0,1] neg_hi:[0,1]
	v_pk_fma_f32 v[202:203], v[202:203], s[34:35], v[218:219] op_sel_hi:[0,1,1]
	v_pk_add_f32 v[218:219], v[216:217], v[212:213]
	v_pk_add_f32 v[212:213], v[216:217], v[212:213] neg_lo:[0,1] neg_hi:[0,1]
	v_pk_add_f32 v[216:217], v[214:215], v[210:211]
	v_pk_add_f32 v[210:211], v[214:215], v[210:211] neg_lo:[0,1] neg_hi:[0,1]
	s_nop 0
	v_xor_b32_e32 v215, 0x80000000, v210
	v_mov_b32_e32 v214, v211
	v_pk_add_f32 v[210:211], v[218:219], v[216:217]
	v_pk_add_f32 v[220:221], v[212:213], v[214:215]
	v_pk_add_f32 v[216:217], v[218:219], v[216:217] neg_lo:[0,1] neg_hi:[0,1]
	v_pk_add_f32 v[212:213], v[212:213], v[214:215] neg_lo:[0,1] neg_hi:[0,1]
	v_pk_add_f32 v[214:215], v[236:237], v[224:225]
	v_pk_add_f32 v[218:219], v[236:237], v[224:225] neg_lo:[0,1] neg_hi:[0,1]
	v_pk_add_f32 v[224:225], v[226:227], v[244:245]
	v_pk_add_f32 v[226:227], v[226:227], v[244:245] neg_lo:[0,1] neg_hi:[0,1]
	s_nop 0
	v_xor_b32_e32 v237, 0x80000000, v226
	v_mov_b32_e32 v236, v227
	v_pk_add_f32 v[226:227], v[214:215], v[224:225]
	v_pk_add_f32 v[214:215], v[214:215], v[224:225] neg_lo:[0,1] neg_hi:[0,1]
	v_pk_add_f32 v[224:225], v[206:207], v[208:209]
	v_pk_add_f32 v[206:207], v[206:207], v[208:209] neg_lo:[0,1] neg_hi:[0,1]
	v_pk_add_f32 v[208:209], v[230:231], v[238:239]
	v_xor_b32_e32 v231, 0x80000000, v222
	v_mov_b32_e32 v230, v223
	v_pk_add_f32 v[222:223], v[224:225], v[208:209]
	v_pk_add_f32 v[208:209], v[224:225], v[208:209] neg_lo:[0,1] neg_hi:[0,1]
	v_pk_add_f32 v[224:225], v[242:243], v[202:203]
	v_pk_add_f32 v[202:203], v[242:243], v[202:203] neg_lo:[0,1] neg_hi:[0,1]
	v_pk_add_f32 v[244:245], v[218:219], v[236:237]
	v_xor_b32_e32 v229, 0x80000000, v202
	v_mov_b32_e32 v228, v203
	v_pk_add_f32 v[202:203], v[204:205], v[224:225]
	v_pk_add_f32 v[204:205], v[204:205], v[224:225] neg_lo:[0,1] neg_hi:[0,1]
	v_lshlrev_b32_e32 v225, 3, v181
	v_ashrrev_i32_e32 v181, 4, v181
	v_add_u32_e32 v224, 0, v234
	v_lshlrev_b32_e32 v181, 3, v181
	v_add3_u32 v181, v224, v225, v181
	v_pk_add_f32 v[218:219], v[218:219], v[236:237] neg_lo:[0,1] neg_hi:[0,1]
	v_pk_add_f32 v[236:237], v[206:207], v[230:231]
	v_pk_add_f32 v[206:207], v[206:207], v[230:231] neg_lo:[0,1] neg_hi:[0,1]
	v_pk_add_f32 v[230:231], v[200:201], v[228:229]
	v_pk_add_f32 v[200:201], v[200:201], v[228:229] neg_lo:[0,1] neg_hi:[0,1]
	v_add_u32_e32 v224, 0x1800, v181
	v_add_u32_e32 v181, 0x1c00, v181
	ds_write2_b64 v224, v[210:211], v[226:227] offset0:16 offset1:33
	ds_write2_b64 v224, v[222:223], v[202:203] offset0:50 offset1:67
	ds_write2_b64 v224, v[220:221], v[244:245] offset0:84 offset1:101
	ds_write2_b64 v224, v[236:237], v[230:231] offset0:118 offset1:135
	ds_write2_b64 v224, v[216:217], v[214:215] offset0:152 offset1:169
	ds_write2_b64 v224, v[208:209], v[204:205] offset0:186 offset1:203
	ds_write2_b64 v224, v[212:213], v[218:219] offset0:220 offset1:237
	ds_write2_b64 v181, v[206:207], v[200:201] offset0:126 offset1:143
.LBB0_360:
	s_or_b64 exec, exec, s[2:3]
	v_mov_b32_e32 v200, v180
	s_waitcnt lgkmcnt(0)
	s_barrier
	s_nop 0
	v_cmp_gt_i32_e32 vcc, s56, v200
	s_and_saveexec_b64 s[2:3], vcc
	s_cbranch_execz .LBB0_362
	v_ashrrev_i32_e32 v181, 31, v200
	v_add_u32_sdwa v181, v200, v181 dst_sel:DWORD dst_unused:UNUSED_PAD src0_sel:DWORD src1_sel:BYTE_3
	v_ashrrev_i32_e32 v181, 8, v181
	v_mul_i32_i24_e32 v201, 0x100, v181
	v_sub_u32_e32 v200, v200, v201
	v_mul_i32_i24_e32 v181, 0x1100, v181
	v_lshlrev_b32_e32 v233, 3, v200
	v_ashrrev_i32_e32 v200, 4, v200
	v_lshlrev_b32_e32 v181, 3, v181
	v_lshlrev_b32_e32 v248, 3, v200
	v_add_u32_e32 v222, 0, v233
	v_add3_u32 v234, v222, v181, v248
	ds_read_b64 v[200:201], v234 offset:6272
	ds_read_b64 v[202:203], v234 offset:8448
	ds_read_b64 v[204:205], v234 offset:10624
	ds_read_b64 v[206:207], v234 offset:12800
	ds_read_b64 v[208:209], v234 offset:14976
	ds_read_b64 v[210:211], v234 offset:17152
	ds_read_b64 v[212:213], v234 offset:19328
	ds_read_b64 v[214:215], v234 offset:21504
	ds_read_b64 v[216:217], v234 offset:34560
	ds_read_b64 v[218:219], v234 offset:36736
	ds_read_b64 v[220:221], v234 offset:38912
	ds_read_b64 v[222:223], v222
	ds_read_b64 v[224:225], v234 offset:23680
	ds_read_b64 v[226:227], v234 offset:25856
	ds_read_b64 v[228:229], v234 offset:28032
	ds_read_b64 v[230:231], v234 offset:30208
	ds_read_b64 v[234:235], v234 offset:32384
	s_waitcnt lgkmcnt(5)
	v_pk_mul_f32 v[236:237], v[202:203], v[222:223] op_sel:[1,1] op_sel_hi:[1,0]
	s_mov_b32 s61, s34
	v_pk_fma_f32 v[238:239], v[202:203], v[222:223], v[236:237] op_sel_hi:[0,1,1] neg_lo:[0,0,1]
	v_pk_mul_f32 v[202:203], v[222:223], v[222:223] op_sel:[1,1] op_sel_hi:[1,0]
	s_mov_b32 s35, s24
	v_pk_fma_f32 v[236:237], v[222:223], v[222:223], v[202:203] op_sel_hi:[1,0,1] neg_lo:[0,0,1] neg_hi:[0,0,1]
	v_pk_fma_f32 v[202:203], v[222:223], v[222:223], v[202:203] op_sel_hi:[1,0,1]
	v_mov_b32_e32 v242, v236
	v_mov_b32_e32 v243, v203
	v_pk_mul_f32 v[202:203], v[204:205], v[202:203] op_sel:[1,1] op_sel_hi:[0,1]
	v_pk_fma_f32 v[244:245], v[204:205], v[236:237], v[202:203] op_sel_hi:[1,0,1] neg_lo:[0,0,1]
	v_pk_mul_f32 v[204:205], v[222:223], v[242:243] op_sel:[1,0] op_sel_hi:[0,1]
	v_pk_mul_f32 v[202:203], v[222:223], v[242:243]
	v_pk_add_f32 v[204:205], v[204:205], v[204:205] op_sel:[0,1] op_sel_hi:[0,1]
	v_pk_mul_f32 v[236:237], v[206:207], v[204:205]
	v_pk_add_f32 v[202:203], v[202:203], v[202:203] op_sel:[0,1] op_sel_hi:[0,1] neg_lo:[0,1] neg_hi:[0,1]
	v_pk_fma_f32 v[242:243], v[206:207], v[202:203], v[236:237] op_sel:[0,0,1] op_sel_hi:[1,1,0] neg_lo:[0,0,1]
	v_pk_mul_f32 v[204:205], v[222:223], v[204:205]
	v_pk_fma_f32 v[206:207], v[222:223], v[202:203], v[204:205] op_sel:[0,0,1] op_sel_hi:[1,1,0] neg_lo:[0,0,1] neg_hi:[0,0,1]
	v_pk_fma_f32 v[202:203], v[222:223], v[202:203], v[204:205] op_sel:[0,0,1] op_sel_hi:[1,1,0]
	v_mov_b32_e32 v204, v206
	v_mov_b32_e32 v205, v203
	v_pk_mul_f32 v[202:203], v[208:209], v[202:203] op_sel:[1,1] op_sel_hi:[0,1]
	v_pk_fma_f32 v[236:237], v[208:209], v[206:207], v[202:203] op_sel_hi:[1,0,1] neg_lo:[0,0,1]
	v_add_u32_e32 v181, s57, v181
	v_pk_mul_f32 v[202:203], v[222:223], v[204:205]
	v_pk_mul_f32 v[204:205], v[222:223], v[204:205] op_sel:[1,0] op_sel_hi:[0,1]
	v_pk_add_f32 v[204:205], v[204:205], v[204:205] op_sel:[0,1] op_sel_hi:[0,1]
	v_pk_mul_f32 v[206:207], v[210:211], v[204:205]
	v_pk_add_f32 v[202:203], v[202:203], v[202:203] op_sel:[0,1] op_sel_hi:[0,1] neg_lo:[0,1] neg_hi:[0,1]
	v_pk_fma_f32 v[208:209], v[210:211], v[202:203], v[206:207] op_sel:[0,0,1] op_sel_hi:[1,1,0] neg_lo:[0,0,1]
	v_pk_mul_f32 v[204:205], v[222:223], v[204:205]
	v_pk_fma_f32 v[206:207], v[222:223], v[202:203], v[204:205] op_sel:[0,0,1] op_sel_hi:[1,1,0] neg_lo:[0,0,1] neg_hi:[0,0,1]
	v_pk_fma_f32 v[202:203], v[222:223], v[202:203], v[204:205] op_sel:[0,0,1] op_sel_hi:[1,1,0]
	v_mov_b32_e32 v204, v206
	v_mov_b32_e32 v205, v203
	v_pk_mul_f32 v[202:203], v[212:213], v[202:203] op_sel:[1,1] op_sel_hi:[0,1]
	v_pk_fma_f32 v[210:211], v[212:213], v[206:207], v[202:203] op_sel_hi:[1,0,1] neg_lo:[0,0,1]
	v_add3_u32 v181, v181, v233, v248
	v_pk_mul_f32 v[202:203], v[222:223], v[204:205]
	v_pk_mul_f32 v[204:205], v[222:223], v[204:205] op_sel:[1,0] op_sel_hi:[0,1]
	v_pk_add_f32 v[204:205], v[204:205], v[204:205] op_sel:[0,1] op_sel_hi:[0,1]
	v_pk_mul_f32 v[206:207], v[214:215], v[204:205]
	v_pk_add_f32 v[202:203], v[202:203], v[202:203] op_sel:[0,1] op_sel_hi:[0,1] neg_lo:[0,1] neg_hi:[0,1]
	v_pk_fma_f32 v[212:213], v[214:215], v[202:203], v[206:207] op_sel:[0,0,1] op_sel_hi:[1,1,0] neg_lo:[0,0,1]
	v_pk_mul_f32 v[204:205], v[222:223], v[204:205]
	v_pk_fma_f32 v[206:207], v[222:223], v[202:203], v[204:205] op_sel:[0,0,1] op_sel_hi:[1,1,0] neg_lo:[0,0,1] neg_hi:[0,0,1]
	v_pk_fma_f32 v[202:203], v[222:223], v[202:203], v[204:205] op_sel:[0,0,1] op_sel_hi:[1,1,0]
	v_mov_b32_e32 v204, v206
	v_mov_b32_e32 v205, v203
	s_waitcnt lgkmcnt(4)
	v_pk_mul_f32 v[202:203], v[224:225], v[202:203] op_sel:[1,1] op_sel_hi:[0,1]
	v_pk_fma_f32 v[214:215], v[224:225], v[206:207], v[202:203] op_sel_hi:[1,0,1] neg_lo:[0,0,1]
	s_nop 0
	v_pk_mul_f32 v[202:203], v[222:223], v[204:205]
	v_pk_mul_f32 v[204:205], v[222:223], v[204:205] op_sel:[1,0] op_sel_hi:[0,1]
	v_pk_add_f32 v[204:205], v[204:205], v[204:205] op_sel:[0,1] op_sel_hi:[0,1]
	s_waitcnt lgkmcnt(3)
	v_pk_mul_f32 v[206:207], v[226:227], v[204:205]
	v_pk_add_f32 v[202:203], v[202:203], v[202:203] op_sel:[0,1] op_sel_hi:[0,1] neg_lo:[0,1] neg_hi:[0,1]
	v_pk_fma_f32 v[224:225], v[226:227], v[202:203], v[206:207] op_sel:[0,0,1] op_sel_hi:[1,1,0] neg_lo:[0,0,1]
	v_pk_mul_f32 v[204:205], v[222:223], v[204:205]
	v_pk_fma_f32 v[206:207], v[222:223], v[202:203], v[204:205] op_sel:[0,0,1] op_sel_hi:[1,1,0] neg_lo:[0,0,1] neg_hi:[0,0,1]
	v_pk_fma_f32 v[202:203], v[222:223], v[202:203], v[204:205] op_sel:[0,0,1] op_sel_hi:[1,1,0]
	v_mov_b32_e32 v204, v206
	v_mov_b32_e32 v205, v203
	s_waitcnt lgkmcnt(2)
	v_pk_mul_f32 v[202:203], v[228:229], v[202:203] op_sel:[1,1] op_sel_hi:[0,1]
	v_pk_fma_f32 v[226:227], v[228:229], v[206:207], v[202:203] op_sel_hi:[1,0,1] neg_lo:[0,0,1]
	s_nop 0
	v_pk_mul_f32 v[202:203], v[222:223], v[204:205]
	v_pk_mul_f32 v[204:205], v[222:223], v[204:205] op_sel:[1,0] op_sel_hi:[0,1]
	v_pk_add_f32 v[204:205], v[204:205], v[204:205] op_sel:[0,1] op_sel_hi:[0,1]
	s_waitcnt lgkmcnt(1)
	v_pk_mul_f32 v[206:207], v[230:231], v[204:205]
	v_pk_add_f32 v[202:203], v[202:203], v[202:203] op_sel:[0,1] op_sel_hi:[0,1] neg_lo:[0,1] neg_hi:[0,1]
	v_pk_fma_f32 v[228:229], v[230:231], v[202:203], v[206:207] op_sel:[0,0,1] op_sel_hi:[1,1,0] neg_lo:[0,0,1]
	v_pk_mul_f32 v[204:205], v[222:223], v[204:205]
	v_pk_fma_f32 v[206:207], v[222:223], v[202:203], v[204:205] op_sel:[0,0,1] op_sel_hi:[1,1,0] neg_lo:[0,0,1] neg_hi:[0,0,1]
	v_pk_fma_f32 v[202:203], v[222:223], v[202:203], v[204:205] op_sel:[0,0,1] op_sel_hi:[1,1,0]
	v_mov_b32_e32 v204, v206
	v_mov_b32_e32 v205, v203
	s_waitcnt lgkmcnt(0)
	v_pk_mul_f32 v[202:203], v[234:235], v[202:203] op_sel:[1,1] op_sel_hi:[0,1]
	v_pk_fma_f32 v[230:231], v[234:235], v[206:207], v[202:203] op_sel_hi:[1,0,1] neg_lo:[0,0,1]
	s_nop 0
	v_pk_mul_f32 v[202:203], v[222:223], v[204:205]
	v_pk_mul_f32 v[204:205], v[222:223], v[204:205] op_sel:[1,0] op_sel_hi:[0,1]
	v_pk_add_f32 v[204:205], v[204:205], v[204:205] op_sel:[0,1] op_sel_hi:[0,1]
	v_pk_mul_f32 v[206:207], v[216:217], v[204:205]
	v_pk_add_f32 v[202:203], v[202:203], v[202:203] op_sel:[0,1] op_sel_hi:[0,1] neg_lo:[0,1] neg_hi:[0,1]
	v_pk_fma_f32 v[234:235], v[216:217], v[202:203], v[206:207] op_sel:[0,0,1] op_sel_hi:[1,1,0] neg_lo:[0,0,1]
	v_pk_mul_f32 v[202:203], v[222:223], v[202:203]
	v_pk_fma_f32 v[206:207], v[222:223], v[204:205], v[202:203] op_sel:[0,0,1] op_sel_hi:[1,1,0] neg_lo:[1,0,0] neg_hi:[1,0,0]
	v_pk_fma_f32 v[202:203], v[222:223], v[204:205], v[202:203] op_sel:[0,0,1] op_sel_hi:[1,1,0]
	v_mov_b32_e32 v205, v207
	v_mov_b32_e32 v204, v202
	v_pk_mul_f32 v[216:217], v[218:219], v[202:203] op_sel:[1,0] op_sel_hi:[0,0]
	v_pk_mov_b32 v[202:203], v[206:207], v[202:203] op_sel:[1,0]
	v_pk_mul_f32 v[204:205], v[222:223], v[204:205]
	v_pk_mul_f32 v[202:203], v[222:223], v[202:203]
	v_pk_add_f32 v[204:205], v[204:205], v[204:205] op_sel:[1,0] op_sel_hi:[1,0]
	v_pk_fma_f32 v[246:247], v[218:219], v[206:207], v[216:217] op_sel:[0,1,0] neg_lo:[0,0,1]
	v_pk_mul_f32 v[204:205], v[220:221], v[204:205] op_sel:[1,0] op_sel_hi:[0,1]
	v_pk_add_f32 v[202:203], v[202:203], v[202:203] op_sel:[0,1] op_sel_hi:[0,1] neg_lo:[0,1] neg_hi:[0,1]
	v_pk_fma_f32 v[206:207], v[220:221], v[202:203], v[204:205] neg_lo:[0,0,1]
	v_pk_add_f32 v[204:205], v[236:237], v[230:231]
	v_pk_add_f32 v[202:203], v[200:201], v[214:215]
	v_pk_add_f32 v[200:201], v[200:201], v[214:215] neg_lo:[0,1] neg_hi:[0,1]
	v_pk_add_f32 v[214:215], v[236:237], v[230:231] neg_lo:[0,1] neg_hi:[0,1]
	v_pk_add_f32 v[220:221], v[208:209], v[234:235]
	v_xor_b32_e32 v217, 0x80000000, v214
	v_mov_b32_e32 v216, v215
	v_pk_add_f32 v[208:209], v[208:209], v[234:235] neg_lo:[0,1] neg_hi:[0,1]
	v_pk_add_f32 v[214:215], v[202:203], v[204:205]
	v_pk_add_f32 v[218:219], v[200:201], v[216:217]
	v_pk_add_f32 v[202:203], v[202:203], v[204:205] neg_lo:[0,1] neg_hi:[0,1]
	v_pk_add_f32 v[200:201], v[200:201], v[216:217] neg_lo:[0,1] neg_hi:[0,1]
	v_pk_add_f32 v[204:205], v[238:239], v[224:225]
	v_pk_add_f32 v[216:217], v[238:239], v[224:225] neg_lo:[0,1] neg_hi:[0,1]
	v_xor_b32_e32 v223, 0x80000000, v208
	v_mov_b32_e32 v222, v209
	v_pk_add_f32 v[208:209], v[204:205], v[220:221]
	v_pk_add_f32 v[224:225], v[216:217], v[222:223]
	v_pk_add_f32 v[204:205], v[204:205], v[220:221] neg_lo:[0,1] neg_hi:[0,1]
	v_pk_add_f32 v[216:217], v[216:217], v[222:223] neg_lo:[0,1] neg_hi:[0,1]
	v_pk_add_f32 v[220:221], v[244:245], v[226:227]
	v_pk_add_f32 v[222:223], v[244:245], v[226:227] neg_lo:[0,1] neg_hi:[0,1]
	v_pk_add_f32 v[226:227], v[210:211], v[246:247]
	v_pk_add_f32 v[210:211], v[210:211], v[246:247] neg_lo:[0,1] neg_hi:[0,1]
	s_nop 0
	v_xor_b32_e32 v231, 0x80000000, v210
	v_mov_b32_e32 v230, v211
	v_pk_add_f32 v[234:235], v[222:223], v[230:231]
	v_pk_add_f32 v[222:223], v[222:223], v[230:231] neg_lo:[0,1] neg_hi:[0,1]
	v_pk_add_f32 v[230:231], v[212:213], v[206:207]
	v_pk_add_f32 v[206:207], v[212:213], v[206:207] neg_lo:[0,1] neg_hi:[0,1]
	v_pk_add_f32 v[210:211], v[220:221], v[226:227]
	v_pk_add_f32 v[220:221], v[220:221], v[226:227] neg_lo:[0,1] neg_hi:[0,1]
	v_pk_add_f32 v[226:227], v[242:243], v[228:229]
	v_pk_add_f32 v[228:229], v[242:243], v[228:229] neg_lo:[0,1] neg_hi:[0,1]
	v_xor_b32_e32 v213, 0x80000000, v206
	v_mov_b32_e32 v212, v207
	v_pk_add_f32 v[236:237], v[228:229], v[212:213]
	v_pk_add_f32 v[212:213], v[228:229], v[212:213] neg_lo:[0,1] neg_hi:[0,1]
	v_pk_mul_f32 v[228:229], v[224:225], s[24:25] op_sel_hi:[1,0]
	v_pk_add_f32 v[206:207], v[226:227], v[230:231]
	v_pk_add_f32 v[226:227], v[226:227], v[230:231] neg_lo:[0,1] neg_hi:[0,1]
	v_pk_fma_f32 v[230:231], v[224:225], s[26:27], v[228:229] op_sel:[0,0,1] op_sel_hi:[1,0,0] neg_hi:[0,0,1]
	s_nop 0
	v_pk_mul_f32 v[224:225], v[204:205], s[28:29] op_sel_hi:[1,0]
	s_nop 0
	v_pk_fma_f32 v[228:229], v[204:205], s[28:29], v[224:225] op_sel:[0,0,1] op_sel_hi:[1,0,0] neg_hi:[0,0,1]
	v_pk_mul_f32 v[224:225], v[216:217], s[26:27] op_sel_hi:[1,0]
	v_pk_fma_f32 v[238:239], v[216:217], s[24:25], v[224:225] op_sel:[0,0,1] op_sel_hi:[1,0,0] neg_hi:[0,0,1]
	s_nop 0
	v_pk_mul_f32 v[216:217], v[234:235], s[28:29] op_sel_hi:[1,0]
	s_nop 0
	v_pk_fma_f32 v[224:225], v[234:235], s[28:29], v[216:217] op_sel:[0,0,1] op_sel_hi:[1,0,0] neg_hi:[0,0,1]
	s_nop 0
	v_pk_fma_f32 v[216:217], v[220:221], 0, v[220:221] op_sel:[0,0,1] op_sel_hi:[1,0,0] neg_hi:[0,0,1]
	s_nop 0
	v_pk_mul_f32 v[220:221], v[222:223], s[30:31] op_sel_hi:[1,0]
	s_nop 0
	v_pk_fma_f32 v[234:235], v[222:223], s[30:31], v[220:221] op_sel:[0,0,1] op_sel_hi:[1,0,0] neg_lo:[0,0,1]
	v_pk_mul_f32 v[222:223], v[236:237], s[26:27] op_sel_hi:[1,0]
	v_pk_fma_f32 v[242:243], v[236:237], s[24:25], v[222:223] op_sel:[0,0,1] op_sel_hi:[1,0,0] neg_hi:[0,0,1]
	v_pk_add_f32 v[220:221], v[200:201], v[234:235]
	v_pk_mul_f32 v[222:223], v[226:227], s[30:31] op_sel_hi:[1,0]
	v_pk_add_f32 v[200:201], v[200:201], v[234:235] neg_lo:[0,1] neg_hi:[0,1]
	v_pk_fma_f32 v[236:237], v[226:227], s[30:31], v[222:223] op_sel:[0,0,1] op_sel_hi:[1,0,0] neg_lo:[0,0,1]
	s_nop 0
	v_pk_mul_f32 v[222:223], v[212:213], s[60:61] op_sel:[1,0]
	v_pk_add_f32 v[204:205], v[228:229], v[236:237]
	v_pk_fma_f32 v[212:213], v[212:213], s[34:35], v[222:223] op_sel_hi:[0,1,1]
	v_pk_add_f32 v[222:223], v[214:215], v[210:211]
	v_pk_add_f32 v[210:211], v[214:215], v[210:211] neg_lo:[0,1] neg_hi:[0,1]
	v_pk_add_f32 v[214:215], v[208:209], v[206:207]
	v_pk_add_f32 v[206:207], v[208:209], v[206:207] neg_lo:[0,1] neg_hi:[0,1]
	s_nop 0
	v_xor_b32_e32 v209, 0x80000000, v206
	v_mov_b32_e32 v208, v207
	v_pk_add_f32 v[206:207], v[222:223], v[214:215]
	v_pk_add_f32 v[226:227], v[210:211], v[208:209]
	v_pk_add_f32 v[214:215], v[222:223], v[214:215] neg_lo:[0,1] neg_hi:[0,1]
	v_pk_add_f32 v[208:209], v[210:211], v[208:209] neg_lo:[0,1] neg_hi:[0,1]
	v_pk_add_f32 v[210:211], v[218:219], v[224:225]
	v_pk_add_f32 v[218:219], v[218:219], v[224:225] neg_lo:[0,1] neg_hi:[0,1]
	v_pk_add_f32 v[222:223], v[230:231], v[242:243]
	v_pk_add_f32 v[224:225], v[230:231], v[242:243] neg_lo:[0,1] neg_hi:[0,1]
	s_nop 0
	v_xor_b32_e32 v231, 0x80000000, v224
	v_mov_b32_e32 v230, v225
	v_pk_add_f32 v[224:225], v[210:211], v[222:223]
	v_pk_add_f32 v[210:211], v[210:211], v[222:223] neg_lo:[0,1] neg_hi:[0,1]
	v_pk_add_f32 v[222:223], v[202:203], v[216:217]
	v_pk_add_f32 v[202:203], v[202:203], v[216:217] neg_lo:[0,1] neg_hi:[0,1]
	v_pk_add_f32 v[216:217], v[228:229], v[236:237] neg_lo:[0,1] neg_hi:[0,1]
	v_pk_add_f32 v[242:243], v[218:219], v[230:231]
	v_xor_b32_e32 v229, 0x80000000, v216
	v_mov_b32_e32 v228, v217
	v_pk_add_f32 v[216:217], v[222:223], v[204:205]
	v_pk_add_f32 v[204:205], v[222:223], v[204:205] neg_lo:[0,1] neg_hi:[0,1]
	v_pk_add_f32 v[222:223], v[238:239], v[212:213]
	v_pk_add_f32 v[212:213], v[238:239], v[212:213] neg_lo:[0,1] neg_hi:[0,1]
	v_pk_add_f32 v[218:219], v[218:219], v[230:231] neg_lo:[0,1] neg_hi:[0,1]
	v_pk_add_f32 v[230:231], v[202:203], v[228:229]
	v_pk_add_f32 v[202:203], v[202:203], v[228:229] neg_lo:[0,1] neg_hi:[0,1]
	v_xor_b32_e32 v229, 0x80000000, v212
	v_mov_b32_e32 v228, v213
	v_pk_add_f32 v[212:213], v[220:221], v[222:223]
	v_pk_add_f32 v[234:235], v[200:201], v[228:229]
	v_pk_add_f32 v[220:221], v[220:221], v[222:223] neg_lo:[0,1] neg_hi:[0,1]
	v_pk_add_f32 v[200:201], v[200:201], v[228:229] neg_lo:[0,1] neg_hi:[0,1]
	ds_write_b64 v181, v[206:207]
	ds_write_b64 v181, v[224:225] offset:2176
	ds_write_b64 v181, v[216:217] offset:4352
	ds_write_b64 v181, v[212:213] offset:6528
	ds_write_b64 v181, v[226:227] offset:8704
	ds_write_b64 v181, v[242:243] offset:10880
	ds_write_b64 v181, v[230:231] offset:13056
	ds_write_b64 v181, v[234:235] offset:15232
	ds_write_b64 v181, v[214:215] offset:17408
	ds_write_b64 v181, v[210:211] offset:19584
	ds_write_b64 v181, v[204:205] offset:21760
	ds_write_b64 v181, v[220:221] offset:23936
	ds_write_b64 v181, v[208:209] offset:26112
	ds_write_b64 v181, v[218:219] offset:28288
	ds_write_b64 v181, v[202:203] offset:30464
	ds_write_b64 v181, v[200:201] offset:32640
.LBB0_362:
	s_or_b64 exec, exec, s[2:3]
	v_mov_b32_e32 v200, v180
	s_waitcnt lgkmcnt(0)
	s_barrier
	s_nop 0
	v_cmp_gt_i32_e32 vcc, s56, v200
	s_and_saveexec_b64 s[2:3], vcc
	s_cbranch_execz .LBB0_364
	v_ashrrev_i32_e32 v181, 31, v200
	v_add_u32_sdwa v181, v200, v181 dst_sel:DWORD dst_unused:UNUSED_PAD src0_sel:DWORD src1_sel:BYTE_3
	v_ashrrev_i32_e32 v181, 8, v181
	v_mul_i32_i24_e32 v201, 0x100, v181
	v_sub_u32_e32 v233, v200, v201
	v_mul_i32_i24_e32 v181, 0x1100, v181
	v_lshlrev_b32_e32 v181, 3, v181
	v_ashrrev_i32_e32 v201, 4, v233
	v_add_u32_e32 v200, s57, v181
	v_lshlrev_b32_e32 v244, 3, v233
	v_lshlrev_b32_e32 v201, 3, v201
	v_add3_u32 v230, v200, v244, v201
	ds_read_b64 v[200:201], v230
	ds_read_b64 v[202:203], v230 offset:2176
	ds_read_b64 v[204:205], v230 offset:4352
	ds_read_b64 v[206:207], v230 offset:6528
	v_pk_mov_b32 v[208:209], v[42:43], v[42:43] op_sel:[1,0]
	v_pk_mov_b32 v[216:217], v[58:59], v[58:59] op_sel:[1,0]
	s_waitcnt lgkmcnt(3)
	v_pk_mul_f32 v[208:209], v[208:209], v[200:201] op_sel:[0,1]
	v_pk_mov_b32 v[224:225], v[74:75], v[74:75] op_sel:[1,0]
	v_pk_fma_f32 v[210:211], v[42:43], v[200:201], v[208:209] op_sel_hi:[1,0,1] neg_lo:[0,0,1]
	v_pk_mov_b32 v[234:235], v[92:93], v[92:93] op_sel:[1,0]
	v_pk_mov_b32 v[200:201], v[46:47], v[46:47] op_sel:[1,0]
	s_mov_b32 s35, s60
	s_waitcnt lgkmcnt(2)
	v_pk_mul_f32 v[200:201], v[200:201], v[202:203] op_sel:[0,1]
	v_add_u32_e32 v181, 0, v181
	v_pk_fma_f32 v[208:209], v[46:47], v[202:203], v[200:201] op_sel_hi:[1,0,1] neg_lo:[0,0,1]
	s_nop 0
	v_pk_mov_b32 v[200:201], v[50:51], v[50:51] op_sel:[1,0]
	s_waitcnt lgkmcnt(1)
	v_pk_mul_f32 v[200:201], v[200:201], v[204:205] op_sel:[0,1]
	s_nop 0
	v_pk_fma_f32 v[202:203], v[50:51], v[204:205], v[200:201] op_sel_hi:[1,0,1] neg_lo:[0,0,1]
	s_nop 0
	v_pk_mov_b32 v[200:201], v[54:55], v[54:55] op_sel:[1,0]
	s_waitcnt lgkmcnt(0)
	v_pk_mul_f32 v[200:201], v[200:201], v[206:207] op_sel:[0,1]
	s_nop 0
	v_pk_fma_f32 v[204:205], v[54:55], v[206:207], v[200:201] op_sel_hi:[1,0,1] neg_lo:[0,0,1]
	ds_read_b64 v[206:207], v230 offset:8704
	ds_read_b64 v[200:201], v230 offset:10880
	ds_read_b64 v[212:213], v230 offset:13056
	ds_read_b64 v[214:215], v230 offset:15232
	s_waitcnt lgkmcnt(3)
	v_pk_mul_f32 v[216:217], v[216:217], v[206:207] op_sel:[0,1]
	s_nop 0
	v_pk_fma_f32 v[218:219], v[58:59], v[206:207], v[216:217] op_sel_hi:[1,0,1] neg_lo:[0,0,1]
	s_nop 0
	v_pk_mov_b32 v[206:207], v[62:63], v[62:63] op_sel:[1,0]
	s_waitcnt lgkmcnt(2)
	v_pk_mul_f32 v[206:207], v[206:207], v[200:201] op_sel:[0,1]
	s_nop 0
	v_pk_fma_f32 v[216:217], v[62:63], v[200:201], v[206:207] op_sel_hi:[1,0,1] neg_lo:[0,0,1]
	s_nop 0
	v_pk_mov_b32 v[200:201], v[66:67], v[66:67] op_sel:[1,0]
	s_waitcnt lgkmcnt(1)
	v_pk_mul_f32 v[200:201], v[200:201], v[212:213] op_sel:[0,1]
	s_nop 0
	v_pk_fma_f32 v[206:207], v[66:67], v[212:213], v[200:201] op_sel_hi:[1,0,1] neg_lo:[0,0,1]
	s_nop 0
	v_pk_mov_b32 v[200:201], v[70:71], v[70:71] op_sel:[1,0]
	s_waitcnt lgkmcnt(0)
	v_pk_mul_f32 v[200:201], v[200:201], v[214:215] op_sel:[0,1]
	s_nop 0
	v_pk_fma_f32 v[212:213], v[70:71], v[214:215], v[200:201] op_sel_hi:[1,0,1] neg_lo:[0,0,1]
	ds_read_b64 v[214:215], v230 offset:17408
	ds_read_b64 v[200:201], v230 offset:19584
	ds_read_b64 v[220:221], v230 offset:21760
	ds_read_b64 v[222:223], v230 offset:23936
	s_waitcnt lgkmcnt(3)
	v_pk_mul_f32 v[224:225], v[224:225], v[214:215] op_sel:[0,1]
	s_nop 0
	v_pk_fma_f32 v[226:227], v[74:75], v[214:215], v[224:225] op_sel_hi:[1,0,1] neg_lo:[0,0,1]
	s_nop 0
	v_pk_mov_b32 v[214:215], v[78:79], v[78:79] op_sel:[1,0]
	s_waitcnt lgkmcnt(2)
	v_pk_mul_f32 v[214:215], v[214:215], v[200:201] op_sel:[0,1]
	s_nop 0
	v_pk_fma_f32 v[224:225], v[78:79], v[200:201], v[214:215] op_sel_hi:[1,0,1] neg_lo:[0,0,1]
	s_nop 0
	v_pk_mov_b32 v[200:201], v[84:85], v[84:85] op_sel:[1,0]
	s_waitcnt lgkmcnt(1)
	v_pk_mul_f32 v[200:201], v[200:201], v[220:221] op_sel:[0,1]
	s_nop 0
	v_pk_fma_f32 v[214:215], v[84:85], v[220:221], v[200:201] op_sel_hi:[1,0,1] neg_lo:[0,0,1]
	s_nop 0
	v_pk_mov_b32 v[200:201], v[88:89], v[88:89] op_sel:[1,0]
	s_waitcnt lgkmcnt(0)
	v_pk_mul_f32 v[200:201], v[200:201], v[222:223] op_sel:[0,1]
	s_nop 0
	v_pk_fma_f32 v[220:221], v[88:89], v[222:223], v[200:201] op_sel_hi:[1,0,1] neg_lo:[0,0,1]
	ds_read_b64 v[222:223], v230 offset:26112
	ds_read_b64 v[200:201], v230 offset:28288
	ds_read_b64 v[228:229], v230 offset:30464
	ds_read_b64 v[230:231], v230 offset:32640
	s_waitcnt lgkmcnt(3)
	v_pk_mul_f32 v[234:235], v[234:235], v[222:223] op_sel:[0,1]
	s_nop 0
	v_pk_fma_f32 v[236:237], v[92:93], v[222:223], v[234:235] op_sel_hi:[1,0,1] neg_lo:[0,0,1]
	s_nop 0
	v_pk_mov_b32 v[222:223], v[98:99], v[98:99] op_sel:[1,0]
	s_waitcnt lgkmcnt(2)
	v_pk_mul_f32 v[222:223], v[222:223], v[200:201] op_sel:[0,1]
	s_nop 0
	v_pk_fma_f32 v[234:235], v[98:99], v[200:201], v[222:223] op_sel_hi:[1,0,1] neg_lo:[0,0,1]
	s_nop 0
	v_pk_mov_b32 v[200:201], v[102:103], v[102:103] op_sel:[1,0]
	s_waitcnt lgkmcnt(1)
	v_pk_mul_f32 v[200:201], v[200:201], v[228:229] op_sel:[0,1]
	s_nop 0
	v_pk_fma_f32 v[222:223], v[102:103], v[228:229], v[200:201] op_sel_hi:[1,0,1] neg_lo:[0,0,1]
	s_nop 0
	v_pk_mov_b32 v[200:201], v[106:107], v[106:107] op_sel:[1,0]
	s_waitcnt lgkmcnt(0)
	v_pk_mul_f32 v[200:201], v[200:201], v[230:231] op_sel:[0,1]
	s_nop 0
	v_pk_fma_f32 v[228:229], v[106:107], v[230:231], v[200:201] op_sel_hi:[1,0,1] neg_lo:[0,0,1]
	s_nop 0
	v_pk_add_f32 v[200:201], v[210:211], v[226:227]
	v_pk_add_f32 v[210:211], v[210:211], v[226:227] neg_lo:[0,1] neg_hi:[0,1]
	v_pk_add_f32 v[226:227], v[218:219], v[236:237]
	v_pk_add_f32 v[218:219], v[218:219], v[236:237] neg_lo:[0,1] neg_hi:[0,1]
	s_nop 0
	v_xor_b32_e32 v230, 0x80000000, v219
	v_mov_b32_e32 v231, v218
	v_pk_add_f32 v[218:219], v[200:201], v[226:227]
	v_pk_add_f32 v[200:201], v[200:201], v[226:227] neg_lo:[0,1] neg_hi:[0,1]
	v_pk_add_f32 v[226:227], v[208:209], v[224:225]
	v_pk_add_f32 v[208:209], v[208:209], v[224:225] neg_lo:[0,1] neg_hi:[0,1]
	v_pk_add_f32 v[224:225], v[216:217], v[234:235]
	v_pk_add_f32 v[216:217], v[216:217], v[234:235] neg_lo:[0,1] neg_hi:[0,1]
	v_pk_add_f32 v[236:237], v[210:211], v[230:231]
	v_pk_add_f32 v[210:211], v[210:211], v[230:231] neg_lo:[0,1] neg_hi:[0,1]
	v_xor_b32_e32 v230, 0x80000000, v217
	v_mov_b32_e32 v231, v216
	v_pk_add_f32 v[216:217], v[226:227], v[224:225]
	v_pk_add_f32 v[224:225], v[226:227], v[224:225] neg_lo:[0,1] neg_hi:[0,1]
	v_pk_add_f32 v[226:227], v[202:203], v[214:215]
	v_pk_add_f32 v[202:203], v[202:203], v[214:215] neg_lo:[0,1] neg_hi:[0,1]
	v_pk_add_f32 v[214:215], v[206:207], v[222:223]
	v_pk_add_f32 v[206:207], v[206:207], v[222:223] neg_lo:[0,1] neg_hi:[0,1]
	v_pk_add_f32 v[234:235], v[208:209], v[230:231]
	v_xor_b32_e32 v222, 0x80000000, v207
	v_mov_b32_e32 v223, v206
	v_pk_add_f32 v[208:209], v[208:209], v[230:231] neg_lo:[0,1] neg_hi:[0,1]
	v_pk_add_f32 v[230:231], v[202:203], v[222:223]
	v_pk_add_f32 v[202:203], v[202:203], v[222:223] neg_lo:[0,1] neg_hi:[0,1]
	v_pk_add_f32 v[222:223], v[204:205], v[220:221]
	v_pk_add_f32 v[204:205], v[204:205], v[220:221] neg_lo:[0,1] neg_hi:[0,1]
	v_pk_add_f32 v[220:221], v[212:213], v[228:229]
	v_pk_add_f32 v[212:213], v[212:213], v[228:229] neg_lo:[0,1] neg_hi:[0,1]
	v_pk_add_f32 v[206:207], v[226:227], v[214:215]
	v_pk_add_f32 v[214:215], v[226:227], v[214:215] neg_lo:[0,1] neg_hi:[0,1]
	v_xor_b32_e32 v226, 0x80000000, v213
	v_mov_b32_e32 v227, v212
	v_pk_add_f32 v[212:213], v[222:223], v[220:221]
	v_pk_add_f32 v[220:221], v[222:223], v[220:221] neg_lo:[0,1] neg_hi:[0,1]
	v_pk_mul_f32 v[222:223], v[234:235], s[24:25] op_sel_hi:[1,0]
	v_pk_add_f32 v[228:229], v[204:205], v[226:227]
	v_pk_add_f32 v[204:205], v[204:205], v[226:227] neg_lo:[0,1] neg_hi:[0,1]
	v_pk_fma_f32 v[226:227], v[234:235], s[26:27], v[222:223] op_sel:[0,0,1] op_sel_hi:[1,0,0] neg_lo:[0,0,1]
	s_nop 0
	v_pk_mul_f32 v[222:223], v[224:225], s[28:29] op_sel_hi:[1,0]
	s_nop 0
	v_pk_fma_f32 v[234:235], v[224:225], s[28:29], v[222:223] op_sel:[0,0,1] op_sel_hi:[1,0,0] neg_lo:[0,0,1]
	v_pk_mul_f32 v[224:225], v[208:209], s[26:27] op_sel_hi:[1,0]
	v_pk_fma_f32 v[238:239], v[208:209], s[24:25], v[224:225] op_sel:[0,0,1] op_sel_hi:[1,0,0] neg_lo:[0,0,1]
	s_nop 0
	v_pk_mul_f32 v[208:209], v[230:231], s[28:29] op_sel_hi:[1,0]
	s_nop 0
	v_pk_fma_f32 v[224:225], v[230:231], s[28:29], v[208:209] op_sel:[0,0,1] op_sel_hi:[1,0,0] neg_lo:[0,0,1]
	s_nop 0
	v_pk_fma_f32 v[208:209], v[214:215], 0, v[214:215] op_sel:[0,0,1] op_sel_hi:[1,0,0] neg_lo:[0,0,1]
	s_nop 0
	v_pk_mul_f32 v[214:215], v[202:203], s[30:31] op_sel_hi:[1,0]
	s_nop 0
	v_pk_fma_f32 v[230:231], v[202:203], s[30:31], v[214:215] op_sel:[0,0,1] op_sel_hi:[1,0,0] neg_hi:[0,0,1]
	v_pk_mul_f32 v[214:215], v[228:229], s[26:27] op_sel_hi:[1,0]
	v_pk_fma_f32 v[242:243], v[228:229], s[24:25], v[214:215] op_sel:[0,0,1] op_sel_hi:[1,0,0] neg_lo:[0,0,1]
	s_mov_b32 s25, s34
	v_pk_mul_f32 v[214:215], v[220:221], s[30:31] op_sel_hi:[1,0]
	v_pk_add_f32 v[202:203], v[210:211], v[230:231]
	v_pk_fma_f32 v[228:229], v[220:221], s[30:31], v[214:215] op_sel:[0,0,1] op_sel_hi:[1,0,0] neg_hi:[0,0,1]
	v_pk_add_f32 v[210:211], v[210:211], v[230:231] neg_lo:[0,1] neg_hi:[0,1]
	v_pk_mul_f32 v[214:215], v[204:205], s[34:35] op_sel_hi:[0,1]
	v_pk_fma_f32 v[204:205], v[204:205], s[24:25], v[214:215] op_sel:[1,0,0]
	v_pk_add_f32 v[214:215], v[218:219], v[206:207]
	v_pk_add_f32 v[206:207], v[218:219], v[206:207] neg_lo:[0,1] neg_hi:[0,1]
	v_pk_add_f32 v[218:219], v[216:217], v[212:213]
	v_pk_add_f32 v[212:213], v[216:217], v[212:213] neg_lo:[0,1] neg_hi:[0,1]
	v_pk_add_f32 v[222:223], v[234:235], v[228:229] neg_lo:[0,1] neg_hi:[0,1]
	v_xor_b32_e32 v216, 0x80000000, v213
	v_mov_b32_e32 v217, v212
	v_pk_add_f32 v[212:213], v[214:215], v[218:219]
	v_pk_add_f32 v[220:221], v[206:207], v[216:217]
	v_pk_add_f32 v[214:215], v[214:215], v[218:219] neg_lo:[0,1] neg_hi:[0,1]
	v_pk_add_f32 v[206:207], v[206:207], v[216:217] neg_lo:[0,1] neg_hi:[0,1]
	v_pk_add_f32 v[216:217], v[236:237], v[224:225]
	v_pk_add_f32 v[218:219], v[236:237], v[224:225] neg_lo:[0,1] neg_hi:[0,1]
	v_pk_add_f32 v[224:225], v[226:227], v[242:243]
	v_pk_add_f32 v[226:227], v[226:227], v[242:243] neg_lo:[0,1] neg_hi:[0,1]
	s_nop 0
	v_xor_b32_e32 v236, 0x80000000, v227
	v_mov_b32_e32 v237, v226
	v_pk_add_f32 v[226:227], v[216:217], v[224:225]
	v_pk_add_f32 v[216:217], v[216:217], v[224:225] neg_lo:[0,1] neg_hi:[0,1]
	v_pk_add_f32 v[224:225], v[200:201], v[208:209]
	v_pk_add_f32 v[200:201], v[200:201], v[208:209] neg_lo:[0,1] neg_hi:[0,1]
	v_pk_add_f32 v[208:209], v[234:235], v[228:229]
	v_xor_b32_e32 v228, 0x80000000, v223
	v_mov_b32_e32 v229, v222
	v_pk_add_f32 v[222:223], v[224:225], v[208:209]
	v_pk_add_f32 v[208:209], v[224:225], v[208:209] neg_lo:[0,1] neg_hi:[0,1]
	v_pk_add_f32 v[224:225], v[238:239], v[204:205]
	v_pk_add_f32 v[204:205], v[238:239], v[204:205] neg_lo:[0,1] neg_hi:[0,1]
	v_pk_add_f32 v[234:235], v[200:201], v[228:229]
	v_pk_add_f32 v[200:201], v[200:201], v[228:229] neg_lo:[0,1] neg_hi:[0,1]
	v_xor_b32_e32 v228, 0x80000000, v205
	v_mov_b32_e32 v229, v204
	v_pk_add_f32 v[204:205], v[202:203], v[224:225]
	v_pk_add_f32 v[202:203], v[202:203], v[224:225] neg_lo:[0,1] neg_hi:[0,1]
	v_lshlrev_b32_e32 v224, 7, v233
	v_add3_u32 v181, v181, v224, v244
	v_add_u32_e32 v224, 0x1880, v181
	ds_write2_b64 v224, v[212:213], v[226:227] offset1:1
	v_add_u32_e32 v212, 0x1890, v181
	v_pk_add_f32 v[242:243], v[218:219], v[236:237]
	ds_write2_b64 v212, v[222:223], v[204:205] offset1:1
	v_add_u32_e32 v204, 0x18a0, v181
	v_pk_add_f32 v[230:231], v[210:211], v[228:229]
	ds_write2_b64 v204, v[220:221], v[242:243] offset1:1
	v_add_u32_e32 v204, 0x18b0, v181
	ds_write2_b64 v204, v[234:235], v[230:231] offset1:1
	v_add_u32_e32 v204, 0x18c0, v181
	ds_write2_b64 v204, v[214:215], v[216:217] offset1:1
	v_add_u32_e32 v204, 0x18d0, v181
	v_pk_add_f32 v[218:219], v[218:219], v[236:237] neg_lo:[0,1] neg_hi:[0,1]
	v_pk_add_f32 v[210:211], v[210:211], v[228:229] neg_lo:[0,1] neg_hi:[0,1]
	ds_write2_b64 v204, v[208:209], v[202:203] offset1:1
	v_add_u32_e32 v202, 0x18e0, v181
	v_add_u32_e32 v181, 0x18f0, v181
	ds_write2_b64 v202, v[206:207], v[218:219] offset1:1
	ds_write2_b64 v181, v[200:201], v[210:211] offset1:1
.LBB0_364:
	s_or_b64 exec, exec, s[2:3]
	v_mov_b32_e32 v200, v180
	s_waitcnt lgkmcnt(0)
	s_barrier
	s_nop 0
	v_cmp_gt_i32_e32 vcc, s56, v200
	s_and_saveexec_b64 s[2:3], vcc
	s_cbranch_execz .LBB0_366
	v_ashrrev_i32_e32 v181, 31, v200
	v_add_u32_sdwa v181, v200, v181 dst_sel:DWORD dst_unused:UNUSED_PAD src0_sel:DWORD src1_sel:BYTE_3
	v_ashrrev_i32_e32 v181, 8, v181
	v_mul_i32_i24_e32 v201, 0x100, v181
	v_sub_u32_e32 v200, v200, v201
	v_ashrrev_i16_e32 v201, 15, v200
	v_lshrrev_b16_e32 v201, 12, v201
	v_add_u16_e32 v201, v200, v201
	v_ashrrev_i16_e32 v233, 4, v201
	v_and_b32_e32 v201, -16, v201
	v_mul_i32_i24_e32 v181, 0x1100, v181
	v_sub_u16_e32 v204, v200, v201
	v_lshlrev_b32_e32 v234, 3, v181
	v_lshlrev_b32_e32 v201, 3, v200
	v_ashrrev_i32_e32 v200, 4, v200
	v_add_u32_e32 v181, 0, v234
	v_lshlrev_b32_e32 v200, 3, v200
	v_add3_u32 v181, v181, v201, v200
	v_bfe_i32 v235, v204, 0, 16
	ds_read_b64 v[200:201], v181 offset:6272
	ds_read_b64 v[202:203], v181 offset:8448
	ds_read_b64 v[214:215], v181 offset:10624
	ds_read_b64 v[216:217], v181 offset:12800
	ds_read_b64 v[218:219], v181 offset:14976
	ds_read_b64 v[222:223], v181 offset:17152
	ds_read_b64 v[224:225], v181 offset:19328
	ds_read_b64 v[226:227], v181 offset:21504
	ds_read_b64 v[228:229], v181 offset:23680
	ds_read_b64 v[230:231], v181 offset:25856
	ds_read_b64 v[236:237], v181 offset:28032
	ds_read_b64 v[238:239], v181 offset:30208
	ds_read_b64 v[242:243], v181 offset:32384
	ds_read_b64 v[244:245], v181 offset:34560
	ds_read_b64 v[246:247], v181 offset:36736
	ds_read_b64 v[206:207], v181 offset:38912
	v_mad_i32_i24 v181, v235, s27, 0
	v_add_u32_e32 v204, 0x808, v181
	ds_read2_b64 v[210:213], v204 offset1:1
	s_mov_b32 s35, s60
	s_waitcnt lgkmcnt(0)
	v_pk_mul_f32 v[204:205], v[202:203], v[210:211] op_sel:[1,1] op_sel_hi:[0,1]
	v_pk_fma_f32 v[208:209], v[202:203], v[210:211], v[204:205]
	v_pk_fma_f32 v[202:203], v[202:203], v[210:211], v[204:205] op_sel_hi:[1,0,1] neg_lo:[0,0,1] neg_hi:[0,0,1]
	s_nop 0
	v_mov_b32_e32 v202, v213
	v_mov_b32_e32 v209, v203
	v_pk_mul_f32 v[202:203], v[214:215], v[202:203] op_sel:[1,0] op_sel_hi:[0,0]
	v_pk_fma_f32 v[204:205], v[214:215], v[212:213], v[202:203]
	v_pk_fma_f32 v[202:203], v[214:215], v[212:213], v[202:203] op_sel_hi:[1,0,1] neg_lo:[0,0,1] neg_hi:[0,0,1]
	s_nop 0
	v_add_u32_e32 v202, 0x818, v181
	ds_read2_b64 v[210:213], v202 offset1:1
	v_mov_b32_e32 v205, v203
	s_waitcnt lgkmcnt(0)
	v_pk_mul_f32 v[214:215], v[216:217], v[210:211] op_sel:[1,1] op_sel_hi:[0,1]
	v_pk_fma_f32 v[202:203], v[216:217], v[210:211], v[214:215]
	v_pk_fma_f32 v[210:211], v[216:217], v[210:211], v[214:215] op_sel_hi:[1,0,1] neg_lo:[0,0,1] neg_hi:[0,0,1]
	s_nop 0
	v_mov_b32_e32 v210, v213
	v_mov_b32_e32 v203, v211
	v_pk_mul_f32 v[210:211], v[218:219], v[210:211] op_sel:[1,0] op_sel_hi:[0,0]
	v_pk_fma_f32 v[216:217], v[218:219], v[212:213], v[210:211]
	v_pk_fma_f32 v[210:211], v[218:219], v[212:213], v[210:211] op_sel_hi:[1,0,1] neg_lo:[0,0,1] neg_hi:[0,0,1]
	s_nop 0
	v_add_u32_e32 v210, 0x828, v181
	ds_read2_b64 v[218:221], v210 offset1:1
	v_mov_b32_e32 v217, v211
	s_waitcnt lgkmcnt(0)
	v_pk_mul_f32 v[210:211], v[222:223], v[218:219] op_sel:[1,1] op_sel_hi:[0,1]
	v_pk_fma_f32 v[214:215], v[222:223], v[218:219], v[210:211]
	v_pk_fma_f32 v[210:211], v[222:223], v[218:219], v[210:211] op_sel_hi:[1,0,1] neg_lo:[0,0,1] neg_hi:[0,0,1]
	s_nop 0
	v_mov_b32_e32 v210, v221
	v_mov_b32_e32 v215, v211
	v_pk_mul_f32 v[210:211], v[224:225], v[210:211] op_sel:[1,0] op_sel_hi:[0,0]
	v_pk_fma_f32 v[212:213], v[224:225], v[220:221], v[210:211]
	v_pk_fma_f32 v[210:211], v[224:225], v[220:221], v[210:211] op_sel_hi:[1,0,1] neg_lo:[0,0,1] neg_hi:[0,0,1]
	s_nop 0
	v_add_u32_e32 v210, 0x838, v181
	ds_read2_b64 v[218:221], v210 offset1:1
	v_mov_b32_e32 v213, v211
	s_waitcnt lgkmcnt(0)
	v_pk_mul_f32 v[222:223], v[226:227], v[218:219] op_sel:[1,1] op_sel_hi:[0,1]
	v_pk_fma_f32 v[210:211], v[226:227], v[218:219], v[222:223]
	v_pk_fma_f32 v[218:219], v[226:227], v[218:219], v[222:223] op_sel_hi:[1,0,1] neg_lo:[0,0,1] neg_hi:[0,0,1]
	s_nop 0
	v_mov_b32_e32 v218, v221
	v_mov_b32_e32 v211, v219
	v_pk_mul_f32 v[218:219], v[228:229], v[218:219] op_sel:[1,0] op_sel_hi:[0,0]
	v_pk_fma_f32 v[224:225], v[228:229], v[220:221], v[218:219]
	v_pk_fma_f32 v[218:219], v[228:229], v[220:221], v[218:219] op_sel_hi:[1,0,1] neg_lo:[0,0,1] neg_hi:[0,0,1]
	s_nop 0
	v_add_u32_e32 v218, 0x848, v181
	ds_read2_b64 v[226:229], v218 offset1:1
	v_mov_b32_e32 v225, v219
	s_waitcnt lgkmcnt(0)
	v_pk_mul_f32 v[218:219], v[230:231], v[226:227] op_sel:[1,1] op_sel_hi:[0,1]
	v_pk_fma_f32 v[222:223], v[230:231], v[226:227], v[218:219]
	v_pk_fma_f32 v[218:219], v[230:231], v[226:227], v[218:219] op_sel_hi:[1,0,1] neg_lo:[0,0,1] neg_hi:[0,0,1]
	s_nop 0
	v_mov_b32_e32 v218, v229
	v_mov_b32_e32 v223, v219
	v_pk_mul_f32 v[218:219], v[236:237], v[218:219] op_sel:[1,0] op_sel_hi:[0,0]
	v_pk_fma_f32 v[220:221], v[236:237], v[228:229], v[218:219]
	v_pk_fma_f32 v[218:219], v[236:237], v[228:229], v[218:219] op_sel_hi:[1,0,1] neg_lo:[0,0,1] neg_hi:[0,0,1]
	s_nop 0
	v_add_u32_e32 v218, 0x858, v181
	ds_read2_b64 v[226:229], v218 offset1:1
	v_mov_b32_e32 v221, v219
	s_waitcnt lgkmcnt(0)
	v_pk_mul_f32 v[230:231], v[238:239], v[226:227] op_sel:[1,1] op_sel_hi:[0,1]
	v_pk_fma_f32 v[218:219], v[238:239], v[226:227], v[230:231]
	v_pk_fma_f32 v[226:227], v[238:239], v[226:227], v[230:231] op_sel_hi:[1,0,1] neg_lo:[0,0,1] neg_hi:[0,0,1]
	s_nop 0
	v_mov_b32_e32 v226, v229
	v_mov_b32_e32 v219, v227
	v_pk_mul_f32 v[226:227], v[242:243], v[226:227] op_sel:[1,0] op_sel_hi:[0,0]
	v_pk_fma_f32 v[230:231], v[242:243], v[228:229], v[226:227]
	v_pk_fma_f32 v[226:227], v[242:243], v[228:229], v[226:227] op_sel_hi:[1,0,1] neg_lo:[0,0,1] neg_hi:[0,0,1]
	s_nop 0
	v_add_u32_e32 v226, 0x868, v181
	ds_read2_b64 v[236:239], v226 offset1:1
	v_mov_b32_e32 v231, v227
	s_waitcnt lgkmcnt(0)
	v_pk_mul_f32 v[226:227], v[244:245], v[236:237] op_sel:[1,1] op_sel_hi:[0,1]
	v_pk_fma_f32 v[228:229], v[244:245], v[236:237], v[226:227]
	v_pk_fma_f32 v[226:227], v[244:245], v[236:237], v[226:227] op_sel_hi:[1,0,1] neg_lo:[0,0,1] neg_hi:[0,0,1]
	s_nop 0
	v_mov_b32_e32 v226, v239
	v_pk_mul_f32 v[236:237], v[246:247], v[226:227] op_sel:[1,0] op_sel_hi:[0,0]
	v_mov_b32_e32 v229, v227
	v_pk_fma_f32 v[226:227], v[246:247], v[238:239], v[236:237] op_sel_hi:[1,0,1] neg_hi:[0,0,1]
	s_nop 0
	ds_read_b64 v[236:237], v181 offset:2168
	v_bfe_i32 v181, v233, 0, 16
	v_lshl_add_u32 v181, v181, 8, v235
	s_waitcnt lgkmcnt(0)
	v_pk_mul_f32 v[238:239], v[206:207], v[236:237] op_sel:[1,1] op_sel_hi:[0,1]
	v_pk_fma_f32 v[242:243], v[206:207], v[236:237], v[238:239] op_sel_hi:[1,0,1] neg_hi:[0,0,1]
	s_nop 0
	v_pk_add_f32 v[206:207], v[200:201], v[224:225]
	v_pk_add_f32 v[200:201], v[200:201], v[224:225] neg_lo:[0,1] neg_hi:[0,1]
	v_pk_add_f32 v[224:225], v[216:217], v[230:231]
	v_pk_add_f32 v[216:217], v[216:217], v[230:231] neg_lo:[0,1] neg_hi:[0,1]
	s_nop 0
	v_xor_b32_e32 v230, 0x80000000, v217
	v_mov_b32_e32 v231, v216
	v_pk_add_f32 v[216:217], v[206:207], v[224:225]
	v_pk_add_f32 v[206:207], v[206:207], v[224:225] neg_lo:[0,1] neg_hi:[0,1]
	v_pk_add_f32 v[224:225], v[208:209], v[222:223]
	v_pk_add_f32 v[208:209], v[208:209], v[222:223] neg_lo:[0,1] neg_hi:[0,1]
	v_pk_add_f32 v[222:223], v[214:215], v[228:229]
	v_pk_add_f32 v[214:215], v[214:215], v[228:229] neg_lo:[0,1] neg_hi:[0,1]
	v_pk_add_f32 v[236:237], v[200:201], v[230:231]
	v_xor_b32_e32 v228, 0x80000000, v215
	v_mov_b32_e32 v229, v214
	v_pk_add_f32 v[214:215], v[224:225], v[222:223]
	v_pk_add_f32 v[222:223], v[224:225], v[222:223] neg_lo:[0,1] neg_hi:[0,1]
	v_pk_add_f32 v[224:225], v[204:205], v[220:221]
	v_pk_add_f32 v[204:205], v[204:205], v[220:221] neg_lo:[0,1] neg_hi:[0,1]
	v_pk_add_f32 v[220:221], v[212:213], v[226:227]
	v_pk_add_f32 v[212:213], v[212:213], v[226:227] neg_lo:[0,1] neg_hi:[0,1]
	v_pk_add_f32 v[200:201], v[200:201], v[230:231] neg_lo:[0,1] neg_hi:[0,1]
	v_pk_add_f32 v[230:231], v[208:209], v[228:229]
	v_xor_b32_e32 v226, 0x80000000, v213
	v_mov_b32_e32 v227, v212
	v_pk_add_f32 v[212:213], v[224:225], v[220:221]
	v_pk_add_f32 v[220:221], v[224:225], v[220:221] neg_lo:[0,1] neg_hi:[0,1]
	v_pk_add_f32 v[224:225], v[202:203], v[218:219]
	v_pk_add_f32 v[202:203], v[202:203], v[218:219] neg_lo:[0,1] neg_hi:[0,1]
	v_pk_add_f32 v[218:219], v[210:211], v[242:243]
	v_pk_add_f32 v[210:211], v[210:211], v[242:243] neg_lo:[0,1] neg_hi:[0,1]
	v_pk_add_f32 v[208:209], v[208:209], v[228:229] neg_lo:[0,1] neg_hi:[0,1]
	v_pk_add_f32 v[228:229], v[204:205], v[226:227]
	v_pk_add_f32 v[204:205], v[204:205], v[226:227] neg_lo:[0,1] neg_hi:[0,1]
	v_xor_b32_e32 v226, 0x80000000, v211
	v_mov_b32_e32 v227, v210
	v_pk_add_f32 v[210:211], v[224:225], v[218:219]
	v_pk_add_f32 v[218:219], v[224:225], v[218:219] neg_lo:[0,1] neg_hi:[0,1]
	v_pk_mul_f32 v[224:225], v[230:231], s[24:25] op_sel_hi:[1,0]
	v_pk_add_f32 v[238:239], v[202:203], v[226:227]
	v_pk_add_f32 v[202:203], v[202:203], v[226:227] neg_lo:[0,1] neg_hi:[0,1]
	v_pk_fma_f32 v[226:227], v[230:231], s[26:27], v[224:225] op_sel:[0,0,1] op_sel_hi:[1,0,0] neg_lo:[0,0,1]
	s_nop 0
	v_pk_mul_f32 v[224:225], v[222:223], s[28:29] op_sel_hi:[1,0]
	s_nop 0
	v_pk_fma_f32 v[230:231], v[222:223], s[28:29], v[224:225] op_sel:[0,0,1] op_sel_hi:[1,0,0] neg_lo:[0,0,1]
	v_pk_mul_f32 v[224:225], v[208:209], s[26:27] op_sel_hi:[1,0]
	v_pk_fma_f32 v[242:243], v[208:209], s[24:25], v[224:225] op_sel:[0,0,1] op_sel_hi:[1,0,0] neg_lo:[0,0,1]
	s_nop 0
	v_pk_mul_f32 v[208:209], v[228:229], s[28:29] op_sel_hi:[1,0]
	s_nop 0
	v_pk_fma_f32 v[224:225], v[228:229], s[28:29], v[208:209] op_sel:[0,0,1] op_sel_hi:[1,0,0] neg_lo:[0,0,1]
	s_nop 0
	v_pk_fma_f32 v[208:209], v[220:221], 0, v[220:221] op_sel:[0,0,1] op_sel_hi:[1,0,0] neg_lo:[0,0,1]
	s_nop 0
	v_pk_mul_f32 v[220:221], v[204:205], s[30:31] op_sel_hi:[1,0]
	s_nop 0
	v_pk_fma_f32 v[228:229], v[204:205], s[30:31], v[220:221] op_sel:[0,0,1] op_sel_hi:[1,0,0] neg_hi:[0,0,1]
	v_pk_mul_f32 v[220:221], v[238:239], s[26:27] op_sel_hi:[1,0]
	v_pk_fma_f32 v[244:245], v[238:239], s[24:25], v[220:221] op_sel:[0,0,1] op_sel_hi:[1,0,0] neg_lo:[0,0,1]
	s_mov_b32 s25, s34
	v_pk_mul_f32 v[220:221], v[218:219], s[30:31] op_sel_hi:[1,0]
	v_pk_add_f32 v[204:205], v[200:201], v[228:229]
	v_pk_fma_f32 v[238:239], v[218:219], s[30:31], v[220:221] op_sel:[0,0,1] op_sel_hi:[1,0,0] neg_hi:[0,0,1]
	v_pk_add_f32 v[200:201], v[200:201], v[228:229] neg_lo:[0,1] neg_hi:[0,1]
	v_pk_mul_f32 v[218:219], v[202:203], s[34:35] op_sel_hi:[0,1]
	v_pk_fma_f32 v[202:203], v[202:203], s[24:25], v[218:219] op_sel:[1,0,0]
	v_pk_add_f32 v[218:219], v[216:217], v[212:213]
	v_pk_add_f32 v[212:213], v[216:217], v[212:213] neg_lo:[0,1] neg_hi:[0,1]
	v_pk_add_f32 v[216:217], v[214:215], v[210:211]
	v_pk_add_f32 v[210:211], v[214:215], v[210:211] neg_lo:[0,1] neg_hi:[0,1]
	v_pk_add_f32 v[222:223], v[230:231], v[238:239] neg_lo:[0,1] neg_hi:[0,1]
	v_xor_b32_e32 v214, 0x80000000, v211
	v_mov_b32_e32 v215, v210
	v_pk_add_f32 v[210:211], v[218:219], v[216:217]
	v_pk_add_f32 v[220:221], v[212:213], v[214:215]
	v_pk_add_f32 v[216:217], v[218:219], v[216:217] neg_lo:[0,1] neg_hi:[0,1]
	v_pk_add_f32 v[212:213], v[212:213], v[214:215] neg_lo:[0,1] neg_hi:[0,1]
	v_pk_add_f32 v[214:215], v[236:237], v[224:225]
	v_pk_add_f32 v[218:219], v[236:237], v[224:225] neg_lo:[0,1] neg_hi:[0,1]
	v_pk_add_f32 v[224:225], v[226:227], v[244:245]
	v_pk_add_f32 v[226:227], v[226:227], v[244:245] neg_lo:[0,1] neg_hi:[0,1]
	s_nop 0
	v_xor_b32_e32 v236, 0x80000000, v227
	v_mov_b32_e32 v237, v226
	v_pk_add_f32 v[226:227], v[214:215], v[224:225]
	v_pk_add_f32 v[214:215], v[214:215], v[224:225] neg_lo:[0,1] neg_hi:[0,1]
	v_pk_add_f32 v[224:225], v[206:207], v[208:209]
	v_pk_add_f32 v[206:207], v[206:207], v[208:209] neg_lo:[0,1] neg_hi:[0,1]
	v_pk_add_f32 v[208:209], v[230:231], v[238:239]
	v_xor_b32_e32 v230, 0x80000000, v223
	v_mov_b32_e32 v231, v222
	v_pk_add_f32 v[222:223], v[224:225], v[208:209]
	v_pk_add_f32 v[208:209], v[224:225], v[208:209] neg_lo:[0,1] neg_hi:[0,1]
	v_pk_add_f32 v[224:225], v[242:243], v[202:203]
	v_pk_add_f32 v[202:203], v[242:243], v[202:203] neg_lo:[0,1] neg_hi:[0,1]
	v_pk_add_f32 v[244:245], v[218:219], v[236:237]
	v_xor_b32_e32 v228, 0x80000000, v203
	v_mov_b32_e32 v229, v202
	v_pk_add_f32 v[202:203], v[204:205], v[224:225]
	v_pk_add_f32 v[204:205], v[204:205], v[224:225] neg_lo:[0,1] neg_hi:[0,1]
	v_lshlrev_b32_e32 v225, 3, v181
	v_ashrrev_i32_e32 v181, 4, v181
	v_add_u32_e32 v224, s57, v234
	v_lshlrev_b32_e32 v181, 3, v181
	v_add3_u32 v181, v224, v225, v181
	v_pk_add_f32 v[218:219], v[218:219], v[236:237] neg_lo:[0,1] neg_hi:[0,1]
	v_pk_add_f32 v[236:237], v[206:207], v[230:231]
	v_pk_add_f32 v[206:207], v[206:207], v[230:231] neg_lo:[0,1] neg_hi:[0,1]
	v_pk_add_f32 v[230:231], v[200:201], v[228:229]
	v_pk_add_f32 v[200:201], v[200:201], v[228:229] neg_lo:[0,1] neg_hi:[0,1]
	ds_write2_b64 v181, v[210:211], v[226:227] offset1:17
	ds_write2_b64 v181, v[222:223], v[202:203] offset0:34 offset1:51
	ds_write2_b64 v181, v[220:221], v[244:245] offset0:68 offset1:85
	ds_write2_b64 v181, v[236:237], v[230:231] offset0:102 offset1:119
	ds_write2_b64 v181, v[216:217], v[214:215] offset0:136 offset1:153
	ds_write2_b64 v181, v[208:209], v[204:205] offset0:170 offset1:187
	ds_write2_b64 v181, v[212:213], v[218:219] offset0:204 offset1:221
	ds_write2_b64 v181, v[206:207], v[200:201] offset0:238 offset1:255
.LBB0_366:
	s_or_b64 exec, exec, s[2:3]
	v_mov_b32_e32 v200, v180
	s_waitcnt lgkmcnt(0)
	s_barrier
	s_nop 0
	v_cmp_gt_i32_e32 vcc, s56, v200
	s_and_saveexec_b64 s[2:3], vcc
	s_cbranch_execz .LBB0_368
	v_ashrrev_i32_e32 v181, 31, v200
	v_add_u32_sdwa v181, v200, v181 dst_sel:DWORD dst_unused:UNUSED_PAD src0_sel:DWORD src1_sel:BYTE_3
	v_ashrrev_i32_e32 v181, 8, v181
	v_mul_i32_i24_e32 v201, 0x100, v181
	v_sub_u32_e32 v200, v200, v201
	v_mul_i32_i24_e32 v181, 0x1100, v181
	v_lshlrev_b32_e32 v181, 3, v181
	v_lshlrev_b32_e32 v224, 3, v200
	v_ashrrev_i32_e32 v200, 4, v200
	v_add_u32_e32 v201, s57, v181
	v_lshlrev_b32_e32 v233, 3, v200
	v_add3_u32 v234, v201, v224, v233
	v_add_u32_e32 v248, 0, v224
	ds_read_b64 v[200:201], v234
	ds_read_b64 v[202:203], v234 offset:2176
	ds_read_b64 v[204:205], v234 offset:4352
	ds_read_b64 v[206:207], v234 offset:6528
	ds_read_b64 v[208:209], v234 offset:8704
	ds_read_b64 v[210:211], v234 offset:10880
	ds_read_b64 v[212:213], v234 offset:13056
	ds_read_b64 v[214:215], v234 offset:15232
	ds_read_b64 v[216:217], v234 offset:17408
	ds_read_b64 v[218:219], v234 offset:19584
	ds_read_b64 v[220:221], v234 offset:21760
	ds_read_b64 v[222:223], v234 offset:23936
	ds_read_b64 v[224:225], v248
	ds_read_b64 v[226:227], v234 offset:26112
	ds_read_b64 v[228:229], v234 offset:28288
	ds_read_b64 v[230:231], v234 offset:30464
	ds_read_b64 v[234:235], v234 offset:32640
	s_waitcnt lgkmcnt(4)
	v_pk_mul_f32 v[238:239], v[202:203], v[224:225] op_sel:[0,1]
	v_xor_b32_e32 v236, 0x80000000, v225
	v_pk_fma_f32 v[242:243], v[202:203], v[224:225], v[238:239] op_sel:[0,0,1] op_sel_hi:[1,0,0] neg_hi:[0,0,1]
	v_mov_b32_e32 v237, v224
	v_pk_mul_f32 v[202:203], v[224:225], v[224:225] op_sel:[1,0]
	s_mov_b32 s35, s60
	v_pk_fma_f32 v[202:203], v[224:225], v[236:237], v[202:203] op_sel_hi:[0,1,1] neg_lo:[0,0,1] neg_hi:[0,0,1]
	v_pk_mul_f32 v[236:237], v[204:205], v[202:203] op_sel:[1,0] op_sel_hi:[0,0]
	v_pk_fma_f32 v[238:239], v[204:205], v[202:203], v[236:237] op_sel:[0,1,0] neg_lo:[0,0,1]
	v_add3_u32 v181, v248, v181, v233
	v_pk_mul_f32 v[204:205], v[224:225], v[202:203] op_sel:[0,1] op_sel_hi:[1,0]
	v_pk_mul_f32 v[202:203], v[224:225], v[202:203]
	v_pk_add_f32 v[204:205], v[204:205], v[204:205] op_sel:[0,1] op_sel_hi:[0,1]
	v_pk_add_f32 v[202:203], v[202:203], v[202:203] op_sel:[0,1] op_sel_hi:[0,1] neg_lo:[0,1] neg_hi:[0,1]
	v_pk_mul_f32 v[236:237], v[206:207], v[202:203]
	s_nop 0
	v_pk_fma_f32 v[244:245], v[206:207], v[204:205], v[236:237] op_sel:[0,0,1] op_sel_hi:[1,1,0] neg_lo:[0,0,1]
	v_pk_mul_f32 v[204:205], v[224:225], v[204:205]
	v_pk_fma_f32 v[206:207], v[224:225], v[202:203], v[204:205] op_sel:[0,0,1] op_sel_hi:[1,1,0] neg_lo:[0,0,1] neg_hi:[0,0,1]
	v_pk_fma_f32 v[202:203], v[224:225], v[202:203], v[204:205] op_sel:[0,0,1] op_sel_hi:[1,1,0]
	v_mov_b32_e32 v204, v206
	v_mov_b32_e32 v205, v203
	v_pk_mul_f32 v[236:237], v[208:209], v[206:207] op_sel:[1,0] op_sel_hi:[0,0]
	v_pk_mov_b32 v[206:207], v[202:203], v[206:207] op_sel:[1,0]
	v_pk_fma_f32 v[246:247], v[208:209], v[202:203], v[236:237] op_sel:[0,1,0] neg_lo:[0,0,1]
	v_pk_mul_f32 v[204:205], v[224:225], v[204:205]
	v_pk_mul_f32 v[202:203], v[224:225], v[206:207]
	v_pk_add_f32 v[204:205], v[204:205], v[204:205] op_sel:[0,1] op_sel_hi:[0,1] neg_lo:[0,1] neg_hi:[0,1]
	v_pk_mul_f32 v[206:207], v[210:211], v[204:205]
	v_pk_add_f32 v[202:203], v[202:203], v[202:203] op_sel:[0,1] op_sel_hi:[0,1]
	v_pk_fma_f32 v[208:209], v[210:211], v[202:203], v[206:207] op_sel:[0,0,1] op_sel_hi:[1,1,0] neg_lo:[0,0,1]
	v_pk_mul_f32 v[202:203], v[224:225], v[202:203]
	v_pk_fma_f32 v[206:207], v[224:225], v[204:205], v[202:203] op_sel:[0,0,1] op_sel_hi:[1,1,0] neg_lo:[0,0,1] neg_hi:[0,0,1]
	v_pk_fma_f32 v[202:203], v[224:225], v[204:205], v[202:203] op_sel:[0,0,1] op_sel_hi:[1,1,0]
	v_mov_b32_e32 v204, v206
	v_mov_b32_e32 v205, v203
	v_pk_mul_f32 v[210:211], v[212:213], v[206:207] op_sel:[1,0] op_sel_hi:[0,0]
	v_pk_mov_b32 v[206:207], v[202:203], v[206:207] op_sel:[1,0]
	v_pk_fma_f32 v[236:237], v[212:213], v[202:203], v[210:211] op_sel:[0,1,0] neg_lo:[0,0,1]
	v_pk_mul_f32 v[204:205], v[224:225], v[204:205]
	v_pk_mul_f32 v[202:203], v[224:225], v[206:207]
	v_pk_add_f32 v[204:205], v[204:205], v[204:205] op_sel:[0,1] op_sel_hi:[0,1] neg_lo:[0,1] neg_hi:[0,1]
	v_pk_mul_f32 v[206:207], v[214:215], v[204:205]
	v_pk_add_f32 v[202:203], v[202:203], v[202:203] op_sel:[0,1] op_sel_hi:[0,1]
	v_pk_fma_f32 v[210:211], v[214:215], v[202:203], v[206:207] op_sel:[0,0,1] op_sel_hi:[1,1,0] neg_lo:[0,0,1]
	v_pk_mul_f32 v[202:203], v[224:225], v[202:203]
	v_pk_fma_f32 v[206:207], v[224:225], v[204:205], v[202:203] op_sel:[0,0,1] op_sel_hi:[1,1,0] neg_lo:[0,0,1] neg_hi:[0,0,1]
	v_pk_fma_f32 v[202:203], v[224:225], v[204:205], v[202:203] op_sel:[0,0,1] op_sel_hi:[1,1,0]
	v_mov_b32_e32 v204, v206
	v_mov_b32_e32 v205, v203
	v_pk_mul_f32 v[212:213], v[216:217], v[206:207] op_sel:[1,0] op_sel_hi:[0,0]
	v_pk_mov_b32 v[206:207], v[202:203], v[206:207] op_sel:[1,0]
	v_pk_fma_f32 v[214:215], v[216:217], v[202:203], v[212:213] op_sel:[0,1,0] neg_lo:[0,0,1]
	v_pk_mul_f32 v[204:205], v[224:225], v[204:205]
	v_pk_mul_f32 v[202:203], v[224:225], v[206:207]
	v_pk_add_f32 v[204:205], v[204:205], v[204:205] op_sel:[0,1] op_sel_hi:[0,1] neg_lo:[0,1] neg_hi:[0,1]
	v_pk_mul_f32 v[206:207], v[218:219], v[204:205]
	v_pk_add_f32 v[202:203], v[202:203], v[202:203] op_sel:[0,1] op_sel_hi:[0,1]
	v_pk_fma_f32 v[212:213], v[218:219], v[202:203], v[206:207] op_sel:[0,0,1] op_sel_hi:[1,1,0] neg_lo:[0,0,1]
	v_pk_mul_f32 v[202:203], v[224:225], v[202:203]
	v_pk_fma_f32 v[206:207], v[224:225], v[204:205], v[202:203] op_sel:[0,0,1] op_sel_hi:[1,1,0] neg_lo:[0,0,1] neg_hi:[0,0,1]
	v_pk_fma_f32 v[202:203], v[224:225], v[204:205], v[202:203] op_sel:[0,0,1] op_sel_hi:[1,1,0]
	v_mov_b32_e32 v204, v206
	v_mov_b32_e32 v205, v203
	v_pk_mul_f32 v[216:217], v[220:221], v[206:207] op_sel:[1,0] op_sel_hi:[0,0]
	v_pk_mov_b32 v[206:207], v[202:203], v[206:207] op_sel:[1,0]
	v_pk_fma_f32 v[218:219], v[220:221], v[202:203], v[216:217] op_sel:[0,1,0] neg_lo:[0,0,1]
	v_pk_mul_f32 v[204:205], v[224:225], v[204:205]
	v_pk_mul_f32 v[202:203], v[224:225], v[206:207]
	v_pk_add_f32 v[204:205], v[204:205], v[204:205] op_sel:[0,1] op_sel_hi:[0,1] neg_lo:[0,1] neg_hi:[0,1]
	v_pk_mul_f32 v[206:207], v[222:223], v[204:205]
	v_pk_add_f32 v[202:203], v[202:203], v[202:203] op_sel:[0,1] op_sel_hi:[0,1]
	v_pk_fma_f32 v[216:217], v[222:223], v[202:203], v[206:207] op_sel:[0,0,1] op_sel_hi:[1,1,0] neg_lo:[0,0,1]
	v_pk_mul_f32 v[202:203], v[224:225], v[202:203]
	v_pk_fma_f32 v[206:207], v[224:225], v[204:205], v[202:203] op_sel:[0,0,1] op_sel_hi:[1,1,0] neg_lo:[0,0,1] neg_hi:[0,0,1]
	v_pk_fma_f32 v[202:203], v[224:225], v[204:205], v[202:203] op_sel:[0,0,1] op_sel_hi:[1,1,0]
	v_mov_b32_e32 v204, v206
	v_mov_b32_e32 v205, v203
	s_waitcnt lgkmcnt(3)
	v_pk_mul_f32 v[220:221], v[226:227], v[206:207] op_sel:[1,0] op_sel_hi:[0,0]
	v_pk_mov_b32 v[206:207], v[202:203], v[206:207] op_sel:[1,0]
	v_pk_fma_f32 v[222:223], v[226:227], v[202:203], v[220:221] op_sel:[0,1,0] neg_lo:[0,0,1]
	v_pk_mul_f32 v[204:205], v[224:225], v[204:205]
	v_pk_mul_f32 v[202:203], v[224:225], v[206:207]
	v_pk_add_f32 v[204:205], v[204:205], v[204:205] op_sel:[0,1] op_sel_hi:[0,1] neg_lo:[0,1] neg_hi:[0,1]
	s_waitcnt lgkmcnt(2)
	v_pk_mul_f32 v[206:207], v[228:229], v[204:205]
	v_pk_add_f32 v[202:203], v[202:203], v[202:203] op_sel:[0,1] op_sel_hi:[0,1]
	v_pk_fma_f32 v[220:221], v[228:229], v[202:203], v[206:207] op_sel:[0,0,1] op_sel_hi:[1,1,0] neg_lo:[0,0,1]
	v_pk_mul_f32 v[202:203], v[224:225], v[202:203]
	v_pk_fma_f32 v[206:207], v[224:225], v[204:205], v[202:203] op_sel:[0,0,1] op_sel_hi:[1,1,0] neg_lo:[0,0,1] neg_hi:[0,0,1]
	v_pk_fma_f32 v[202:203], v[224:225], v[204:205], v[202:203] op_sel:[0,0,1] op_sel_hi:[1,1,0]
	v_mov_b32_e32 v204, v206
	v_mov_b32_e32 v205, v203
	s_waitcnt lgkmcnt(1)
	v_pk_mul_f32 v[226:227], v[230:231], v[206:207] op_sel:[1,0] op_sel_hi:[0,0]
	v_pk_mov_b32 v[206:207], v[202:203], v[206:207] op_sel:[1,0]
	v_pk_fma_f32 v[228:229], v[230:231], v[202:203], v[226:227] op_sel:[0,1,0] neg_lo:[0,0,1]
	v_pk_mul_f32 v[204:205], v[224:225], v[204:205]
	v_pk_mul_f32 v[202:203], v[224:225], v[206:207]
	v_pk_add_f32 v[204:205], v[204:205], v[204:205] op_sel:[0,1] op_sel_hi:[0,1] neg_lo:[0,1] neg_hi:[0,1]
	s_waitcnt lgkmcnt(0)
	v_pk_mul_f32 v[204:205], v[234:235], v[204:205] op_sel:[1,0] op_sel_hi:[0,1]
	v_pk_add_f32 v[202:203], v[202:203], v[202:203] op_sel:[0,1] op_sel_hi:[0,1]
	v_pk_fma_f32 v[206:207], v[234:235], v[202:203], v[204:205] neg_lo:[0,0,1]
	v_pk_add_f32 v[204:205], v[246:247], v[222:223]
	v_pk_add_f32 v[202:203], v[200:201], v[214:215]
	v_pk_add_f32 v[200:201], v[200:201], v[214:215] neg_lo:[0,1] neg_hi:[0,1]
	v_pk_add_f32 v[214:215], v[246:247], v[222:223] neg_lo:[0,1] neg_hi:[0,1]
	s_nop 0
	v_xor_b32_e32 v222, 0x80000000, v215
	v_mov_b32_e32 v223, v214
	v_pk_add_f32 v[214:215], v[202:203], v[204:205]
	v_pk_add_f32 v[224:225], v[200:201], v[222:223]
	v_pk_add_f32 v[202:203], v[202:203], v[204:205] neg_lo:[0,1] neg_hi:[0,1]
	v_pk_add_f32 v[200:201], v[200:201], v[222:223] neg_lo:[0,1] neg_hi:[0,1]
	v_pk_add_f32 v[204:205], v[242:243], v[212:213]
	v_pk_add_f32 v[222:223], v[208:209], v[220:221]
	v_pk_add_f32 v[208:209], v[208:209], v[220:221] neg_lo:[0,1] neg_hi:[0,1]
	v_pk_add_f32 v[212:213], v[242:243], v[212:213] neg_lo:[0,1] neg_hi:[0,1]
	v_xor_b32_e32 v220, 0x80000000, v209
	v_mov_b32_e32 v221, v208
	v_pk_add_f32 v[208:209], v[204:205], v[222:223]
	v_pk_add_f32 v[204:205], v[204:205], v[222:223] neg_lo:[0,1] neg_hi:[0,1]
	v_pk_add_f32 v[222:223], v[236:237], v[228:229]
	v_pk_add_f32 v[228:229], v[236:237], v[228:229] neg_lo:[0,1] neg_hi:[0,1]
	v_pk_add_f32 v[226:227], v[212:213], v[220:221]
	v_pk_add_f32 v[212:213], v[212:213], v[220:221] neg_lo:[0,1] neg_hi:[0,1]
	v_pk_add_f32 v[220:221], v[238:239], v[218:219]
	v_pk_add_f32 v[218:219], v[238:239], v[218:219] neg_lo:[0,1] neg_hi:[0,1]
	v_xor_b32_e32 v230, 0x80000000, v229
	v_mov_b32_e32 v231, v228
	v_pk_add_f32 v[234:235], v[218:219], v[230:231]
	v_pk_add_f32 v[218:219], v[218:219], v[230:231] neg_lo:[0,1] neg_hi:[0,1]
	v_pk_add_f32 v[230:231], v[210:211], v[206:207]
	v_pk_add_f32 v[206:207], v[210:211], v[206:207] neg_lo:[0,1] neg_hi:[0,1]
	v_pk_add_f32 v[228:229], v[220:221], v[222:223]
	v_pk_add_f32 v[220:221], v[220:221], v[222:223] neg_lo:[0,1] neg_hi:[0,1]
	v_pk_add_f32 v[222:223], v[244:245], v[216:217]
	v_pk_add_f32 v[216:217], v[244:245], v[216:217] neg_lo:[0,1] neg_hi:[0,1]
	v_xor_b32_e32 v210, 0x80000000, v207
	v_mov_b32_e32 v211, v206
	v_pk_add_f32 v[236:237], v[216:217], v[210:211]
	v_pk_add_f32 v[210:211], v[216:217], v[210:211] neg_lo:[0,1] neg_hi:[0,1]
	v_pk_mul_f32 v[216:217], v[226:227], s[24:25] op_sel_hi:[1,0]
	v_pk_add_f32 v[206:207], v[222:223], v[230:231]
	v_pk_add_f32 v[222:223], v[222:223], v[230:231] neg_lo:[0,1] neg_hi:[0,1]
	v_pk_fma_f32 v[230:231], v[226:227], s[26:27], v[216:217] op_sel:[0,0,1] op_sel_hi:[1,0,0] neg_lo:[0,0,1]
	s_nop 0
	v_pk_mul_f32 v[216:217], v[204:205], s[28:29] op_sel_hi:[1,0]
	s_nop 0
	v_pk_fma_f32 v[226:227], v[204:205], s[28:29], v[216:217] op_sel:[0,0,1] op_sel_hi:[1,0,0] neg_lo:[0,0,1]
	v_pk_mul_f32 v[216:217], v[212:213], s[26:27] op_sel_hi:[1,0]
	v_pk_fma_f32 v[238:239], v[212:213], s[24:25], v[216:217] op_sel:[0,0,1] op_sel_hi:[1,0,0] neg_lo:[0,0,1]
	s_nop 0
	v_pk_mul_f32 v[212:213], v[234:235], s[28:29] op_sel_hi:[1,0]
	s_nop 0
	v_pk_fma_f32 v[216:217], v[234:235], s[28:29], v[212:213] op_sel:[0,0,1] op_sel_hi:[1,0,0] neg_lo:[0,0,1]
	s_nop 0
	v_pk_fma_f32 v[212:213], v[220:221], 0, v[220:221] op_sel:[0,0,1] op_sel_hi:[1,0,0] neg_lo:[0,0,1]
	s_nop 0
	v_pk_mul_f32 v[220:221], v[218:219], s[30:31] op_sel_hi:[1,0]
	s_nop 0
	v_pk_fma_f32 v[234:235], v[218:219], s[30:31], v[220:221] op_sel:[0,0,1] op_sel_hi:[1,0,0] neg_hi:[0,0,1]
	v_pk_mul_f32 v[220:221], v[236:237], s[26:27] op_sel_hi:[1,0]
	v_pk_fma_f32 v[242:243], v[236:237], s[24:25], v[220:221] op_sel:[0,0,1] op_sel_hi:[1,0,0] neg_lo:[0,0,1]
	s_mov_b32 s25, s34
	v_pk_mul_f32 v[220:221], v[222:223], s[30:31] op_sel_hi:[1,0]
	v_pk_add_f32 v[218:219], v[200:201], v[234:235]
	v_pk_fma_f32 v[236:237], v[222:223], s[30:31], v[220:221] op_sel:[0,0,1] op_sel_hi:[1,0,0] neg_hi:[0,0,1]
	v_pk_add_f32 v[222:223], v[208:209], v[206:207]
	v_pk_mul_f32 v[220:221], v[210:211], s[34:35] op_sel_hi:[0,1]
	v_pk_add_f32 v[206:207], v[208:209], v[206:207] neg_lo:[0,1] neg_hi:[0,1]
	v_pk_fma_f32 v[210:211], v[210:211], s[24:25], v[220:221] op_sel:[1,0,0]
	v_pk_add_f32 v[220:221], v[214:215], v[228:229]
	v_pk_add_f32 v[214:215], v[214:215], v[228:229] neg_lo:[0,1] neg_hi:[0,1]
	v_xor_b32_e32 v208, 0x80000000, v207
	v_mov_b32_e32 v209, v206
	v_pk_add_f32 v[206:207], v[220:221], v[222:223]
	v_pk_add_f32 v[228:229], v[214:215], v[208:209]
	v_pk_add_f32 v[220:221], v[220:221], v[222:223] neg_lo:[0,1] neg_hi:[0,1]
	v_pk_add_f32 v[208:209], v[214:215], v[208:209] neg_lo:[0,1] neg_hi:[0,1]
	v_pk_add_f32 v[214:215], v[224:225], v[216:217]
	v_pk_add_f32 v[216:217], v[224:225], v[216:217] neg_lo:[0,1] neg_hi:[0,1]
	v_pk_add_f32 v[222:223], v[230:231], v[242:243]
	v_pk_add_f32 v[224:225], v[230:231], v[242:243] neg_lo:[0,1] neg_hi:[0,1]
	v_pk_add_f32 v[204:205], v[226:227], v[236:237]
	v_xor_b32_e32 v230, 0x80000000, v225
	v_mov_b32_e32 v231, v224
	v_pk_add_f32 v[224:225], v[214:215], v[222:223]
	v_pk_add_f32 v[214:215], v[214:215], v[222:223] neg_lo:[0,1] neg_hi:[0,1]
	v_pk_add_f32 v[222:223], v[202:203], v[212:213]
	v_pk_add_f32 v[202:203], v[202:203], v[212:213] neg_lo:[0,1] neg_hi:[0,1]
	v_pk_add_f32 v[212:213], v[226:227], v[236:237] neg_lo:[0,1] neg_hi:[0,1]
	v_pk_add_f32 v[242:243], v[216:217], v[230:231]
	v_xor_b32_e32 v226, 0x80000000, v213
	v_mov_b32_e32 v227, v212
	v_pk_add_f32 v[212:213], v[222:223], v[204:205]
	v_pk_add_f32 v[204:205], v[222:223], v[204:205] neg_lo:[0,1] neg_hi:[0,1]
	v_pk_add_f32 v[222:223], v[238:239], v[210:211]
	v_pk_add_f32 v[210:211], v[238:239], v[210:211] neg_lo:[0,1] neg_hi:[0,1]
	v_pk_add_f32 v[216:217], v[216:217], v[230:231] neg_lo:[0,1] neg_hi:[0,1]
	v_pk_add_f32 v[230:231], v[202:203], v[226:227]
	v_pk_add_f32 v[202:203], v[202:203], v[226:227] neg_lo:[0,1] neg_hi:[0,1]
	v_pk_add_f32 v[200:201], v[200:201], v[234:235] neg_lo:[0,1] neg_hi:[0,1]
	v_xor_b32_e32 v226, 0x80000000, v211
	v_mov_b32_e32 v227, v210
	v_pk_add_f32 v[210:211], v[218:219], v[222:223]
	v_pk_add_f32 v[234:235], v[200:201], v[226:227]
	v_pk_add_f32 v[218:219], v[218:219], v[222:223] neg_lo:[0,1] neg_hi:[0,1]
	v_pk_add_f32 v[200:201], v[200:201], v[226:227] neg_lo:[0,1] neg_hi:[0,1]
	ds_write_b64 v181, v[206:207] offset:6272
	ds_write_b64 v181, v[224:225] offset:8448
	ds_write_b64 v181, v[212:213] offset:10624
	ds_write_b64 v181, v[210:211] offset:12800
	ds_write_b64 v181, v[228:229] offset:14976
	ds_write_b64 v181, v[242:243] offset:17152
	ds_write_b64 v181, v[230:231] offset:19328
	ds_write_b64 v181, v[234:235] offset:21504
	ds_write_b64 v181, v[220:221] offset:23680
	ds_write_b64 v181, v[214:215] offset:25856
	ds_write_b64 v181, v[204:205] offset:28032
	ds_write_b64 v181, v[218:219] offset:30208
	ds_write_b64 v181, v[208:209] offset:32384
	ds_write_b64 v181, v[216:217] offset:34560
	ds_write_b64 v181, v[202:203] offset:36736
	ds_write_b64 v181, v[200:201] offset:38912
.LBB0_368:
	s_or_b64 exec, exec, s[2:3]
	v_add_u32_e32 v235, 0x1880, v0
	s_waitcnt lgkmcnt(0)
	s_barrier
	ds_read2_b64 v[200:203], v235 offset1:1
	v_add_u32_e32 v236, 0x1890, v0
	v_add_u32_e32 v234, 0xa080, v0
	v_add_u32_e32 v233, 0xa090, v0
	s_waitcnt lgkmcnt(0)
	v_mov_b32_e32 v205, v200
	v_mov_b32_e32 v200, v203
	v_mov_b32_e32 v204, v202
	v_pk_fma_f32 v[192:193], v[2:3], v[192:193], v[200:201]
	ds_read2_b64 v[200:203], v236 offset1:1
	v_pk_fma_f32 v[196:197], v[2:3], v[196:197], v[204:205]
	v_pk_mul_f32 v[192:193], v[170:171], v[192:193]
	v_pk_mul_f32 v[196:197], v[178:179], v[196:197]
	s_waitcnt lgkmcnt(0)
	v_mov_b32_e32 v205, v202
	v_mov_b32_e32 v202, v201
	v_mov_b32_e32 v204, v200
	v_pk_fma_f32 v[194:195], v[2:3], v[194:195], v[202:203]
	ds_read2_b64 v[200:203], v234 offset1:1
	v_pk_fma_f32 v[198:199], v[2:3], v[198:199], v[204:205]
	v_pk_mul_f32 v[194:195], v[172:173], v[194:195]
	v_pk_mul_f32 v[198:199], v[182:183], v[198:199]
	s_waitcnt lgkmcnt(0)
	v_mov_b32_e32 v205, v200
	v_mov_b32_e32 v200, v203
	v_mov_b32_e32 v204, v202
	v_pk_fma_f32 v[184:185], v[2:3], v[184:185], v[200:201]
	ds_read2_b64 v[200:203], v233 offset1:1
	v_pk_fma_f32 v[188:189], v[2:3], v[188:189], v[204:205]
	s_waitcnt lgkmcnt(0)
	s_barrier
	v_mov_b32_e32 v204, v200
	v_mov_b32_e32 v205, v202
	v_mov_b32_e32 v202, v201
	v_mov_b32_e32 v200, v197
	v_mov_b32_e32 v201, v193
	ds_write_b64 v0, v[200:201] offset:6272
	ds_write_b64 v232, v[240:241] offset:22656
	v_mov_b32_e32 v200, v196
	v_mov_b32_e32 v201, v192
	ds_write_b64 v0, v[200:201] offset:6280
	ds_write_b64 v232, v[240:241] offset:22664
	v_mov_b32_e32 v200, v198
	v_mov_b32_e32 v201, v194
	v_pk_mul_f32 v[188:189], v[158:159], v[188:189]
	v_pk_mul_f32 v[184:185], v[82:83], v[184:185]
	ds_write_b64 v0, v[200:201] offset:6288
	ds_write_b64 v232, v[240:241] offset:22672
	v_mov_b32_e32 v200, v199
	v_mov_b32_e32 v201, v195
	v_pk_fma_f32 v[190:191], v[2:3], v[190:191], v[204:205]
	v_pk_fma_f32 v[186:187], v[2:3], v[186:187], v[202:203]
	ds_write_b64 v0, v[200:201] offset:6296
	ds_write_b64 v232, v[240:241] offset:22680
	v_mov_b32_e32 v200, v189
	v_mov_b32_e32 v201, v185
	v_pk_mul_f32 v[190:191], v[160:161], v[190:191]
	v_pk_mul_f32 v[186:187], v[96:97], v[186:187]
	ds_write_b64 v0, v[200:201] offset:41088
	ds_write_b64 v232, v[240:241] offset:57472
	v_mov_b32_e32 v200, v188
	v_mov_b32_e32 v201, v184
	ds_write_b64 v0, v[200:201] offset:41096
	ds_write_b64 v232, v[240:241] offset:57480
	v_mov_b32_e32 v200, v190
	v_mov_b32_e32 v201, v186
	ds_write_b64 v0, v[200:201] offset:41104
	ds_write_b64 v232, v[240:241] offset:57488
	v_mov_b32_e32 v200, v191
	v_mov_b32_e32 v201, v187
	ds_write_b64 v0, v[200:201] offset:41112
	ds_write_b64 v232, v[240:241] offset:57496
	v_mov_b32_e32 v200, v180
	s_waitcnt lgkmcnt(0)
	s_barrier
	s_nop 0
	v_cmp_gt_i32_e32 vcc, s56, v200
	s_and_saveexec_b64 s[2:3], vcc
	s_cbranch_execz .LBB0_370
	v_ashrrev_i32_e32 v181, 31, v200
	v_add_u32_sdwa v181, v200, v181 dst_sel:DWORD dst_unused:UNUSED_PAD src0_sel:DWORD src1_sel:BYTE_3
	v_ashrrev_i32_e32 v181, 8, v181
	v_mul_i32_i24_e32 v201, 0x100, v181
	v_sub_u32_e32 v237, v200, v201
	v_mul_i32_i24_e32 v181, 0x1100, v181
	v_lshlrev_b32_e32 v181, 3, v181
	v_ashrrev_i32_e32 v201, 4, v237
	v_add_u32_e32 v200, 0, v181
	v_lshlrev_b32_e32 v248, 3, v237
	v_lshlrev_b32_e32 v201, 3, v201
	v_add3_u32 v230, v200, v248, v201
	ds_read_b64 v[200:201], v230 offset:6272
	ds_read_b64 v[202:203], v230 offset:8448
	ds_read_b64 v[204:205], v230 offset:10624
	ds_read_b64 v[206:207], v230 offset:12800
	ds_read_b64 v[208:209], v230 offset:14976
	ds_read_b64 v[210:211], v230 offset:17152
	ds_read_b64 v[212:213], v230 offset:19328
	ds_read_b64 v[214:215], v230 offset:21504
	ds_read_b64 v[216:217], v230 offset:23680
	ds_read_b64 v[218:219], v230 offset:25856
	ds_read_b64 v[220:221], v230 offset:28032
	ds_read_b64 v[222:223], v230 offset:30208
	ds_read_b64 v[224:225], v230 offset:32384
	ds_read_b64 v[226:227], v230 offset:34560
	ds_read_b64 v[228:229], v230 offset:36736
	ds_read_b64 v[230:231], v230 offset:38912
	s_waitcnt lgkmcnt(7)
	v_pk_add_f32 v[238:239], v[200:201], v[216:217]
	v_pk_add_f32 v[200:201], v[200:201], v[216:217] neg_lo:[0,1] neg_hi:[0,1]
	s_waitcnt lgkmcnt(3)
	v_pk_add_f32 v[216:217], v[208:209], v[224:225]
	v_pk_add_f32 v[208:209], v[208:209], v[224:225] neg_lo:[0,1] neg_hi:[0,1]
	s_mov_b32 s61, s34
	v_xor_b32_e32 v225, 0x80000000, v208
	v_mov_b32_e32 v224, v209
	v_pk_add_f32 v[242:243], v[200:201], v[224:225]
	v_pk_add_f32 v[200:201], v[200:201], v[224:225] neg_lo:[0,1] neg_hi:[0,1]
	v_pk_add_f32 v[224:225], v[202:203], v[218:219]
	v_pk_add_f32 v[202:203], v[202:203], v[218:219] neg_lo:[0,1] neg_hi:[0,1]
	s_waitcnt lgkmcnt(2)
	v_pk_add_f32 v[218:219], v[210:211], v[226:227]
	v_pk_add_f32 v[210:211], v[210:211], v[226:227] neg_lo:[0,1] neg_hi:[0,1]
	v_pk_add_f32 v[208:209], v[238:239], v[216:217]
	v_xor_b32_e32 v227, 0x80000000, v210
	v_mov_b32_e32 v226, v211
	v_pk_add_f32 v[210:211], v[224:225], v[218:219]
	v_pk_add_f32 v[218:219], v[224:225], v[218:219] neg_lo:[0,1] neg_hi:[0,1]
	v_pk_add_f32 v[224:225], v[204:205], v[220:221]
	v_pk_add_f32 v[204:205], v[204:205], v[220:221] neg_lo:[0,1] neg_hi:[0,1]
	s_waitcnt lgkmcnt(1)
	v_pk_add_f32 v[220:221], v[212:213], v[228:229]
	v_pk_add_f32 v[212:213], v[212:213], v[228:229] neg_lo:[0,1] neg_hi:[0,1]
	v_pk_add_f32 v[216:217], v[238:239], v[216:217] neg_lo:[0,1] neg_hi:[0,1]
	v_pk_add_f32 v[238:239], v[202:203], v[226:227]
	v_pk_add_f32 v[202:203], v[202:203], v[226:227] neg_lo:[0,1] neg_hi:[0,1]
	v_xor_b32_e32 v227, 0x80000000, v212
	v_mov_b32_e32 v226, v213
	v_pk_add_f32 v[212:213], v[224:225], v[220:221]
	v_pk_add_f32 v[220:221], v[224:225], v[220:221] neg_lo:[0,1] neg_hi:[0,1]
	v_pk_add_f32 v[224:225], v[206:207], v[222:223]
	v_pk_add_f32 v[206:207], v[206:207], v[222:223] neg_lo:[0,1] neg_hi:[0,1]
	s_waitcnt lgkmcnt(0)
	v_pk_add_f32 v[222:223], v[214:215], v[230:231]
	v_pk_add_f32 v[214:215], v[214:215], v[230:231] neg_lo:[0,1] neg_hi:[0,1]
	v_pk_add_f32 v[228:229], v[204:205], v[226:227]
	v_pk_add_f32 v[204:205], v[204:205], v[226:227] neg_lo:[0,1] neg_hi:[0,1]
	v_xor_b32_e32 v227, 0x80000000, v214
	v_mov_b32_e32 v226, v215
	v_pk_add_f32 v[214:215], v[224:225], v[222:223]
	v_pk_add_f32 v[222:223], v[224:225], v[222:223] neg_lo:[0,1] neg_hi:[0,1]
	v_pk_mul_f32 v[224:225], v[238:239], s[24:25] op_sel_hi:[1,0]
	v_pk_add_f32 v[230:231], v[206:207], v[226:227]
	v_pk_add_f32 v[206:207], v[206:207], v[226:227] neg_lo:[0,1] neg_hi:[0,1]
	v_pk_fma_f32 v[226:227], v[238:239], s[26:27], v[224:225] op_sel:[0,0,1] op_sel_hi:[1,0,0] neg_hi:[0,0,1]
	s_mov_b32 s35, s24
	v_pk_mul_f32 v[224:225], v[218:219], s[28:29] op_sel_hi:[1,0]
	v_add_u32_e32 v181, s57, v181
	v_pk_fma_f32 v[238:239], v[218:219], s[28:29], v[224:225] op_sel:[0,0,1] op_sel_hi:[1,0,0] neg_hi:[0,0,1]
	v_pk_mul_f32 v[224:225], v[202:203], s[26:27] op_sel_hi:[1,0]
	v_pk_fma_f32 v[244:245], v[202:203], s[24:25], v[224:225] op_sel:[0,0,1] op_sel_hi:[1,0,0] neg_hi:[0,0,1]
	s_nop 0
	v_pk_mul_f32 v[202:203], v[228:229], s[28:29] op_sel_hi:[1,0]
	s_nop 0
	v_pk_fma_f32 v[224:225], v[228:229], s[28:29], v[202:203] op_sel:[0,0,1] op_sel_hi:[1,0,0] neg_hi:[0,0,1]
	s_nop 0
	v_pk_fma_f32 v[202:203], v[220:221], 0, v[220:221] op_sel:[0,0,1] op_sel_hi:[1,0,0] neg_hi:[0,0,1]
	s_nop 0
	v_pk_mul_f32 v[220:221], v[204:205], s[30:31] op_sel_hi:[1,0]
	s_nop 0
	v_pk_fma_f32 v[228:229], v[204:205], s[30:31], v[220:221] op_sel:[0,0,1] op_sel_hi:[1,0,0] neg_lo:[0,0,1]
	v_pk_mul_f32 v[220:221], v[230:231], s[26:27] op_sel_hi:[1,0]
	v_pk_fma_f32 v[246:247], v[230:231], s[24:25], v[220:221] op_sel:[0,0,1] op_sel_hi:[1,0,0] neg_hi:[0,0,1]
	v_pk_add_f32 v[204:205], v[200:201], v[228:229]
	v_pk_mul_f32 v[220:221], v[222:223], s[30:31] op_sel_hi:[1,0]
	v_pk_add_f32 v[200:201], v[200:201], v[228:229] neg_lo:[0,1] neg_hi:[0,1]
	v_pk_fma_f32 v[230:231], v[222:223], s[30:31], v[220:221] op_sel:[0,0,1] op_sel_hi:[1,0,0] neg_lo:[0,0,1]
	s_nop 0
	v_pk_mul_f32 v[220:221], v[206:207], s[60:61] op_sel:[1,0]
	v_pk_add_f32 v[218:219], v[238:239], v[230:231] neg_lo:[0,1] neg_hi:[0,1]
	v_pk_fma_f32 v[206:207], v[206:207], s[34:35], v[220:221] op_sel_hi:[0,1,1]
	v_pk_add_f32 v[220:221], v[208:209], v[212:213]
	v_pk_add_f32 v[208:209], v[208:209], v[212:213] neg_lo:[0,1] neg_hi:[0,1]
	v_pk_add_f32 v[212:213], v[210:211], v[214:215]
	v_pk_add_f32 v[210:211], v[210:211], v[214:215] neg_lo:[0,1] neg_hi:[0,1]
	s_nop 0
	v_xor_b32_e32 v215, 0x80000000, v210
	v_mov_b32_e32 v214, v211
	v_pk_add_f32 v[210:211], v[220:221], v[212:213]
	v_pk_add_f32 v[222:223], v[208:209], v[214:215]
	v_pk_add_f32 v[212:213], v[220:221], v[212:213] neg_lo:[0,1] neg_hi:[0,1]
	v_pk_add_f32 v[208:209], v[208:209], v[214:215] neg_lo:[0,1] neg_hi:[0,1]
	v_pk_add_f32 v[214:215], v[242:243], v[224:225]
	v_pk_add_f32 v[220:221], v[242:243], v[224:225] neg_lo:[0,1] neg_hi:[0,1]
	v_pk_add_f32 v[224:225], v[226:227], v[246:247]
	v_pk_add_f32 v[226:227], v[226:227], v[246:247] neg_lo:[0,1] neg_hi:[0,1]
	s_nop 0
	v_xor_b32_e32 v243, 0x80000000, v226
	v_mov_b32_e32 v242, v227
	v_pk_add_f32 v[226:227], v[214:215], v[224:225]
	v_pk_add_f32 v[214:215], v[214:215], v[224:225] neg_lo:[0,1] neg_hi:[0,1]
	v_pk_add_f32 v[224:225], v[216:217], v[202:203]
	v_pk_add_f32 v[202:203], v[216:217], v[202:203] neg_lo:[0,1] neg_hi:[0,1]
	v_pk_add_f32 v[216:217], v[238:239], v[230:231]
	v_xor_b32_e32 v231, 0x80000000, v218
	v_mov_b32_e32 v230, v219
	v_pk_add_f32 v[218:219], v[224:225], v[216:217]
	v_pk_add_f32 v[216:217], v[224:225], v[216:217] neg_lo:[0,1] neg_hi:[0,1]
	v_pk_add_f32 v[224:225], v[244:245], v[206:207]
	v_pk_add_f32 v[206:207], v[244:245], v[206:207] neg_lo:[0,1] neg_hi:[0,1]
	v_pk_add_f32 v[246:247], v[220:221], v[242:243]
	v_xor_b32_e32 v229, 0x80000000, v206
	v_mov_b32_e32 v228, v207
	v_pk_add_f32 v[206:207], v[204:205], v[224:225]
	v_pk_add_f32 v[204:205], v[204:205], v[224:225] neg_lo:[0,1] neg_hi:[0,1]
	v_lshlrev_b32_e32 v224, 7, v237
	v_add3_u32 v181, v181, v224, v248
	v_pk_add_f32 v[220:221], v[220:221], v[242:243] neg_lo:[0,1] neg_hi:[0,1]
	v_pk_add_f32 v[238:239], v[202:203], v[230:231]
	v_pk_add_f32 v[202:203], v[202:203], v[230:231] neg_lo:[0,1] neg_hi:[0,1]
	v_pk_add_f32 v[230:231], v[200:201], v[228:229]
	v_pk_add_f32 v[200:201], v[200:201], v[228:229] neg_lo:[0,1] neg_hi:[0,1]
	ds_write2_b64 v181, v[210:211], v[226:227] offset1:1
	ds_write2_b64 v181, v[218:219], v[206:207] offset0:2 offset1:3
	ds_write2_b64 v181, v[222:223], v[246:247] offset0:4 offset1:5
	ds_write2_b64 v181, v[238:239], v[230:231] offset0:6 offset1:7
	ds_write2_b64 v181, v[212:213], v[214:215] offset0:8 offset1:9
	ds_write2_b64 v181, v[216:217], v[204:205] offset0:10 offset1:11
	ds_write2_b64 v181, v[208:209], v[220:221] offset0:12 offset1:13
	ds_write2_b64 v181, v[202:203], v[200:201] offset0:14 offset1:15
.LBB0_370:
	s_or_b64 exec, exec, s[2:3]
	v_mov_b32_e32 v200, v180
	s_waitcnt lgkmcnt(0)
	s_barrier
	s_nop 0
	v_cmp_gt_i32_e32 vcc, s56, v200
	s_and_saveexec_b64 s[2:3], vcc
	s_cbranch_execz .LBB0_372
	v_ashrrev_i32_e32 v181, 31, v200
	v_add_u32_sdwa v181, v200, v181 dst_sel:DWORD dst_unused:UNUSED_PAD src0_sel:DWORD src1_sel:BYTE_3
	v_ashrrev_i32_e32 v181, 8, v181
	v_mul_i32_i24_e32 v201, 0x100, v181
	v_sub_u32_e32 v200, v200, v201
	v_ashrrev_i16_e32 v201, 15, v200
	v_lshrrev_b16_e32 v201, 12, v201
	v_add_u16_e32 v201, v200, v201
	v_ashrrev_i16_e32 v237, 4, v201
	v_and_b32_e32 v201, -16, v201
	v_mul_i32_i24_e32 v181, 0x1100, v181
	v_sub_u16_e32 v204, v200, v201
	v_lshlrev_b32_e32 v238, 3, v181
	v_lshlrev_b32_e32 v201, 3, v200
	v_ashrrev_i32_e32 v200, 4, v200
	v_add_u32_e32 v181, s57, v238
	v_lshlrev_b32_e32 v200, 3, v200
	v_add3_u32 v181, v181, v201, v200
	v_bfe_i32 v239, v204, 0, 16
	ds_read_b64 v[200:201], v181
	ds_read_b64 v[202:203], v181 offset:2176
	ds_read_b64 v[214:215], v181 offset:4352
	ds_read_b64 v[216:217], v181 offset:6528
	ds_read_b64 v[218:219], v181 offset:8704
	ds_read_b64 v[222:223], v181 offset:10880
	ds_read_b64 v[224:225], v181 offset:13056
	ds_read_b64 v[226:227], v181 offset:15232
	ds_read_b64 v[228:229], v181 offset:17408
	ds_read_b64 v[230:231], v181 offset:19584
	ds_read_b64 v[242:243], v181 offset:21760
	ds_read_b64 v[244:245], v181 offset:23936
	ds_read_b64 v[246:247], v181 offset:26112
	ds_read_b64 v[248:249], v181 offset:28288
	ds_read_b64 v[250:251], v181 offset:30464
	ds_read_b64 v[206:207], v181 offset:32640
	v_mad_i32_i24 v181, v239, s27, 0
	v_add_u32_e32 v204, 0x808, v181
	ds_read2_b64 v[210:213], v204 offset1:1
	s_mov_b32 s61, s34
	s_mov_b32 s35, s24
	s_waitcnt lgkmcnt(0)
	v_pk_mul_f32 v[204:205], v[202:203], v[210:211] op_sel:[1,1] op_sel_hi:[1,0]
	s_nop 0
	v_pk_fma_f32 v[208:209], v[202:203], v[210:211], v[204:205] op_sel_hi:[0,1,1] neg_lo:[0,0,1]
	v_pk_mul_f32 v[202:203], v[214:215], v[212:213] op_sel:[1,1] op_sel_hi:[1,0]
	s_nop 0
	v_pk_fma_f32 v[204:205], v[214:215], v[212:213], v[202:203] neg_lo:[0,0,1] neg_hi:[0,0,1]
	v_pk_fma_f32 v[202:203], v[214:215], v[212:213], v[202:203] op_sel_hi:[0,1,1]
	v_add_u32_e32 v202, 0x818, v181
	ds_read2_b64 v[210:213], v202 offset1:1
	v_mov_b32_e32 v205, v203
	s_waitcnt lgkmcnt(0)
	v_pk_mul_f32 v[214:215], v[216:217], v[210:211] op_sel:[1,1] op_sel_hi:[1,0]
	s_nop 0
	v_pk_fma_f32 v[202:203], v[216:217], v[210:211], v[214:215] op_sel_hi:[0,1,1] neg_lo:[0,0,1]
	v_pk_mul_f32 v[210:211], v[218:219], v[212:213] op_sel:[1,1] op_sel_hi:[1,0]
	s_nop 0
	v_pk_fma_f32 v[216:217], v[218:219], v[212:213], v[210:211] neg_lo:[0,0,1] neg_hi:[0,0,1]
	v_pk_fma_f32 v[210:211], v[218:219], v[212:213], v[210:211] op_sel_hi:[0,1,1]
	v_add_u32_e32 v210, 0x828, v181
	ds_read2_b64 v[218:221], v210 offset1:1
	v_mov_b32_e32 v217, v211
	s_waitcnt lgkmcnt(0)
	v_pk_mul_f32 v[210:211], v[222:223], v[218:219] op_sel:[1,1] op_sel_hi:[1,0]
	s_nop 0
	v_pk_fma_f32 v[214:215], v[222:223], v[218:219], v[210:211] op_sel_hi:[0,1,1] neg_lo:[0,0,1]
	v_pk_mul_f32 v[210:211], v[224:225], v[220:221] op_sel:[1,1] op_sel_hi:[1,0]
	s_nop 0
	v_pk_fma_f32 v[212:213], v[224:225], v[220:221], v[210:211] neg_lo:[0,0,1] neg_hi:[0,0,1]
	v_pk_fma_f32 v[210:211], v[224:225], v[220:221], v[210:211] op_sel_hi:[0,1,1]
	v_add_u32_e32 v210, 0x838, v181
	ds_read2_b64 v[218:221], v210 offset1:1
	v_mov_b32_e32 v213, v211
	s_waitcnt lgkmcnt(0)
	v_pk_mul_f32 v[222:223], v[226:227], v[218:219] op_sel:[1,1] op_sel_hi:[1,0]
	s_nop 0
	v_pk_fma_f32 v[210:211], v[226:227], v[218:219], v[222:223] op_sel_hi:[0,1,1] neg_lo:[0,0,1]
	v_pk_mul_f32 v[218:219], v[228:229], v[220:221] op_sel:[1,1] op_sel_hi:[1,0]
	s_nop 0
	v_pk_fma_f32 v[224:225], v[228:229], v[220:221], v[218:219] neg_lo:[0,0,1] neg_hi:[0,0,1]
	v_pk_fma_f32 v[218:219], v[228:229], v[220:221], v[218:219] op_sel_hi:[0,1,1]
	v_add_u32_e32 v218, 0x848, v181
	ds_read2_b64 v[226:229], v218 offset1:1
	v_mov_b32_e32 v225, v219
	s_waitcnt lgkmcnt(0)
	v_pk_mul_f32 v[218:219], v[230:231], v[226:227] op_sel:[1,1] op_sel_hi:[1,0]
	s_nop 0
	v_pk_fma_f32 v[222:223], v[230:231], v[226:227], v[218:219] op_sel_hi:[0,1,1] neg_lo:[0,0,1]
	v_pk_mul_f32 v[218:219], v[242:243], v[228:229] op_sel:[1,1] op_sel_hi:[1,0]
	s_nop 0
	v_pk_fma_f32 v[220:221], v[242:243], v[228:229], v[218:219] neg_lo:[0,0,1] neg_hi:[0,0,1]
	v_pk_fma_f32 v[218:219], v[242:243], v[228:229], v[218:219] op_sel_hi:[0,1,1]
	v_add_u32_e32 v218, 0x858, v181
	ds_read2_b64 v[226:229], v218 offset1:1
	v_mov_b32_e32 v221, v219
	s_waitcnt lgkmcnt(0)
	v_pk_mul_f32 v[230:231], v[244:245], v[226:227] op_sel:[1,1] op_sel_hi:[1,0]
	s_nop 0
	v_pk_fma_f32 v[218:219], v[244:245], v[226:227], v[230:231] op_sel_hi:[0,1,1] neg_lo:[0,0,1]
	v_pk_mul_f32 v[226:227], v[246:247], v[228:229] op_sel:[1,1] op_sel_hi:[1,0]
	s_nop 0
	v_pk_fma_f32 v[230:231], v[246:247], v[228:229], v[226:227] neg_lo:[0,0,1] neg_hi:[0,0,1]
	v_pk_fma_f32 v[226:227], v[246:247], v[228:229], v[226:227] op_sel_hi:[0,1,1]
	v_add_u32_e32 v226, 0x868, v181
	ds_read2_b64 v[242:245], v226 offset1:1
	v_mov_b32_e32 v231, v227
	s_waitcnt lgkmcnt(0)
	v_pk_mul_f32 v[226:227], v[248:249], v[242:243] op_sel:[1,1] op_sel_hi:[1,0]
	s_nop 0
	v_pk_fma_f32 v[228:229], v[248:249], v[242:243], v[226:227] op_sel_hi:[0,1,1] neg_lo:[0,0,1]
	v_pk_mul_f32 v[242:243], v[250:251], v[244:245] op_sel:[1,1] op_sel_hi:[1,0]
	v_pk_fma_f32 v[226:227], v[250:251], v[244:245], v[242:243] op_sel_hi:[0,1,1] neg_lo:[0,0,1]
	ds_read_b64 v[242:243], v181 offset:2168
	v_bfe_i32 v181, v237, 0, 16
	v_lshl_add_u32 v181, v181, 8, v239
	s_waitcnt lgkmcnt(0)
	v_pk_mul_f32 v[244:245], v[206:207], v[242:243] op_sel:[1,1] op_sel_hi:[1,0]
	s_nop 0
	v_pk_fma_f32 v[246:247], v[206:207], v[242:243], v[244:245] op_sel_hi:[0,1,1] neg_lo:[0,0,1]
	v_pk_add_f32 v[206:207], v[200:201], v[224:225]
	v_pk_add_f32 v[200:201], v[200:201], v[224:225] neg_lo:[0,1] neg_hi:[0,1]
	v_pk_add_f32 v[224:225], v[216:217], v[230:231]
	v_pk_add_f32 v[216:217], v[216:217], v[230:231] neg_lo:[0,1] neg_hi:[0,1]
	s_nop 0
	v_xor_b32_e32 v231, 0x80000000, v216
	v_mov_b32_e32 v230, v217
	v_pk_add_f32 v[216:217], v[206:207], v[224:225]
	v_pk_add_f32 v[206:207], v[206:207], v[224:225] neg_lo:[0,1] neg_hi:[0,1]
	v_pk_add_f32 v[224:225], v[208:209], v[222:223]
	v_pk_add_f32 v[208:209], v[208:209], v[222:223] neg_lo:[0,1] neg_hi:[0,1]
	v_pk_add_f32 v[222:223], v[214:215], v[228:229]
	v_pk_add_f32 v[214:215], v[214:215], v[228:229] neg_lo:[0,1] neg_hi:[0,1]
	v_pk_add_f32 v[242:243], v[200:201], v[230:231]
	v_xor_b32_e32 v229, 0x80000000, v214
	v_mov_b32_e32 v228, v215
	v_pk_add_f32 v[214:215], v[224:225], v[222:223]
	v_pk_add_f32 v[222:223], v[224:225], v[222:223] neg_lo:[0,1] neg_hi:[0,1]
	v_pk_add_f32 v[224:225], v[204:205], v[220:221]
	v_pk_add_f32 v[204:205], v[204:205], v[220:221] neg_lo:[0,1] neg_hi:[0,1]
	v_pk_add_f32 v[220:221], v[212:213], v[226:227]
	v_pk_add_f32 v[212:213], v[212:213], v[226:227] neg_lo:[0,1] neg_hi:[0,1]
	v_pk_add_f32 v[200:201], v[200:201], v[230:231] neg_lo:[0,1] neg_hi:[0,1]
	v_pk_add_f32 v[230:231], v[208:209], v[228:229]
	v_xor_b32_e32 v227, 0x80000000, v212
	v_mov_b32_e32 v226, v213
	v_pk_add_f32 v[212:213], v[224:225], v[220:221]
	v_pk_add_f32 v[220:221], v[224:225], v[220:221] neg_lo:[0,1] neg_hi:[0,1]
	v_pk_add_f32 v[224:225], v[202:203], v[218:219]
	v_pk_add_f32 v[202:203], v[202:203], v[218:219] neg_lo:[0,1] neg_hi:[0,1]
	v_pk_add_f32 v[218:219], v[210:211], v[246:247]
	v_pk_add_f32 v[210:211], v[210:211], v[246:247] neg_lo:[0,1] neg_hi:[0,1]
	v_pk_add_f32 v[208:209], v[208:209], v[228:229] neg_lo:[0,1] neg_hi:[0,1]
	v_pk_add_f32 v[228:229], v[204:205], v[226:227]
	v_pk_add_f32 v[204:205], v[204:205], v[226:227] neg_lo:[0,1] neg_hi:[0,1]
	v_xor_b32_e32 v227, 0x80000000, v210
	v_mov_b32_e32 v226, v211
	v_pk_add_f32 v[210:211], v[224:225], v[218:219]
	v_pk_add_f32 v[218:219], v[224:225], v[218:219] neg_lo:[0,1] neg_hi:[0,1]
	v_pk_mul_f32 v[224:225], v[230:231], s[24:25] op_sel_hi:[1,0]
	v_pk_add_f32 v[244:245], v[202:203], v[226:227]
	v_pk_add_f32 v[202:203], v[202:203], v[226:227] neg_lo:[0,1] neg_hi:[0,1]
	v_pk_fma_f32 v[226:227], v[230:231], s[26:27], v[224:225] op_sel:[0,0,1] op_sel_hi:[1,0,0] neg_hi:[0,0,1]
	s_nop 0
	v_pk_mul_f32 v[224:225], v[222:223], s[28:29] op_sel_hi:[1,0]
	s_nop 0
	v_pk_fma_f32 v[230:231], v[222:223], s[28:29], v[224:225] op_sel:[0,0,1] op_sel_hi:[1,0,0] neg_hi:[0,0,1]
	v_pk_mul_f32 v[224:225], v[208:209], s[26:27] op_sel_hi:[1,0]
	v_pk_fma_f32 v[246:247], v[208:209], s[24:25], v[224:225] op_sel:[0,0,1] op_sel_hi:[1,0,0] neg_hi:[0,0,1]
	s_nop 0
	v_pk_mul_f32 v[208:209], v[228:229], s[28:29] op_sel_hi:[1,0]
	s_nop 0
	v_pk_fma_f32 v[224:225], v[228:229], s[28:29], v[208:209] op_sel:[0,0,1] op_sel_hi:[1,0,0] neg_hi:[0,0,1]
	s_nop 0
	v_pk_fma_f32 v[208:209], v[220:221], 0, v[220:221] op_sel:[0,0,1] op_sel_hi:[1,0,0] neg_hi:[0,0,1]
	s_nop 0
	v_pk_mul_f32 v[220:221], v[204:205], s[30:31] op_sel_hi:[1,0]
	s_nop 0
	v_pk_fma_f32 v[228:229], v[204:205], s[30:31], v[220:221] op_sel:[0,0,1] op_sel_hi:[1,0,0] neg_lo:[0,0,1]
	v_pk_mul_f32 v[220:221], v[244:245], s[26:27] op_sel_hi:[1,0]
	v_pk_fma_f32 v[248:249], v[244:245], s[24:25], v[220:221] op_sel:[0,0,1] op_sel_hi:[1,0,0] neg_hi:[0,0,1]
	v_pk_add_f32 v[204:205], v[200:201], v[228:229]
	v_pk_mul_f32 v[220:221], v[218:219], s[30:31] op_sel_hi:[1,0]
	v_pk_add_f32 v[200:201], v[200:201], v[228:229] neg_lo:[0,1] neg_hi:[0,1]
	v_pk_fma_f32 v[244:245], v[218:219], s[30:31], v[220:221] op_sel:[0,0,1] op_sel_hi:[1,0,0] neg_lo:[0,0,1]
	s_nop 0
	v_pk_mul_f32 v[218:219], v[202:203], s[60:61] op_sel:[1,0]
	v_pk_add_f32 v[222:223], v[230:231], v[244:245] neg_lo:[0,1] neg_hi:[0,1]
	v_pk_fma_f32 v[202:203], v[202:203], s[34:35], v[218:219] op_sel_hi:[0,1,1]
	v_pk_add_f32 v[218:219], v[216:217], v[212:213]
	v_pk_add_f32 v[212:213], v[216:217], v[212:213] neg_lo:[0,1] neg_hi:[0,1]
	v_pk_add_f32 v[216:217], v[214:215], v[210:211]
	v_pk_add_f32 v[210:211], v[214:215], v[210:211] neg_lo:[0,1] neg_hi:[0,1]
	s_nop 0
	v_xor_b32_e32 v215, 0x80000000, v210
	v_mov_b32_e32 v214, v211
	v_pk_add_f32 v[210:211], v[218:219], v[216:217]
	v_pk_add_f32 v[220:221], v[212:213], v[214:215]
	v_pk_add_f32 v[216:217], v[218:219], v[216:217] neg_lo:[0,1] neg_hi:[0,1]
	v_pk_add_f32 v[212:213], v[212:213], v[214:215] neg_lo:[0,1] neg_hi:[0,1]
	v_pk_add_f32 v[214:215], v[242:243], v[224:225]
	v_pk_add_f32 v[218:219], v[242:243], v[224:225] neg_lo:[0,1] neg_hi:[0,1]
	v_pk_add_f32 v[224:225], v[226:227], v[248:249]
	v_pk_add_f32 v[226:227], v[226:227], v[248:249] neg_lo:[0,1] neg_hi:[0,1]
	s_nop 0
	v_xor_b32_e32 v243, 0x80000000, v226
	v_mov_b32_e32 v242, v227
	v_pk_add_f32 v[226:227], v[214:215], v[224:225]
	v_pk_add_f32 v[214:215], v[214:215], v[224:225] neg_lo:[0,1] neg_hi:[0,1]
	v_pk_add_f32 v[224:225], v[206:207], v[208:209]
	v_pk_add_f32 v[206:207], v[206:207], v[208:209] neg_lo:[0,1] neg_hi:[0,1]
	v_pk_add_f32 v[208:209], v[230:231], v[244:245]
	v_xor_b32_e32 v231, 0x80000000, v222
	v_mov_b32_e32 v230, v223
	v_pk_add_f32 v[222:223], v[224:225], v[208:209]
	v_pk_add_f32 v[208:209], v[224:225], v[208:209] neg_lo:[0,1] neg_hi:[0,1]
	v_pk_add_f32 v[224:225], v[246:247], v[202:203]
	v_pk_add_f32 v[202:203], v[246:247], v[202:203] neg_lo:[0,1] neg_hi:[0,1]
	v_pk_add_f32 v[248:249], v[218:219], v[242:243]
	v_xor_b32_e32 v229, 0x80000000, v202
	v_mov_b32_e32 v228, v203
	v_pk_add_f32 v[202:203], v[204:205], v[224:225]
	v_pk_add_f32 v[204:205], v[204:205], v[224:225] neg_lo:[0,1] neg_hi:[0,1]
	v_lshlrev_b32_e32 v225, 3, v181
	v_ashrrev_i32_e32 v181, 4, v181
	v_add_u32_e32 v224, 0, v238
	v_lshlrev_b32_e32 v181, 3, v181
	v_add3_u32 v181, v224, v225, v181
	v_pk_add_f32 v[218:219], v[218:219], v[242:243] neg_lo:[0,1] neg_hi:[0,1]
	v_pk_add_f32 v[242:243], v[206:207], v[230:231]
	v_pk_add_f32 v[206:207], v[206:207], v[230:231] neg_lo:[0,1] neg_hi:[0,1]
	v_pk_add_f32 v[230:231], v[200:201], v[228:229]
	v_pk_add_f32 v[200:201], v[200:201], v[228:229] neg_lo:[0,1] neg_hi:[0,1]
	v_add_u32_e32 v224, 0x1800, v181
	v_add_u32_e32 v181, 0x1c00, v181
	ds_write2_b64 v224, v[210:211], v[226:227] offset0:16 offset1:33
	ds_write2_b64 v224, v[222:223], v[202:203] offset0:50 offset1:67
	ds_write2_b64 v224, v[220:221], v[248:249] offset0:84 offset1:101
	ds_write2_b64 v224, v[242:243], v[230:231] offset0:118 offset1:135
	ds_write2_b64 v224, v[216:217], v[214:215] offset0:152 offset1:169
	ds_write2_b64 v224, v[208:209], v[204:205] offset0:186 offset1:203
	ds_write2_b64 v224, v[212:213], v[218:219] offset0:220 offset1:237
	ds_write2_b64 v181, v[206:207], v[200:201] offset0:126 offset1:143
.LBB0_372:
	s_or_b64 exec, exec, s[2:3]
	v_mov_b32_e32 v200, v180
	s_waitcnt lgkmcnt(0)
	s_barrier
	s_nop 0
	v_cmp_gt_i32_e32 vcc, s56, v200
	s_and_saveexec_b64 s[2:3], vcc
	s_cbranch_execz .LBB0_374
	v_ashrrev_i32_e32 v181, 31, v200
	v_add_u32_sdwa v181, v200, v181 dst_sel:DWORD dst_unused:UNUSED_PAD src0_sel:DWORD src1_sel:BYTE_3
	v_ashrrev_i32_e32 v181, 8, v181
	v_mul_i32_i24_e32 v201, 0x100, v181
	v_sub_u32_e32 v200, v200, v201
	v_mul_i32_i24_e32 v181, 0x1100, v181
	v_lshlrev_b32_e32 v237, 3, v200
	v_ashrrev_i32_e32 v200, 4, v200
	v_lshlrev_b32_e32 v181, 3, v181
	v_lshlrev_b32_e32 v252, 3, v200
	v_add_u32_e32 v222, 0, v237
	v_add3_u32 v238, v222, v181, v252
	ds_read_b64 v[200:201], v238 offset:6272
	ds_read_b64 v[202:203], v238 offset:8448
	ds_read_b64 v[204:205], v238 offset:10624
	ds_read_b64 v[206:207], v238 offset:12800
	ds_read_b64 v[208:209], v238 offset:14976
	ds_read_b64 v[210:211], v238 offset:17152
	ds_read_b64 v[212:213], v238 offset:19328
	ds_read_b64 v[214:215], v238 offset:21504
	ds_read_b64 v[216:217], v238 offset:34560
	ds_read_b64 v[218:219], v238 offset:36736
	ds_read_b64 v[220:221], v238 offset:38912
	ds_read_b64 v[222:223], v222
	ds_read_b64 v[224:225], v238 offset:23680
	ds_read_b64 v[226:227], v238 offset:25856
	ds_read_b64 v[228:229], v238 offset:28032
	ds_read_b64 v[230:231], v238 offset:30208
	ds_read_b64 v[238:239], v238 offset:32384
	s_waitcnt lgkmcnt(5)
	v_pk_mul_f32 v[242:243], v[202:203], v[222:223] op_sel:[1,1] op_sel_hi:[1,0]
	s_mov_b32 s61, s34
	v_pk_fma_f32 v[244:245], v[202:203], v[222:223], v[242:243] op_sel_hi:[0,1,1] neg_lo:[0,0,1]
	v_pk_mul_f32 v[202:203], v[222:223], v[222:223] op_sel:[1,1] op_sel_hi:[1,0]
	s_mov_b32 s35, s24
	v_pk_fma_f32 v[242:243], v[222:223], v[222:223], v[202:203] op_sel_hi:[1,0,1] neg_lo:[0,0,1] neg_hi:[0,0,1]
	v_pk_fma_f32 v[202:203], v[222:223], v[222:223], v[202:203] op_sel_hi:[1,0,1]
	v_mov_b32_e32 v246, v242
	v_mov_b32_e32 v247, v203
	v_pk_mul_f32 v[202:203], v[204:205], v[202:203] op_sel:[1,1] op_sel_hi:[0,1]
	v_pk_fma_f32 v[248:249], v[204:205], v[242:243], v[202:203] op_sel_hi:[1,0,1] neg_lo:[0,0,1]
	v_pk_mul_f32 v[204:205], v[222:223], v[246:247] op_sel:[1,0] op_sel_hi:[0,1]
	v_pk_mul_f32 v[202:203], v[222:223], v[246:247]
	v_pk_add_f32 v[204:205], v[204:205], v[204:205] op_sel:[0,1] op_sel_hi:[0,1]
	v_pk_mul_f32 v[242:243], v[206:207], v[204:205]
	v_pk_add_f32 v[202:203], v[202:203], v[202:203] op_sel:[0,1] op_sel_hi:[0,1] neg_lo:[0,1] neg_hi:[0,1]
	v_pk_fma_f32 v[246:247], v[206:207], v[202:203], v[242:243] op_sel:[0,0,1] op_sel_hi:[1,1,0] neg_lo:[0,0,1]
	v_pk_mul_f32 v[204:205], v[222:223], v[204:205]
	v_pk_fma_f32 v[206:207], v[222:223], v[202:203], v[204:205] op_sel:[0,0,1] op_sel_hi:[1,1,0] neg_lo:[0,0,1] neg_hi:[0,0,1]
	v_pk_fma_f32 v[202:203], v[222:223], v[202:203], v[204:205] op_sel:[0,0,1] op_sel_hi:[1,1,0]
	v_mov_b32_e32 v204, v206
	v_mov_b32_e32 v205, v203
	v_pk_mul_f32 v[202:203], v[208:209], v[202:203] op_sel:[1,1] op_sel_hi:[0,1]
	v_pk_fma_f32 v[242:243], v[208:209], v[206:207], v[202:203] op_sel_hi:[1,0,1] neg_lo:[0,0,1]
	v_add_u32_e32 v181, s57, v181
	v_pk_mul_f32 v[202:203], v[222:223], v[204:205]
	v_pk_mul_f32 v[204:205], v[222:223], v[204:205] op_sel:[1,0] op_sel_hi:[0,1]
	v_pk_add_f32 v[204:205], v[204:205], v[204:205] op_sel:[0,1] op_sel_hi:[0,1]
	v_pk_mul_f32 v[206:207], v[210:211], v[204:205]
	v_pk_add_f32 v[202:203], v[202:203], v[202:203] op_sel:[0,1] op_sel_hi:[0,1] neg_lo:[0,1] neg_hi:[0,1]
	v_pk_fma_f32 v[208:209], v[210:211], v[202:203], v[206:207] op_sel:[0,0,1] op_sel_hi:[1,1,0] neg_lo:[0,0,1]
	v_pk_mul_f32 v[204:205], v[222:223], v[204:205]
	v_pk_fma_f32 v[206:207], v[222:223], v[202:203], v[204:205] op_sel:[0,0,1] op_sel_hi:[1,1,0] neg_lo:[0,0,1] neg_hi:[0,0,1]
	v_pk_fma_f32 v[202:203], v[222:223], v[202:203], v[204:205] op_sel:[0,0,1] op_sel_hi:[1,1,0]
	v_mov_b32_e32 v204, v206
	v_mov_b32_e32 v205, v203
	v_pk_mul_f32 v[202:203], v[212:213], v[202:203] op_sel:[1,1] op_sel_hi:[0,1]
	v_pk_fma_f32 v[210:211], v[212:213], v[206:207], v[202:203] op_sel_hi:[1,0,1] neg_lo:[0,0,1]
	v_add3_u32 v181, v181, v237, v252
	v_pk_mul_f32 v[202:203], v[222:223], v[204:205]
	v_pk_mul_f32 v[204:205], v[222:223], v[204:205] op_sel:[1,0] op_sel_hi:[0,1]
	v_pk_add_f32 v[204:205], v[204:205], v[204:205] op_sel:[0,1] op_sel_hi:[0,1]
	v_pk_mul_f32 v[206:207], v[214:215], v[204:205]
	v_pk_add_f32 v[202:203], v[202:203], v[202:203] op_sel:[0,1] op_sel_hi:[0,1] neg_lo:[0,1] neg_hi:[0,1]
	v_pk_fma_f32 v[212:213], v[214:215], v[202:203], v[206:207] op_sel:[0,0,1] op_sel_hi:[1,1,0] neg_lo:[0,0,1]
	v_pk_mul_f32 v[204:205], v[222:223], v[204:205]
	v_pk_fma_f32 v[206:207], v[222:223], v[202:203], v[204:205] op_sel:[0,0,1] op_sel_hi:[1,1,0] neg_lo:[0,0,1] neg_hi:[0,0,1]
	v_pk_fma_f32 v[202:203], v[222:223], v[202:203], v[204:205] op_sel:[0,0,1] op_sel_hi:[1,1,0]
	v_mov_b32_e32 v204, v206
	v_mov_b32_e32 v205, v203
	s_waitcnt lgkmcnt(4)
	v_pk_mul_f32 v[202:203], v[224:225], v[202:203] op_sel:[1,1] op_sel_hi:[0,1]
	v_pk_fma_f32 v[214:215], v[224:225], v[206:207], v[202:203] op_sel_hi:[1,0,1] neg_lo:[0,0,1]
	s_nop 0
	v_pk_mul_f32 v[202:203], v[222:223], v[204:205]
	v_pk_mul_f32 v[204:205], v[222:223], v[204:205] op_sel:[1,0] op_sel_hi:[0,1]
	v_pk_add_f32 v[204:205], v[204:205], v[204:205] op_sel:[0,1] op_sel_hi:[0,1]
	s_waitcnt lgkmcnt(3)
	v_pk_mul_f32 v[206:207], v[226:227], v[204:205]
	v_pk_add_f32 v[202:203], v[202:203], v[202:203] op_sel:[0,1] op_sel_hi:[0,1] neg_lo:[0,1] neg_hi:[0,1]
	v_pk_fma_f32 v[224:225], v[226:227], v[202:203], v[206:207] op_sel:[0,0,1] op_sel_hi:[1,1,0] neg_lo:[0,0,1]
	v_pk_mul_f32 v[204:205], v[222:223], v[204:205]
	v_pk_fma_f32 v[206:207], v[222:223], v[202:203], v[204:205] op_sel:[0,0,1] op_sel_hi:[1,1,0] neg_lo:[0,0,1] neg_hi:[0,0,1]
	v_pk_fma_f32 v[202:203], v[222:223], v[202:203], v[204:205] op_sel:[0,0,1] op_sel_hi:[1,1,0]
	v_mov_b32_e32 v204, v206
	v_mov_b32_e32 v205, v203
	s_waitcnt lgkmcnt(2)
	v_pk_mul_f32 v[202:203], v[228:229], v[202:203] op_sel:[1,1] op_sel_hi:[0,1]
	v_pk_fma_f32 v[226:227], v[228:229], v[206:207], v[202:203] op_sel_hi:[1,0,1] neg_lo:[0,0,1]
	s_nop 0
	v_pk_mul_f32 v[202:203], v[222:223], v[204:205]
	v_pk_mul_f32 v[204:205], v[222:223], v[204:205] op_sel:[1,0] op_sel_hi:[0,1]
	v_pk_add_f32 v[204:205], v[204:205], v[204:205] op_sel:[0,1] op_sel_hi:[0,1]
	s_waitcnt lgkmcnt(1)
	v_pk_mul_f32 v[206:207], v[230:231], v[204:205]
	v_pk_add_f32 v[202:203], v[202:203], v[202:203] op_sel:[0,1] op_sel_hi:[0,1] neg_lo:[0,1] neg_hi:[0,1]
	v_pk_fma_f32 v[228:229], v[230:231], v[202:203], v[206:207] op_sel:[0,0,1] op_sel_hi:[1,1,0] neg_lo:[0,0,1]
	v_pk_mul_f32 v[204:205], v[222:223], v[204:205]
	v_pk_fma_f32 v[206:207], v[222:223], v[202:203], v[204:205] op_sel:[0,0,1] op_sel_hi:[1,1,0] neg_lo:[0,0,1] neg_hi:[0,0,1]
	v_pk_fma_f32 v[202:203], v[222:223], v[202:203], v[204:205] op_sel:[0,0,1] op_sel_hi:[1,1,0]
	v_mov_b32_e32 v204, v206
	v_mov_b32_e32 v205, v203
	s_waitcnt lgkmcnt(0)
	v_pk_mul_f32 v[202:203], v[238:239], v[202:203] op_sel:[1,1] op_sel_hi:[0,1]
	v_pk_fma_f32 v[230:231], v[238:239], v[206:207], v[202:203] op_sel_hi:[1,0,1] neg_lo:[0,0,1]
	s_nop 0
	v_pk_mul_f32 v[202:203], v[222:223], v[204:205]
	v_pk_mul_f32 v[204:205], v[222:223], v[204:205] op_sel:[1,0] op_sel_hi:[0,1]
	v_pk_add_f32 v[204:205], v[204:205], v[204:205] op_sel:[0,1] op_sel_hi:[0,1]
	v_pk_mul_f32 v[206:207], v[216:217], v[204:205]
	v_pk_add_f32 v[202:203], v[202:203], v[202:203] op_sel:[0,1] op_sel_hi:[0,1] neg_lo:[0,1] neg_hi:[0,1]
	v_pk_fma_f32 v[238:239], v[216:217], v[202:203], v[206:207] op_sel:[0,0,1] op_sel_hi:[1,1,0] neg_lo:[0,0,1]
	v_pk_mul_f32 v[202:203], v[222:223], v[202:203]
	v_pk_fma_f32 v[206:207], v[222:223], v[204:205], v[202:203] op_sel:[0,0,1] op_sel_hi:[1,1,0] neg_lo:[1,0,0] neg_hi:[1,0,0]
	v_pk_fma_f32 v[202:203], v[222:223], v[204:205], v[202:203] op_sel:[0,0,1] op_sel_hi:[1,1,0]
	v_mov_b32_e32 v205, v207
	v_mov_b32_e32 v204, v202
	v_pk_mul_f32 v[216:217], v[218:219], v[202:203] op_sel:[1,0] op_sel_hi:[0,0]
	v_pk_mov_b32 v[202:203], v[206:207], v[202:203] op_sel:[1,0]
	v_pk_mul_f32 v[204:205], v[222:223], v[204:205]
	v_pk_mul_f32 v[202:203], v[222:223], v[202:203]
	v_pk_add_f32 v[204:205], v[204:205], v[204:205] op_sel:[1,0] op_sel_hi:[1,0]
	v_pk_fma_f32 v[250:251], v[218:219], v[206:207], v[216:217] op_sel:[0,1,0] neg_lo:[0,0,1]
	v_pk_mul_f32 v[204:205], v[220:221], v[204:205] op_sel:[1,0] op_sel_hi:[0,1]
	v_pk_add_f32 v[202:203], v[202:203], v[202:203] op_sel:[0,1] op_sel_hi:[0,1] neg_lo:[0,1] neg_hi:[0,1]
	v_pk_fma_f32 v[206:207], v[220:221], v[202:203], v[204:205] neg_lo:[0,0,1]
	v_pk_add_f32 v[204:205], v[242:243], v[230:231]
	v_pk_add_f32 v[202:203], v[200:201], v[214:215]
	v_pk_add_f32 v[200:201], v[200:201], v[214:215] neg_lo:[0,1] neg_hi:[0,1]
	v_pk_add_f32 v[214:215], v[242:243], v[230:231] neg_lo:[0,1] neg_hi:[0,1]
	v_pk_add_f32 v[220:221], v[208:209], v[238:239]
	v_xor_b32_e32 v217, 0x80000000, v214
	v_mov_b32_e32 v216, v215
	v_pk_add_f32 v[208:209], v[208:209], v[238:239] neg_lo:[0,1] neg_hi:[0,1]
	v_pk_add_f32 v[214:215], v[202:203], v[204:205]
	v_pk_add_f32 v[218:219], v[200:201], v[216:217]
	v_pk_add_f32 v[202:203], v[202:203], v[204:205] neg_lo:[0,1] neg_hi:[0,1]
	v_pk_add_f32 v[200:201], v[200:201], v[216:217] neg_lo:[0,1] neg_hi:[0,1]
	v_pk_add_f32 v[204:205], v[244:245], v[224:225]
	v_pk_add_f32 v[216:217], v[244:245], v[224:225] neg_lo:[0,1] neg_hi:[0,1]
	v_xor_b32_e32 v223, 0x80000000, v208
	v_mov_b32_e32 v222, v209
	v_pk_add_f32 v[208:209], v[204:205], v[220:221]
	v_pk_add_f32 v[224:225], v[216:217], v[222:223]
	v_pk_add_f32 v[204:205], v[204:205], v[220:221] neg_lo:[0,1] neg_hi:[0,1]
	v_pk_add_f32 v[216:217], v[216:217], v[222:223] neg_lo:[0,1] neg_hi:[0,1]
	v_pk_add_f32 v[220:221], v[248:249], v[226:227]
	v_pk_add_f32 v[222:223], v[248:249], v[226:227] neg_lo:[0,1] neg_hi:[0,1]
	v_pk_add_f32 v[226:227], v[210:211], v[250:251]
	v_pk_add_f32 v[210:211], v[210:211], v[250:251] neg_lo:[0,1] neg_hi:[0,1]
	s_nop 0
	v_xor_b32_e32 v231, 0x80000000, v210
	v_mov_b32_e32 v230, v211
	v_pk_add_f32 v[238:239], v[222:223], v[230:231]
	v_pk_add_f32 v[222:223], v[222:223], v[230:231] neg_lo:[0,1] neg_hi:[0,1]
	v_pk_add_f32 v[230:231], v[212:213], v[206:207]
	v_pk_add_f32 v[206:207], v[212:213], v[206:207] neg_lo:[0,1] neg_hi:[0,1]
	v_pk_add_f32 v[210:211], v[220:221], v[226:227]
	v_pk_add_f32 v[220:221], v[220:221], v[226:227] neg_lo:[0,1] neg_hi:[0,1]
	v_pk_add_f32 v[226:227], v[246:247], v[228:229]
	v_pk_add_f32 v[228:229], v[246:247], v[228:229] neg_lo:[0,1] neg_hi:[0,1]
	v_xor_b32_e32 v213, 0x80000000, v206
	v_mov_b32_e32 v212, v207
	v_pk_add_f32 v[242:243], v[228:229], v[212:213]
	v_pk_add_f32 v[212:213], v[228:229], v[212:213] neg_lo:[0,1] neg_hi:[0,1]
	v_pk_mul_f32 v[228:229], v[224:225], s[24:25] op_sel_hi:[1,0]
	v_pk_add_f32 v[206:207], v[226:227], v[230:231]
	v_pk_add_f32 v[226:227], v[226:227], v[230:231] neg_lo:[0,1] neg_hi:[0,1]
	v_pk_fma_f32 v[230:231], v[224:225], s[26:27], v[228:229] op_sel:[0,0,1] op_sel_hi:[1,0,0] neg_hi:[0,0,1]
	s_nop 0
	v_pk_mul_f32 v[224:225], v[204:205], s[28:29] op_sel_hi:[1,0]
	s_nop 0
	v_pk_fma_f32 v[228:229], v[204:205], s[28:29], v[224:225] op_sel:[0,0,1] op_sel_hi:[1,0,0] neg_hi:[0,0,1]
	v_pk_mul_f32 v[224:225], v[216:217], s[26:27] op_sel_hi:[1,0]
	v_pk_fma_f32 v[244:245], v[216:217], s[24:25], v[224:225] op_sel:[0,0,1] op_sel_hi:[1,0,0] neg_hi:[0,0,1]
	s_nop 0
	v_pk_mul_f32 v[216:217], v[238:239], s[28:29] op_sel_hi:[1,0]
	s_nop 0
	v_pk_fma_f32 v[224:225], v[238:239], s[28:29], v[216:217] op_sel:[0,0,1] op_sel_hi:[1,0,0] neg_hi:[0,0,1]
	s_nop 0
	v_pk_fma_f32 v[216:217], v[220:221], 0, v[220:221] op_sel:[0,0,1] op_sel_hi:[1,0,0] neg_hi:[0,0,1]
	s_nop 0
	v_pk_mul_f32 v[220:221], v[222:223], s[30:31] op_sel_hi:[1,0]
	s_nop 0
	v_pk_fma_f32 v[238:239], v[222:223], s[30:31], v[220:221] op_sel:[0,0,1] op_sel_hi:[1,0,0] neg_lo:[0,0,1]
	v_pk_mul_f32 v[222:223], v[242:243], s[26:27] op_sel_hi:[1,0]
	v_pk_fma_f32 v[246:247], v[242:243], s[24:25], v[222:223] op_sel:[0,0,1] op_sel_hi:[1,0,0] neg_hi:[0,0,1]
	v_pk_add_f32 v[220:221], v[200:201], v[238:239]
	v_pk_mul_f32 v[222:223], v[226:227], s[30:31] op_sel_hi:[1,0]
	v_pk_add_f32 v[200:201], v[200:201], v[238:239] neg_lo:[0,1] neg_hi:[0,1]
	v_pk_fma_f32 v[242:243], v[226:227], s[30:31], v[222:223] op_sel:[0,0,1] op_sel_hi:[1,0,0] neg_lo:[0,0,1]
	s_nop 0
	v_pk_mul_f32 v[222:223], v[212:213], s[60:61] op_sel:[1,0]
	v_pk_add_f32 v[204:205], v[228:229], v[242:243]
	v_pk_fma_f32 v[212:213], v[212:213], s[34:35], v[222:223] op_sel_hi:[0,1,1]
	v_pk_add_f32 v[222:223], v[214:215], v[210:211]
	v_pk_add_f32 v[210:211], v[214:215], v[210:211] neg_lo:[0,1] neg_hi:[0,1]
	v_pk_add_f32 v[214:215], v[208:209], v[206:207]
	v_pk_add_f32 v[206:207], v[208:209], v[206:207] neg_lo:[0,1] neg_hi:[0,1]
	s_nop 0
	v_xor_b32_e32 v209, 0x80000000, v206
	v_mov_b32_e32 v208, v207
	v_pk_add_f32 v[206:207], v[222:223], v[214:215]
	v_pk_add_f32 v[226:227], v[210:211], v[208:209]
	v_pk_add_f32 v[214:215], v[222:223], v[214:215] neg_lo:[0,1] neg_hi:[0,1]
	v_pk_add_f32 v[208:209], v[210:211], v[208:209] neg_lo:[0,1] neg_hi:[0,1]
	v_pk_add_f32 v[210:211], v[218:219], v[224:225]
	v_pk_add_f32 v[218:219], v[218:219], v[224:225] neg_lo:[0,1] neg_hi:[0,1]
	v_pk_add_f32 v[222:223], v[230:231], v[246:247]
	v_pk_add_f32 v[224:225], v[230:231], v[246:247] neg_lo:[0,1] neg_hi:[0,1]
	s_nop 0
	v_xor_b32_e32 v231, 0x80000000, v224
	v_mov_b32_e32 v230, v225
	v_pk_add_f32 v[224:225], v[210:211], v[222:223]
	v_pk_add_f32 v[210:211], v[210:211], v[222:223] neg_lo:[0,1] neg_hi:[0,1]
	v_pk_add_f32 v[222:223], v[202:203], v[216:217]
	v_pk_add_f32 v[202:203], v[202:203], v[216:217] neg_lo:[0,1] neg_hi:[0,1]
	v_pk_add_f32 v[216:217], v[228:229], v[242:243] neg_lo:[0,1] neg_hi:[0,1]
	v_pk_add_f32 v[246:247], v[218:219], v[230:231]
	v_xor_b32_e32 v229, 0x80000000, v216
	v_mov_b32_e32 v228, v217
	v_pk_add_f32 v[216:217], v[222:223], v[204:205]
	v_pk_add_f32 v[204:205], v[222:223], v[204:205] neg_lo:[0,1] neg_hi:[0,1]
	v_pk_add_f32 v[222:223], v[244:245], v[212:213]
	v_pk_add_f32 v[212:213], v[244:245], v[212:213] neg_lo:[0,1] neg_hi:[0,1]
	v_pk_add_f32 v[218:219], v[218:219], v[230:231] neg_lo:[0,1] neg_hi:[0,1]
	v_pk_add_f32 v[230:231], v[202:203], v[228:229]
	v_pk_add_f32 v[202:203], v[202:203], v[228:229] neg_lo:[0,1] neg_hi:[0,1]
	v_xor_b32_e32 v229, 0x80000000, v212
	v_mov_b32_e32 v228, v213
	v_pk_add_f32 v[212:213], v[220:221], v[222:223]
	v_pk_add_f32 v[238:239], v[200:201], v[228:229]
	v_pk_add_f32 v[220:221], v[220:221], v[222:223] neg_lo:[0,1] neg_hi:[0,1]
	v_pk_add_f32 v[200:201], v[200:201], v[228:229] neg_lo:[0,1] neg_hi:[0,1]
	ds_write_b64 v181, v[206:207]
	ds_write_b64 v181, v[224:225] offset:2176
	ds_write_b64 v181, v[216:217] offset:4352
	ds_write_b64 v181, v[212:213] offset:6528
	ds_write_b64 v181, v[226:227] offset:8704
	ds_write_b64 v181, v[246:247] offset:10880
	ds_write_b64 v181, v[230:231] offset:13056
	ds_write_b64 v181, v[238:239] offset:15232
	ds_write_b64 v181, v[214:215] offset:17408
	ds_write_b64 v181, v[210:211] offset:19584
	ds_write_b64 v181, v[204:205] offset:21760
	ds_write_b64 v181, v[220:221] offset:23936
	ds_write_b64 v181, v[208:209] offset:26112
	ds_write_b64 v181, v[218:219] offset:28288
	ds_write_b64 v181, v[202:203] offset:30464
	ds_write_b64 v181, v[200:201] offset:32640
.LBB0_374:
	s_or_b64 exec, exec, s[2:3]
	v_mov_b32_e32 v200, v180
	s_waitcnt lgkmcnt(0)
	s_barrier
	s_nop 0
	v_cmp_gt_i32_e32 vcc, s56, v200
	s_and_saveexec_b64 s[2:3], vcc
	s_cbranch_execz .LBB0_376
	v_ashrrev_i32_e32 v181, 31, v200
	v_add_u32_sdwa v181, v200, v181 dst_sel:DWORD dst_unused:UNUSED_PAD src0_sel:DWORD src1_sel:BYTE_3
	v_ashrrev_i32_e32 v181, 8, v181
	v_mul_i32_i24_e32 v201, 0x100, v181
	v_sub_u32_e32 v237, v200, v201
	v_mul_i32_i24_e32 v181, 0x1100, v181
	v_lshlrev_b32_e32 v181, 3, v181
	v_ashrrev_i32_e32 v201, 4, v237
	v_add_u32_e32 v200, s57, v181
	v_lshlrev_b32_e32 v248, 3, v237
	v_lshlrev_b32_e32 v201, 3, v201
	v_add3_u32 v230, v200, v248, v201
	ds_read_b64 v[200:201], v230
	ds_read_b64 v[202:203], v230 offset:2176
	ds_read_b64 v[204:205], v230 offset:4352
	ds_read_b64 v[206:207], v230 offset:6528
	v_pk_mov_b32 v[208:209], v[44:45], v[44:45] op_sel:[1,0]
	v_pk_mov_b32 v[216:217], v[60:61], v[60:61] op_sel:[1,0]
	s_waitcnt lgkmcnt(3)
	v_pk_mul_f32 v[208:209], v[208:209], v[200:201] op_sel:[0,1]
	s_mov_b32 s35, s60
	v_pk_fma_f32 v[210:211], v[44:45], v[200:201], v[208:209] op_sel_hi:[1,0,1] neg_lo:[0,0,1]
	v_add_u32_e32 v181, 0, v181
	v_pk_mov_b32 v[200:201], v[48:49], v[48:49] op_sel:[1,0]
	s_waitcnt lgkmcnt(2)
	v_pk_mul_f32 v[200:201], v[200:201], v[202:203] op_sel:[0,1]
	s_nop 0
	v_pk_fma_f32 v[208:209], v[48:49], v[202:203], v[200:201] op_sel_hi:[1,0,1] neg_lo:[0,0,1]
	s_nop 0
	v_pk_mov_b32 v[200:201], v[52:53], v[52:53] op_sel:[1,0]
	s_waitcnt lgkmcnt(1)
	v_pk_mul_f32 v[200:201], v[200:201], v[204:205] op_sel:[0,1]
	s_nop 0
	v_pk_fma_f32 v[202:203], v[52:53], v[204:205], v[200:201] op_sel_hi:[1,0,1] neg_lo:[0,0,1]
	s_nop 0
	v_pk_mov_b32 v[200:201], v[56:57], v[56:57] op_sel:[1,0]
	s_waitcnt lgkmcnt(0)
	v_pk_mul_f32 v[200:201], v[200:201], v[206:207] op_sel:[0,1]
	s_nop 0
	v_pk_fma_f32 v[204:205], v[56:57], v[206:207], v[200:201] op_sel_hi:[1,0,1] neg_lo:[0,0,1]
	ds_read_b64 v[206:207], v230 offset:8704
	ds_read_b64 v[200:201], v230 offset:10880
	ds_read_b64 v[212:213], v230 offset:13056
	ds_read_b64 v[214:215], v230 offset:15232
	s_waitcnt lgkmcnt(3)
	v_pk_mul_f32 v[216:217], v[216:217], v[206:207] op_sel:[0,1]
	s_nop 0
	v_pk_fma_f32 v[218:219], v[60:61], v[206:207], v[216:217] op_sel_hi:[1,0,1] neg_lo:[0,0,1]
	s_nop 0
	v_pk_mov_b32 v[206:207], v[64:65], v[64:65] op_sel:[1,0]
	s_waitcnt lgkmcnt(2)
	v_pk_mul_f32 v[206:207], v[206:207], v[200:201] op_sel:[0,1]
	s_nop 0
	v_pk_fma_f32 v[216:217], v[64:65], v[200:201], v[206:207] op_sel_hi:[1,0,1] neg_lo:[0,0,1]
	s_nop 0
	v_pk_mov_b32 v[200:201], v[68:69], v[68:69] op_sel:[1,0]
	s_waitcnt lgkmcnt(1)
	v_pk_mul_f32 v[200:201], v[200:201], v[212:213] op_sel:[0,1]
	s_nop 0
	v_pk_fma_f32 v[206:207], v[68:69], v[212:213], v[200:201] op_sel_hi:[1,0,1] neg_lo:[0,0,1]
	s_nop 0
	s_waitcnt lgkmcnt(0)
	v_pk_mul_f32 v[200:201], v[138:139], v[214:215] op_sel:[0,1]
	s_nop 0
	v_pk_fma_f32 v[212:213], v[72:73], v[214:215], v[200:201] op_sel_hi:[1,0,1] neg_lo:[0,0,1]
	ds_read_b64 v[214:215], v230 offset:17408
	ds_read_b64 v[200:201], v230 offset:19584
	ds_read_b64 v[220:221], v230 offset:21760
	ds_read_b64 v[222:223], v230 offset:23936
	s_waitcnt lgkmcnt(3)
	v_pk_mul_f32 v[224:225], v[140:141], v[214:215] op_sel:[0,1]
	s_nop 0
	v_pk_fma_f32 v[226:227], v[76:77], v[214:215], v[224:225] op_sel_hi:[1,0,1] neg_lo:[0,0,1]
	s_nop 0
	s_waitcnt lgkmcnt(2)
	v_pk_mul_f32 v[214:215], v[142:143], v[200:201] op_sel:[0,1]
	s_nop 0
	v_pk_fma_f32 v[224:225], v[80:81], v[200:201], v[214:215] op_sel_hi:[1,0,1] neg_lo:[0,0,1]
	s_nop 0
	s_waitcnt lgkmcnt(1)
	v_pk_mul_f32 v[200:201], v[144:145], v[220:221] op_sel:[0,1]
	s_nop 0
	v_pk_fma_f32 v[214:215], v[86:87], v[220:221], v[200:201] op_sel_hi:[1,0,1] neg_lo:[0,0,1]
	s_nop 0
	s_waitcnt lgkmcnt(0)
	v_pk_mul_f32 v[200:201], v[146:147], v[222:223] op_sel:[0,1]
	s_nop 0
	v_pk_fma_f32 v[220:221], v[90:91], v[222:223], v[200:201] op_sel_hi:[1,0,1] neg_lo:[0,0,1]
	ds_read_b64 v[222:223], v230 offset:26112
	ds_read_b64 v[200:201], v230 offset:28288
	ds_read_b64 v[228:229], v230 offset:30464
	ds_read_b64 v[230:231], v230 offset:32640
	s_waitcnt lgkmcnt(3)
	v_pk_mul_f32 v[238:239], v[148:149], v[222:223] op_sel:[0,1]
	s_nop 0
	v_pk_fma_f32 v[242:243], v[94:95], v[222:223], v[238:239] op_sel_hi:[1,0,1] neg_lo:[0,0,1]
	s_nop 0
	s_waitcnt lgkmcnt(2)
	v_pk_mul_f32 v[222:223], v[150:151], v[200:201] op_sel:[0,1]
	s_nop 0
	v_pk_fma_f32 v[238:239], v[100:101], v[200:201], v[222:223] op_sel_hi:[1,0,1] neg_lo:[0,0,1]
	s_nop 0
	s_waitcnt lgkmcnt(1)
	v_pk_mul_f32 v[200:201], v[152:153], v[228:229] op_sel:[0,1]
	s_nop 0
	v_pk_fma_f32 v[222:223], v[104:105], v[228:229], v[200:201] op_sel_hi:[1,0,1] neg_lo:[0,0,1]
	s_nop 0
	s_waitcnt lgkmcnt(0)
	v_pk_mul_f32 v[200:201], v[154:155], v[230:231] op_sel:[0,1]
	s_nop 0
	v_pk_fma_f32 v[228:229], v[108:109], v[230:231], v[200:201] op_sel_hi:[1,0,1] neg_lo:[0,0,1]
	s_nop 0
	v_pk_add_f32 v[200:201], v[210:211], v[226:227]
	v_pk_add_f32 v[210:211], v[210:211], v[226:227] neg_lo:[0,1] neg_hi:[0,1]
	v_pk_add_f32 v[226:227], v[218:219], v[242:243]
	v_pk_add_f32 v[218:219], v[218:219], v[242:243] neg_lo:[0,1] neg_hi:[0,1]
	s_nop 0
	v_xor_b32_e32 v230, 0x80000000, v219
	v_mov_b32_e32 v231, v218
	v_pk_add_f32 v[218:219], v[200:201], v[226:227]
	v_pk_add_f32 v[200:201], v[200:201], v[226:227] neg_lo:[0,1] neg_hi:[0,1]
	v_pk_add_f32 v[226:227], v[208:209], v[224:225]
	v_pk_add_f32 v[208:209], v[208:209], v[224:225] neg_lo:[0,1] neg_hi:[0,1]
	v_pk_add_f32 v[224:225], v[216:217], v[238:239]
	v_pk_add_f32 v[216:217], v[216:217], v[238:239] neg_lo:[0,1] neg_hi:[0,1]
	v_pk_add_f32 v[242:243], v[210:211], v[230:231]
	v_pk_add_f32 v[210:211], v[210:211], v[230:231] neg_lo:[0,1] neg_hi:[0,1]
	v_xor_b32_e32 v230, 0x80000000, v217
	v_mov_b32_e32 v231, v216
	v_pk_add_f32 v[216:217], v[226:227], v[224:225]
	v_pk_add_f32 v[224:225], v[226:227], v[224:225] neg_lo:[0,1] neg_hi:[0,1]
	v_pk_add_f32 v[226:227], v[202:203], v[214:215]
	v_pk_add_f32 v[202:203], v[202:203], v[214:215] neg_lo:[0,1] neg_hi:[0,1]
	v_pk_add_f32 v[214:215], v[206:207], v[222:223]
	v_pk_add_f32 v[206:207], v[206:207], v[222:223] neg_lo:[0,1] neg_hi:[0,1]
	v_pk_add_f32 v[238:239], v[208:209], v[230:231]
	v_xor_b32_e32 v222, 0x80000000, v207
	v_mov_b32_e32 v223, v206
	v_pk_add_f32 v[208:209], v[208:209], v[230:231] neg_lo:[0,1] neg_hi:[0,1]
	v_pk_add_f32 v[230:231], v[202:203], v[222:223]
	v_pk_add_f32 v[202:203], v[202:203], v[222:223] neg_lo:[0,1] neg_hi:[0,1]
	v_pk_add_f32 v[222:223], v[204:205], v[220:221]
	v_pk_add_f32 v[204:205], v[204:205], v[220:221] neg_lo:[0,1] neg_hi:[0,1]
	v_pk_add_f32 v[220:221], v[212:213], v[228:229]
	v_pk_add_f32 v[212:213], v[212:213], v[228:229] neg_lo:[0,1] neg_hi:[0,1]
	v_pk_add_f32 v[206:207], v[226:227], v[214:215]
	v_pk_add_f32 v[214:215], v[226:227], v[214:215] neg_lo:[0,1] neg_hi:[0,1]
	v_xor_b32_e32 v226, 0x80000000, v213
	v_mov_b32_e32 v227, v212
	v_pk_add_f32 v[212:213], v[222:223], v[220:221]
	v_pk_add_f32 v[220:221], v[222:223], v[220:221] neg_lo:[0,1] neg_hi:[0,1]
	v_pk_mul_f32 v[222:223], v[238:239], s[24:25] op_sel_hi:[1,0]
	v_pk_add_f32 v[228:229], v[204:205], v[226:227]
	v_pk_add_f32 v[204:205], v[204:205], v[226:227] neg_lo:[0,1] neg_hi:[0,1]
	v_pk_fma_f32 v[226:227], v[238:239], s[26:27], v[222:223] op_sel:[0,0,1] op_sel_hi:[1,0,0] neg_lo:[0,0,1]
	s_nop 0
	v_pk_mul_f32 v[222:223], v[224:225], s[28:29] op_sel_hi:[1,0]
	s_nop 0
	v_pk_fma_f32 v[238:239], v[224:225], s[28:29], v[222:223] op_sel:[0,0,1] op_sel_hi:[1,0,0] neg_lo:[0,0,1]
	v_pk_mul_f32 v[224:225], v[208:209], s[26:27] op_sel_hi:[1,0]
	v_pk_fma_f32 v[244:245], v[208:209], s[24:25], v[224:225] op_sel:[0,0,1] op_sel_hi:[1,0,0] neg_lo:[0,0,1]
	s_nop 0
	v_pk_mul_f32 v[208:209], v[230:231], s[28:29] op_sel_hi:[1,0]
	s_nop 0
	v_pk_fma_f32 v[224:225], v[230:231], s[28:29], v[208:209] op_sel:[0,0,1] op_sel_hi:[1,0,0] neg_lo:[0,0,1]
	s_nop 0
	v_pk_fma_f32 v[208:209], v[214:215], 0, v[214:215] op_sel:[0,0,1] op_sel_hi:[1,0,0] neg_lo:[0,0,1]
	s_nop 0
	v_pk_mul_f32 v[214:215], v[202:203], s[30:31] op_sel_hi:[1,0]
	s_nop 0
	v_pk_fma_f32 v[230:231], v[202:203], s[30:31], v[214:215] op_sel:[0,0,1] op_sel_hi:[1,0,0] neg_hi:[0,0,1]
	v_pk_mul_f32 v[214:215], v[228:229], s[26:27] op_sel_hi:[1,0]
	v_pk_fma_f32 v[246:247], v[228:229], s[24:25], v[214:215] op_sel:[0,0,1] op_sel_hi:[1,0,0] neg_lo:[0,0,1]
	s_mov_b32 s25, s34
	v_pk_mul_f32 v[214:215], v[220:221], s[30:31] op_sel_hi:[1,0]
	v_pk_add_f32 v[202:203], v[210:211], v[230:231]
	v_pk_fma_f32 v[228:229], v[220:221], s[30:31], v[214:215] op_sel:[0,0,1] op_sel_hi:[1,0,0] neg_hi:[0,0,1]
	v_pk_add_f32 v[210:211], v[210:211], v[230:231] neg_lo:[0,1] neg_hi:[0,1]
	v_pk_mul_f32 v[214:215], v[204:205], s[34:35] op_sel_hi:[0,1]
	v_pk_fma_f32 v[204:205], v[204:205], s[24:25], v[214:215] op_sel:[1,0,0]
	v_pk_add_f32 v[214:215], v[218:219], v[206:207]
	v_pk_add_f32 v[206:207], v[218:219], v[206:207] neg_lo:[0,1] neg_hi:[0,1]
	v_pk_add_f32 v[218:219], v[216:217], v[212:213]
	v_pk_add_f32 v[212:213], v[216:217], v[212:213] neg_lo:[0,1] neg_hi:[0,1]
	v_pk_add_f32 v[222:223], v[238:239], v[228:229] neg_lo:[0,1] neg_hi:[0,1]
	v_xor_b32_e32 v216, 0x80000000, v213
	v_mov_b32_e32 v217, v212
	v_pk_add_f32 v[212:213], v[214:215], v[218:219]
	v_pk_add_f32 v[220:221], v[206:207], v[216:217]
	v_pk_add_f32 v[214:215], v[214:215], v[218:219] neg_lo:[0,1] neg_hi:[0,1]
	v_pk_add_f32 v[206:207], v[206:207], v[216:217] neg_lo:[0,1] neg_hi:[0,1]
	v_pk_add_f32 v[216:217], v[242:243], v[224:225]
	v_pk_add_f32 v[218:219], v[242:243], v[224:225] neg_lo:[0,1] neg_hi:[0,1]
	v_pk_add_f32 v[224:225], v[226:227], v[246:247]
	v_pk_add_f32 v[226:227], v[226:227], v[246:247] neg_lo:[0,1] neg_hi:[0,1]
	s_nop 0
	v_xor_b32_e32 v242, 0x80000000, v227
	v_mov_b32_e32 v243, v226
	v_pk_add_f32 v[226:227], v[216:217], v[224:225]
	v_pk_add_f32 v[216:217], v[216:217], v[224:225] neg_lo:[0,1] neg_hi:[0,1]
	v_pk_add_f32 v[224:225], v[200:201], v[208:209]
	v_pk_add_f32 v[200:201], v[200:201], v[208:209] neg_lo:[0,1] neg_hi:[0,1]
	v_pk_add_f32 v[208:209], v[238:239], v[228:229]
	v_xor_b32_e32 v228, 0x80000000, v223
	v_mov_b32_e32 v229, v222
	v_pk_add_f32 v[222:223], v[224:225], v[208:209]
	v_pk_add_f32 v[208:209], v[224:225], v[208:209] neg_lo:[0,1] neg_hi:[0,1]
	v_pk_add_f32 v[224:225], v[244:245], v[204:205]
	v_pk_add_f32 v[204:205], v[244:245], v[204:205] neg_lo:[0,1] neg_hi:[0,1]
	v_pk_add_f32 v[238:239], v[200:201], v[228:229]
	v_pk_add_f32 v[200:201], v[200:201], v[228:229] neg_lo:[0,1] neg_hi:[0,1]
	v_xor_b32_e32 v228, 0x80000000, v205
	v_mov_b32_e32 v229, v204
	v_pk_add_f32 v[204:205], v[202:203], v[224:225]
	v_pk_add_f32 v[202:203], v[202:203], v[224:225] neg_lo:[0,1] neg_hi:[0,1]
	v_lshlrev_b32_e32 v224, 7, v237
	v_add3_u32 v181, v181, v224, v248
	v_add_u32_e32 v224, 0x1880, v181
	ds_write2_b64 v224, v[212:213], v[226:227] offset1:1
	v_add_u32_e32 v212, 0x1890, v181
	v_pk_add_f32 v[246:247], v[218:219], v[242:243]
	ds_write2_b64 v212, v[222:223], v[204:205] offset1:1
	v_add_u32_e32 v204, 0x18a0, v181
	v_pk_add_f32 v[230:231], v[210:211], v[228:229]
	ds_write2_b64 v204, v[220:221], v[246:247] offset1:1
	v_add_u32_e32 v204, 0x18b0, v181
	ds_write2_b64 v204, v[238:239], v[230:231] offset1:1
	v_add_u32_e32 v204, 0x18c0, v181
	ds_write2_b64 v204, v[214:215], v[216:217] offset1:1
	v_add_u32_e32 v204, 0x18d0, v181
	v_pk_add_f32 v[218:219], v[218:219], v[242:243] neg_lo:[0,1] neg_hi:[0,1]
	v_pk_add_f32 v[210:211], v[210:211], v[228:229] neg_lo:[0,1] neg_hi:[0,1]
	ds_write2_b64 v204, v[208:209], v[202:203] offset1:1
	v_add_u32_e32 v202, 0x18e0, v181
	v_add_u32_e32 v181, 0x18f0, v181
	ds_write2_b64 v202, v[206:207], v[218:219] offset1:1
	ds_write2_b64 v181, v[200:201], v[210:211] offset1:1
.LBB0_376:
	s_or_b64 exec, exec, s[2:3]
	v_mov_b32_e32 v200, v180
	s_waitcnt lgkmcnt(0)
	s_barrier
	s_nop 0
	v_cmp_gt_i32_e32 vcc, s56, v200
	s_and_saveexec_b64 s[2:3], vcc
	s_cbranch_execz .LBB0_378
	v_ashrrev_i32_e32 v181, 31, v200
	v_add_u32_sdwa v181, v200, v181 dst_sel:DWORD dst_unused:UNUSED_PAD src0_sel:DWORD src1_sel:BYTE_3
	v_ashrrev_i32_e32 v181, 8, v181
	v_mul_i32_i24_e32 v201, 0x100, v181
	v_sub_u32_e32 v200, v200, v201
	v_ashrrev_i16_e32 v201, 15, v200
	v_lshrrev_b16_e32 v201, 12, v201
	v_add_u16_e32 v201, v200, v201
	v_ashrrev_i16_e32 v237, 4, v201
	v_and_b32_e32 v201, -16, v201
	v_mul_i32_i24_e32 v181, 0x1100, v181
	v_sub_u16_e32 v204, v200, v201
	v_lshlrev_b32_e32 v238, 3, v181
	v_lshlrev_b32_e32 v201, 3, v200
	v_ashrrev_i32_e32 v200, 4, v200
	v_add_u32_e32 v181, 0, v238
	v_lshlrev_b32_e32 v200, 3, v200
	v_add3_u32 v181, v181, v201, v200
	v_bfe_i32 v239, v204, 0, 16
	ds_read_b64 v[200:201], v181 offset:6272
	ds_read_b64 v[202:203], v181 offset:8448
	ds_read_b64 v[214:215], v181 offset:10624
	ds_read_b64 v[216:217], v181 offset:12800
	ds_read_b64 v[218:219], v181 offset:14976
	ds_read_b64 v[222:223], v181 offset:17152
	ds_read_b64 v[224:225], v181 offset:19328
	ds_read_b64 v[226:227], v181 offset:21504
	ds_read_b64 v[228:229], v181 offset:23680
	ds_read_b64 v[230:231], v181 offset:25856
	ds_read_b64 v[242:243], v181 offset:28032
	ds_read_b64 v[244:245], v181 offset:30208
	ds_read_b64 v[246:247], v181 offset:32384
	ds_read_b64 v[248:249], v181 offset:34560
	ds_read_b64 v[250:251], v181 offset:36736
	ds_read_b64 v[206:207], v181 offset:38912
	v_mad_i32_i24 v181, v239, s27, 0
	v_add_u32_e32 v204, 0x808, v181
	ds_read2_b64 v[210:213], v204 offset1:1
	s_mov_b32 s35, s60
	s_waitcnt lgkmcnt(0)
	v_pk_mul_f32 v[204:205], v[202:203], v[210:211] op_sel:[1,1] op_sel_hi:[0,1]
	v_pk_fma_f32 v[208:209], v[202:203], v[210:211], v[204:205]
	v_pk_fma_f32 v[202:203], v[202:203], v[210:211], v[204:205] op_sel_hi:[1,0,1] neg_lo:[0,0,1] neg_hi:[0,0,1]
	s_nop 0
	v_mov_b32_e32 v202, v213
	v_mov_b32_e32 v209, v203
	v_pk_mul_f32 v[202:203], v[214:215], v[202:203] op_sel:[1,0] op_sel_hi:[0,0]
	v_pk_fma_f32 v[204:205], v[214:215], v[212:213], v[202:203]
	v_pk_fma_f32 v[202:203], v[214:215], v[212:213], v[202:203] op_sel_hi:[1,0,1] neg_lo:[0,0,1] neg_hi:[0,0,1]
	s_nop 0
	v_add_u32_e32 v202, 0x818, v181
	ds_read2_b64 v[210:213], v202 offset1:1
	v_mov_b32_e32 v205, v203
	s_waitcnt lgkmcnt(0)
	v_pk_mul_f32 v[214:215], v[216:217], v[210:211] op_sel:[1,1] op_sel_hi:[0,1]
	v_pk_fma_f32 v[202:203], v[216:217], v[210:211], v[214:215]
	v_pk_fma_f32 v[210:211], v[216:217], v[210:211], v[214:215] op_sel_hi:[1,0,1] neg_lo:[0,0,1] neg_hi:[0,0,1]
	s_nop 0
	v_mov_b32_e32 v210, v213
	v_mov_b32_e32 v203, v211
	v_pk_mul_f32 v[210:211], v[218:219], v[210:211] op_sel:[1,0] op_sel_hi:[0,0]
	v_pk_fma_f32 v[216:217], v[218:219], v[212:213], v[210:211]
	v_pk_fma_f32 v[210:211], v[218:219], v[212:213], v[210:211] op_sel_hi:[1,0,1] neg_lo:[0,0,1] neg_hi:[0,0,1]
	s_nop 0
	v_add_u32_e32 v210, 0x828, v181
	ds_read2_b64 v[218:221], v210 offset1:1
	v_mov_b32_e32 v217, v211
	s_waitcnt lgkmcnt(0)
	v_pk_mul_f32 v[210:211], v[222:223], v[218:219] op_sel:[1,1] op_sel_hi:[0,1]
	v_pk_fma_f32 v[214:215], v[222:223], v[218:219], v[210:211]
	v_pk_fma_f32 v[210:211], v[222:223], v[218:219], v[210:211] op_sel_hi:[1,0,1] neg_lo:[0,0,1] neg_hi:[0,0,1]
	s_nop 0
	v_mov_b32_e32 v210, v221
	v_mov_b32_e32 v215, v211
	v_pk_mul_f32 v[210:211], v[224:225], v[210:211] op_sel:[1,0] op_sel_hi:[0,0]
	v_pk_fma_f32 v[212:213], v[224:225], v[220:221], v[210:211]
	v_pk_fma_f32 v[210:211], v[224:225], v[220:221], v[210:211] op_sel_hi:[1,0,1] neg_lo:[0,0,1] neg_hi:[0,0,1]
	s_nop 0
	v_add_u32_e32 v210, 0x838, v181
	ds_read2_b64 v[218:221], v210 offset1:1
	v_mov_b32_e32 v213, v211
	s_waitcnt lgkmcnt(0)
	v_pk_mul_f32 v[222:223], v[226:227], v[218:219] op_sel:[1,1] op_sel_hi:[0,1]
	v_pk_fma_f32 v[210:211], v[226:227], v[218:219], v[222:223]
	v_pk_fma_f32 v[218:219], v[226:227], v[218:219], v[222:223] op_sel_hi:[1,0,1] neg_lo:[0,0,1] neg_hi:[0,0,1]
	s_nop 0
	v_mov_b32_e32 v218, v221
	v_mov_b32_e32 v211, v219
	v_pk_mul_f32 v[218:219], v[228:229], v[218:219] op_sel:[1,0] op_sel_hi:[0,0]
	v_pk_fma_f32 v[224:225], v[228:229], v[220:221], v[218:219]
	v_pk_fma_f32 v[218:219], v[228:229], v[220:221], v[218:219] op_sel_hi:[1,0,1] neg_lo:[0,0,1] neg_hi:[0,0,1]
	s_nop 0
	v_add_u32_e32 v218, 0x848, v181
	ds_read2_b64 v[226:229], v218 offset1:1
	v_mov_b32_e32 v225, v219
	s_waitcnt lgkmcnt(0)
	v_pk_mul_f32 v[218:219], v[230:231], v[226:227] op_sel:[1,1] op_sel_hi:[0,1]
	v_pk_fma_f32 v[222:223], v[230:231], v[226:227], v[218:219]
	v_pk_fma_f32 v[218:219], v[230:231], v[226:227], v[218:219] op_sel_hi:[1,0,1] neg_lo:[0,0,1] neg_hi:[0,0,1]
	s_nop 0
	v_mov_b32_e32 v218, v229
	v_mov_b32_e32 v223, v219
	v_pk_mul_f32 v[218:219], v[242:243], v[218:219] op_sel:[1,0] op_sel_hi:[0,0]
	v_pk_fma_f32 v[220:221], v[242:243], v[228:229], v[218:219]
	v_pk_fma_f32 v[218:219], v[242:243], v[228:229], v[218:219] op_sel_hi:[1,0,1] neg_lo:[0,0,1] neg_hi:[0,0,1]
	s_nop 0
	v_add_u32_e32 v218, 0x858, v181
	ds_read2_b64 v[226:229], v218 offset1:1
	v_mov_b32_e32 v221, v219
	s_waitcnt lgkmcnt(0)
	v_pk_mul_f32 v[230:231], v[244:245], v[226:227] op_sel:[1,1] op_sel_hi:[0,1]
	v_pk_fma_f32 v[218:219], v[244:245], v[226:227], v[230:231]
	v_pk_fma_f32 v[226:227], v[244:245], v[226:227], v[230:231] op_sel_hi:[1,0,1] neg_lo:[0,0,1] neg_hi:[0,0,1]
	s_nop 0
	v_mov_b32_e32 v226, v229
	v_mov_b32_e32 v219, v227
	v_pk_mul_f32 v[226:227], v[246:247], v[226:227] op_sel:[1,0] op_sel_hi:[0,0]
	v_pk_fma_f32 v[230:231], v[246:247], v[228:229], v[226:227]
	v_pk_fma_f32 v[226:227], v[246:247], v[228:229], v[226:227] op_sel_hi:[1,0,1] neg_lo:[0,0,1] neg_hi:[0,0,1]
	s_nop 0
	v_add_u32_e32 v226, 0x868, v181
	ds_read2_b64 v[242:245], v226 offset1:1
	v_mov_b32_e32 v231, v227
	s_waitcnt lgkmcnt(0)
	v_pk_mul_f32 v[226:227], v[248:249], v[242:243] op_sel:[1,1] op_sel_hi:[0,1]
	v_pk_fma_f32 v[228:229], v[248:249], v[242:243], v[226:227]
	v_pk_fma_f32 v[226:227], v[248:249], v[242:243], v[226:227] op_sel_hi:[1,0,1] neg_lo:[0,0,1] neg_hi:[0,0,1]
	s_nop 0
	v_mov_b32_e32 v226, v245
	v_pk_mul_f32 v[242:243], v[250:251], v[226:227] op_sel:[1,0] op_sel_hi:[0,0]
	v_mov_b32_e32 v229, v227
	v_pk_fma_f32 v[226:227], v[250:251], v[244:245], v[242:243] op_sel_hi:[1,0,1] neg_hi:[0,0,1]
	s_nop 0
	ds_read_b64 v[242:243], v181 offset:2168
	v_bfe_i32 v181, v237, 0, 16
	v_lshl_add_u32 v181, v181, 8, v239
	s_waitcnt lgkmcnt(0)
	v_pk_mul_f32 v[244:245], v[206:207], v[242:243] op_sel:[1,1] op_sel_hi:[0,1]
	v_pk_fma_f32 v[246:247], v[206:207], v[242:243], v[244:245] op_sel_hi:[1,0,1] neg_hi:[0,0,1]
	s_nop 0
	v_pk_add_f32 v[206:207], v[200:201], v[224:225]
	v_pk_add_f32 v[200:201], v[200:201], v[224:225] neg_lo:[0,1] neg_hi:[0,1]
	v_pk_add_f32 v[224:225], v[216:217], v[230:231]
	v_pk_add_f32 v[216:217], v[216:217], v[230:231] neg_lo:[0,1] neg_hi:[0,1]
	s_nop 0
	v_xor_b32_e32 v230, 0x80000000, v217
	v_mov_b32_e32 v231, v216
	v_pk_add_f32 v[216:217], v[206:207], v[224:225]
	v_pk_add_f32 v[206:207], v[206:207], v[224:225] neg_lo:[0,1] neg_hi:[0,1]
	v_pk_add_f32 v[224:225], v[208:209], v[222:223]
	v_pk_add_f32 v[208:209], v[208:209], v[222:223] neg_lo:[0,1] neg_hi:[0,1]
	v_pk_add_f32 v[222:223], v[214:215], v[228:229]
	v_pk_add_f32 v[214:215], v[214:215], v[228:229] neg_lo:[0,1] neg_hi:[0,1]
	v_pk_add_f32 v[242:243], v[200:201], v[230:231]
	v_xor_b32_e32 v228, 0x80000000, v215
	v_mov_b32_e32 v229, v214
	v_pk_add_f32 v[214:215], v[224:225], v[222:223]
	v_pk_add_f32 v[222:223], v[224:225], v[222:223] neg_lo:[0,1] neg_hi:[0,1]
	v_pk_add_f32 v[224:225], v[204:205], v[220:221]
	v_pk_add_f32 v[204:205], v[204:205], v[220:221] neg_lo:[0,1] neg_hi:[0,1]
	v_pk_add_f32 v[220:221], v[212:213], v[226:227]
	v_pk_add_f32 v[212:213], v[212:213], v[226:227] neg_lo:[0,1] neg_hi:[0,1]
	v_pk_add_f32 v[200:201], v[200:201], v[230:231] neg_lo:[0,1] neg_hi:[0,1]
	v_pk_add_f32 v[230:231], v[208:209], v[228:229]
	v_xor_b32_e32 v226, 0x80000000, v213
	v_mov_b32_e32 v227, v212
	v_pk_add_f32 v[212:213], v[224:225], v[220:221]
	v_pk_add_f32 v[220:221], v[224:225], v[220:221] neg_lo:[0,1] neg_hi:[0,1]
	v_pk_add_f32 v[224:225], v[202:203], v[218:219]
	v_pk_add_f32 v[202:203], v[202:203], v[218:219] neg_lo:[0,1] neg_hi:[0,1]
	v_pk_add_f32 v[218:219], v[210:211], v[246:247]
	v_pk_add_f32 v[210:211], v[210:211], v[246:247] neg_lo:[0,1] neg_hi:[0,1]
	v_pk_add_f32 v[208:209], v[208:209], v[228:229] neg_lo:[0,1] neg_hi:[0,1]
	v_pk_add_f32 v[228:229], v[204:205], v[226:227]
	v_pk_add_f32 v[204:205], v[204:205], v[226:227] neg_lo:[0,1] neg_hi:[0,1]
	v_xor_b32_e32 v226, 0x80000000, v211
	v_mov_b32_e32 v227, v210
	v_pk_add_f32 v[210:211], v[224:225], v[218:219]
	v_pk_add_f32 v[218:219], v[224:225], v[218:219] neg_lo:[0,1] neg_hi:[0,1]
	v_pk_mul_f32 v[224:225], v[230:231], s[24:25] op_sel_hi:[1,0]
	v_pk_add_f32 v[244:245], v[202:203], v[226:227]
	v_pk_add_f32 v[202:203], v[202:203], v[226:227] neg_lo:[0,1] neg_hi:[0,1]
	v_pk_fma_f32 v[226:227], v[230:231], s[26:27], v[224:225] op_sel:[0,0,1] op_sel_hi:[1,0,0] neg_lo:[0,0,1]
	s_nop 0
	v_pk_mul_f32 v[224:225], v[222:223], s[28:29] op_sel_hi:[1,0]
	s_nop 0
	v_pk_fma_f32 v[230:231], v[222:223], s[28:29], v[224:225] op_sel:[0,0,1] op_sel_hi:[1,0,0] neg_lo:[0,0,1]
	v_pk_mul_f32 v[224:225], v[208:209], s[26:27] op_sel_hi:[1,0]
	v_pk_fma_f32 v[246:247], v[208:209], s[24:25], v[224:225] op_sel:[0,0,1] op_sel_hi:[1,0,0] neg_lo:[0,0,1]
	s_nop 0
	v_pk_mul_f32 v[208:209], v[228:229], s[28:29] op_sel_hi:[1,0]
	s_nop 0
	v_pk_fma_f32 v[224:225], v[228:229], s[28:29], v[208:209] op_sel:[0,0,1] op_sel_hi:[1,0,0] neg_lo:[0,0,1]
	s_nop 0
	v_pk_fma_f32 v[208:209], v[220:221], 0, v[220:221] op_sel:[0,0,1] op_sel_hi:[1,0,0] neg_lo:[0,0,1]
	s_nop 0
	v_pk_mul_f32 v[220:221], v[204:205], s[30:31] op_sel_hi:[1,0]
	s_nop 0
	v_pk_fma_f32 v[228:229], v[204:205], s[30:31], v[220:221] op_sel:[0,0,1] op_sel_hi:[1,0,0] neg_hi:[0,0,1]
	v_pk_mul_f32 v[220:221], v[244:245], s[26:27] op_sel_hi:[1,0]
	v_pk_fma_f32 v[248:249], v[244:245], s[24:25], v[220:221] op_sel:[0,0,1] op_sel_hi:[1,0,0] neg_lo:[0,0,1]
	s_mov_b32 s25, s34
	v_pk_mul_f32 v[220:221], v[218:219], s[30:31] op_sel_hi:[1,0]
	v_pk_add_f32 v[204:205], v[200:201], v[228:229]
	v_pk_fma_f32 v[244:245], v[218:219], s[30:31], v[220:221] op_sel:[0,0,1] op_sel_hi:[1,0,0] neg_hi:[0,0,1]
	v_pk_add_f32 v[200:201], v[200:201], v[228:229] neg_lo:[0,1] neg_hi:[0,1]
	v_pk_mul_f32 v[218:219], v[202:203], s[34:35] op_sel_hi:[0,1]
	v_pk_fma_f32 v[202:203], v[202:203], s[24:25], v[218:219] op_sel:[1,0,0]
	v_pk_add_f32 v[218:219], v[216:217], v[212:213]
	v_pk_add_f32 v[212:213], v[216:217], v[212:213] neg_lo:[0,1] neg_hi:[0,1]
	v_pk_add_f32 v[216:217], v[214:215], v[210:211]
	v_pk_add_f32 v[210:211], v[214:215], v[210:211] neg_lo:[0,1] neg_hi:[0,1]
	v_pk_add_f32 v[222:223], v[230:231], v[244:245] neg_lo:[0,1] neg_hi:[0,1]
	v_xor_b32_e32 v214, 0x80000000, v211
	v_mov_b32_e32 v215, v210
	v_pk_add_f32 v[210:211], v[218:219], v[216:217]
	v_pk_add_f32 v[220:221], v[212:213], v[214:215]
	v_pk_add_f32 v[216:217], v[218:219], v[216:217] neg_lo:[0,1] neg_hi:[0,1]
	v_pk_add_f32 v[212:213], v[212:213], v[214:215] neg_lo:[0,1] neg_hi:[0,1]
	v_pk_add_f32 v[214:215], v[242:243], v[224:225]
	v_pk_add_f32 v[218:219], v[242:243], v[224:225] neg_lo:[0,1] neg_hi:[0,1]
	v_pk_add_f32 v[224:225], v[226:227], v[248:249]
	v_pk_add_f32 v[226:227], v[226:227], v[248:249] neg_lo:[0,1] neg_hi:[0,1]
	s_nop 0
	v_xor_b32_e32 v242, 0x80000000, v227
	v_mov_b32_e32 v243, v226
	v_pk_add_f32 v[226:227], v[214:215], v[224:225]
	v_pk_add_f32 v[214:215], v[214:215], v[224:225] neg_lo:[0,1] neg_hi:[0,1]
	v_pk_add_f32 v[224:225], v[206:207], v[208:209]
	v_pk_add_f32 v[206:207], v[206:207], v[208:209] neg_lo:[0,1] neg_hi:[0,1]
	v_pk_add_f32 v[208:209], v[230:231], v[244:245]
	v_xor_b32_e32 v230, 0x80000000, v223
	v_mov_b32_e32 v231, v222
	v_pk_add_f32 v[222:223], v[224:225], v[208:209]
	v_pk_add_f32 v[208:209], v[224:225], v[208:209] neg_lo:[0,1] neg_hi:[0,1]
	v_pk_add_f32 v[224:225], v[246:247], v[202:203]
	v_pk_add_f32 v[202:203], v[246:247], v[202:203] neg_lo:[0,1] neg_hi:[0,1]
	v_pk_add_f32 v[248:249], v[218:219], v[242:243]
	v_xor_b32_e32 v228, 0x80000000, v203
	v_mov_b32_e32 v229, v202
	v_pk_add_f32 v[202:203], v[204:205], v[224:225]
	v_pk_add_f32 v[204:205], v[204:205], v[224:225] neg_lo:[0,1] neg_hi:[0,1]
	v_lshlrev_b32_e32 v225, 3, v181
	v_ashrrev_i32_e32 v181, 4, v181
	v_add_u32_e32 v224, s57, v238
	v_lshlrev_b32_e32 v181, 3, v181
	v_add3_u32 v181, v224, v225, v181
	v_pk_add_f32 v[218:219], v[218:219], v[242:243] neg_lo:[0,1] neg_hi:[0,1]
	v_pk_add_f32 v[242:243], v[206:207], v[230:231]
	v_pk_add_f32 v[206:207], v[206:207], v[230:231] neg_lo:[0,1] neg_hi:[0,1]
	v_pk_add_f32 v[230:231], v[200:201], v[228:229]
	v_pk_add_f32 v[200:201], v[200:201], v[228:229] neg_lo:[0,1] neg_hi:[0,1]
	ds_write2_b64 v181, v[210:211], v[226:227] offset1:17
	ds_write2_b64 v181, v[222:223], v[202:203] offset0:34 offset1:51
	ds_write2_b64 v181, v[220:221], v[248:249] offset0:68 offset1:85
	ds_write2_b64 v181, v[242:243], v[230:231] offset0:102 offset1:119
	ds_write2_b64 v181, v[216:217], v[214:215] offset0:136 offset1:153
	ds_write2_b64 v181, v[208:209], v[204:205] offset0:170 offset1:187
	ds_write2_b64 v181, v[212:213], v[218:219] offset0:204 offset1:221
	ds_write2_b64 v181, v[206:207], v[200:201] offset0:238 offset1:255
.LBB0_378:
	s_or_b64 exec, exec, s[2:3]
	v_mov_b32_e32 v200, v180
	s_waitcnt lgkmcnt(0)
	s_barrier
	s_nop 0
	v_cmp_gt_i32_e32 vcc, s56, v200
	s_and_saveexec_b64 s[2:3], vcc
	s_cbranch_execz .LBB0_380
	v_ashrrev_i32_e32 v181, 31, v200
	v_add_u32_sdwa v181, v200, v181 dst_sel:DWORD dst_unused:UNUSED_PAD src0_sel:DWORD src1_sel:BYTE_3
	v_ashrrev_i32_e32 v181, 8, v181
	v_mul_i32_i24_e32 v201, 0x100, v181
	v_sub_u32_e32 v200, v200, v201
	v_mul_i32_i24_e32 v181, 0x1100, v181
	v_lshlrev_b32_e32 v181, 3, v181
	v_lshlrev_b32_e32 v224, 3, v200
	v_ashrrev_i32_e32 v200, 4, v200
	v_add_u32_e32 v201, s57, v181
	v_lshlrev_b32_e32 v237, 3, v200
	v_add3_u32 v238, v201, v224, v237
	v_add_u32_e32 v252, 0, v224
	ds_read_b64 v[200:201], v238
	ds_read_b64 v[202:203], v238 offset:2176
	ds_read_b64 v[204:205], v238 offset:4352
	ds_read_b64 v[206:207], v238 offset:6528
	ds_read_b64 v[208:209], v238 offset:8704
	ds_read_b64 v[210:211], v238 offset:10880
	ds_read_b64 v[212:213], v238 offset:13056
	ds_read_b64 v[214:215], v238 offset:15232
	ds_read_b64 v[216:217], v238 offset:17408
	ds_read_b64 v[218:219], v238 offset:19584
	ds_read_b64 v[220:221], v238 offset:21760
	ds_read_b64 v[222:223], v238 offset:23936
	ds_read_b64 v[224:225], v252
	ds_read_b64 v[226:227], v238 offset:26112
	ds_read_b64 v[228:229], v238 offset:28288
	ds_read_b64 v[230:231], v238 offset:30464
	ds_read_b64 v[238:239], v238 offset:32640
	s_waitcnt lgkmcnt(4)
	v_pk_mul_f32 v[244:245], v[202:203], v[224:225] op_sel:[0,1]
	v_xor_b32_e32 v242, 0x80000000, v225
	v_pk_fma_f32 v[246:247], v[202:203], v[224:225], v[244:245] op_sel:[0,0,1] op_sel_hi:[1,0,0] neg_hi:[0,0,1]
	v_mov_b32_e32 v243, v224
	v_pk_mul_f32 v[202:203], v[224:225], v[224:225] op_sel:[1,0]
	s_mov_b32 s35, s60
	v_pk_fma_f32 v[202:203], v[224:225], v[242:243], v[202:203] op_sel_hi:[0,1,1] neg_lo:[0,0,1] neg_hi:[0,0,1]
	v_pk_mul_f32 v[242:243], v[204:205], v[202:203] op_sel:[1,0] op_sel_hi:[0,0]
	v_pk_fma_f32 v[244:245], v[204:205], v[202:203], v[242:243] op_sel:[0,1,0] neg_lo:[0,0,1]
	v_add3_u32 v181, v252, v181, v237
	v_pk_mul_f32 v[204:205], v[224:225], v[202:203] op_sel:[0,1] op_sel_hi:[1,0]
	v_pk_mul_f32 v[202:203], v[224:225], v[202:203]
	v_pk_add_f32 v[204:205], v[204:205], v[204:205] op_sel:[0,1] op_sel_hi:[0,1]
	v_pk_add_f32 v[202:203], v[202:203], v[202:203] op_sel:[0,1] op_sel_hi:[0,1] neg_lo:[0,1] neg_hi:[0,1]
	v_pk_mul_f32 v[242:243], v[206:207], v[202:203]
	s_nop 0
	v_pk_fma_f32 v[248:249], v[206:207], v[204:205], v[242:243] op_sel:[0,0,1] op_sel_hi:[1,1,0] neg_lo:[0,0,1]
	v_pk_mul_f32 v[204:205], v[224:225], v[204:205]
	v_pk_fma_f32 v[206:207], v[224:225], v[202:203], v[204:205] op_sel:[0,0,1] op_sel_hi:[1,1,0] neg_lo:[0,0,1] neg_hi:[0,0,1]
	v_pk_fma_f32 v[202:203], v[224:225], v[202:203], v[204:205] op_sel:[0,0,1] op_sel_hi:[1,1,0]
	v_mov_b32_e32 v204, v206
	v_mov_b32_e32 v205, v203
	v_pk_mul_f32 v[242:243], v[208:209], v[206:207] op_sel:[1,0] op_sel_hi:[0,0]
	v_pk_mov_b32 v[206:207], v[202:203], v[206:207] op_sel:[1,0]
	v_pk_fma_f32 v[250:251], v[208:209], v[202:203], v[242:243] op_sel:[0,1,0] neg_lo:[0,0,1]
	v_pk_mul_f32 v[204:205], v[224:225], v[204:205]
	v_pk_mul_f32 v[202:203], v[224:225], v[206:207]
	v_pk_add_f32 v[204:205], v[204:205], v[204:205] op_sel:[0,1] op_sel_hi:[0,1] neg_lo:[0,1] neg_hi:[0,1]
	v_pk_mul_f32 v[206:207], v[210:211], v[204:205]
	v_pk_add_f32 v[202:203], v[202:203], v[202:203] op_sel:[0,1] op_sel_hi:[0,1]
	v_pk_fma_f32 v[208:209], v[210:211], v[202:203], v[206:207] op_sel:[0,0,1] op_sel_hi:[1,1,0] neg_lo:[0,0,1]
	v_pk_mul_f32 v[202:203], v[224:225], v[202:203]
	v_pk_fma_f32 v[206:207], v[224:225], v[204:205], v[202:203] op_sel:[0,0,1] op_sel_hi:[1,1,0] neg_lo:[0,0,1] neg_hi:[0,0,1]
	v_pk_fma_f32 v[202:203], v[224:225], v[204:205], v[202:203] op_sel:[0,0,1] op_sel_hi:[1,1,0]
	v_mov_b32_e32 v204, v206
	v_mov_b32_e32 v205, v203
	v_pk_mul_f32 v[210:211], v[212:213], v[206:207] op_sel:[1,0] op_sel_hi:[0,0]
	v_pk_mov_b32 v[206:207], v[202:203], v[206:207] op_sel:[1,0]
	v_pk_fma_f32 v[242:243], v[212:213], v[202:203], v[210:211] op_sel:[0,1,0] neg_lo:[0,0,1]
	v_pk_mul_f32 v[204:205], v[224:225], v[204:205]
	v_pk_mul_f32 v[202:203], v[224:225], v[206:207]
	v_pk_add_f32 v[204:205], v[204:205], v[204:205] op_sel:[0,1] op_sel_hi:[0,1] neg_lo:[0,1] neg_hi:[0,1]
	v_pk_mul_f32 v[206:207], v[214:215], v[204:205]
	v_pk_add_f32 v[202:203], v[202:203], v[202:203] op_sel:[0,1] op_sel_hi:[0,1]
	v_pk_fma_f32 v[210:211], v[214:215], v[202:203], v[206:207] op_sel:[0,0,1] op_sel_hi:[1,1,0] neg_lo:[0,0,1]
	v_pk_mul_f32 v[202:203], v[224:225], v[202:203]
	v_pk_fma_f32 v[206:207], v[224:225], v[204:205], v[202:203] op_sel:[0,0,1] op_sel_hi:[1,1,0] neg_lo:[0,0,1] neg_hi:[0,0,1]
	v_pk_fma_f32 v[202:203], v[224:225], v[204:205], v[202:203] op_sel:[0,0,1] op_sel_hi:[1,1,0]
	v_mov_b32_e32 v204, v206
	v_mov_b32_e32 v205, v203
	v_pk_mul_f32 v[212:213], v[216:217], v[206:207] op_sel:[1,0] op_sel_hi:[0,0]
	v_pk_mov_b32 v[206:207], v[202:203], v[206:207] op_sel:[1,0]
	v_pk_fma_f32 v[214:215], v[216:217], v[202:203], v[212:213] op_sel:[0,1,0] neg_lo:[0,0,1]
	v_pk_mul_f32 v[204:205], v[224:225], v[204:205]
	v_pk_mul_f32 v[202:203], v[224:225], v[206:207]
	v_pk_add_f32 v[204:205], v[204:205], v[204:205] op_sel:[0,1] op_sel_hi:[0,1] neg_lo:[0,1] neg_hi:[0,1]
	v_pk_mul_f32 v[206:207], v[218:219], v[204:205]
	v_pk_add_f32 v[202:203], v[202:203], v[202:203] op_sel:[0,1] op_sel_hi:[0,1]
	v_pk_fma_f32 v[212:213], v[218:219], v[202:203], v[206:207] op_sel:[0,0,1] op_sel_hi:[1,1,0] neg_lo:[0,0,1]
	v_pk_mul_f32 v[202:203], v[224:225], v[202:203]
	v_pk_fma_f32 v[206:207], v[224:225], v[204:205], v[202:203] op_sel:[0,0,1] op_sel_hi:[1,1,0] neg_lo:[0,0,1] neg_hi:[0,0,1]
	v_pk_fma_f32 v[202:203], v[224:225], v[204:205], v[202:203] op_sel:[0,0,1] op_sel_hi:[1,1,0]
	v_mov_b32_e32 v204, v206
	v_mov_b32_e32 v205, v203
	v_pk_mul_f32 v[216:217], v[220:221], v[206:207] op_sel:[1,0] op_sel_hi:[0,0]
	v_pk_mov_b32 v[206:207], v[202:203], v[206:207] op_sel:[1,0]
	v_pk_fma_f32 v[218:219], v[220:221], v[202:203], v[216:217] op_sel:[0,1,0] neg_lo:[0,0,1]
	v_pk_mul_f32 v[204:205], v[224:225], v[204:205]
	v_pk_mul_f32 v[202:203], v[224:225], v[206:207]
	v_pk_add_f32 v[204:205], v[204:205], v[204:205] op_sel:[0,1] op_sel_hi:[0,1] neg_lo:[0,1] neg_hi:[0,1]
	v_pk_mul_f32 v[206:207], v[222:223], v[204:205]
	v_pk_add_f32 v[202:203], v[202:203], v[202:203] op_sel:[0,1] op_sel_hi:[0,1]
	v_pk_fma_f32 v[216:217], v[222:223], v[202:203], v[206:207] op_sel:[0,0,1] op_sel_hi:[1,1,0] neg_lo:[0,0,1]
	v_pk_mul_f32 v[202:203], v[224:225], v[202:203]
	v_pk_fma_f32 v[206:207], v[224:225], v[204:205], v[202:203] op_sel:[0,0,1] op_sel_hi:[1,1,0] neg_lo:[0,0,1] neg_hi:[0,0,1]
	v_pk_fma_f32 v[202:203], v[224:225], v[204:205], v[202:203] op_sel:[0,0,1] op_sel_hi:[1,1,0]
	v_mov_b32_e32 v204, v206
	v_mov_b32_e32 v205, v203
	s_waitcnt lgkmcnt(3)
	v_pk_mul_f32 v[220:221], v[226:227], v[206:207] op_sel:[1,0] op_sel_hi:[0,0]
	v_pk_mov_b32 v[206:207], v[202:203], v[206:207] op_sel:[1,0]
	v_pk_fma_f32 v[222:223], v[226:227], v[202:203], v[220:221] op_sel:[0,1,0] neg_lo:[0,0,1]
	v_pk_mul_f32 v[204:205], v[224:225], v[204:205]
	v_pk_mul_f32 v[202:203], v[224:225], v[206:207]
	v_pk_add_f32 v[204:205], v[204:205], v[204:205] op_sel:[0,1] op_sel_hi:[0,1] neg_lo:[0,1] neg_hi:[0,1]
	s_waitcnt lgkmcnt(2)
	v_pk_mul_f32 v[206:207], v[228:229], v[204:205]
	v_pk_add_f32 v[202:203], v[202:203], v[202:203] op_sel:[0,1] op_sel_hi:[0,1]
	v_pk_fma_f32 v[220:221], v[228:229], v[202:203], v[206:207] op_sel:[0,0,1] op_sel_hi:[1,1,0] neg_lo:[0,0,1]
	v_pk_mul_f32 v[202:203], v[224:225], v[202:203]
	v_pk_fma_f32 v[206:207], v[224:225], v[204:205], v[202:203] op_sel:[0,0,1] op_sel_hi:[1,1,0] neg_lo:[0,0,1] neg_hi:[0,0,1]
	v_pk_fma_f32 v[202:203], v[224:225], v[204:205], v[202:203] op_sel:[0,0,1] op_sel_hi:[1,1,0]
	v_mov_b32_e32 v204, v206
	v_mov_b32_e32 v205, v203
	s_waitcnt lgkmcnt(1)
	v_pk_mul_f32 v[226:227], v[230:231], v[206:207] op_sel:[1,0] op_sel_hi:[0,0]
	v_pk_mov_b32 v[206:207], v[202:203], v[206:207] op_sel:[1,0]
	v_pk_fma_f32 v[228:229], v[230:231], v[202:203], v[226:227] op_sel:[0,1,0] neg_lo:[0,0,1]
	v_pk_mul_f32 v[204:205], v[224:225], v[204:205]
	v_pk_mul_f32 v[202:203], v[224:225], v[206:207]
	v_pk_add_f32 v[204:205], v[204:205], v[204:205] op_sel:[0,1] op_sel_hi:[0,1] neg_lo:[0,1] neg_hi:[0,1]
	s_waitcnt lgkmcnt(0)
	v_pk_mul_f32 v[204:205], v[238:239], v[204:205] op_sel:[1,0] op_sel_hi:[0,1]
	v_pk_add_f32 v[202:203], v[202:203], v[202:203] op_sel:[0,1] op_sel_hi:[0,1]
	v_pk_fma_f32 v[206:207], v[238:239], v[202:203], v[204:205] neg_lo:[0,0,1]
	v_pk_add_f32 v[204:205], v[250:251], v[222:223]
	v_pk_add_f32 v[202:203], v[200:201], v[214:215]
	v_pk_add_f32 v[200:201], v[200:201], v[214:215] neg_lo:[0,1] neg_hi:[0,1]
	v_pk_add_f32 v[214:215], v[250:251], v[222:223] neg_lo:[0,1] neg_hi:[0,1]
	s_nop 0
	v_xor_b32_e32 v222, 0x80000000, v215
	v_mov_b32_e32 v223, v214
	v_pk_add_f32 v[214:215], v[202:203], v[204:205]
	v_pk_add_f32 v[224:225], v[200:201], v[222:223]
	v_pk_add_f32 v[202:203], v[202:203], v[204:205] neg_lo:[0,1] neg_hi:[0,1]
	v_pk_add_f32 v[200:201], v[200:201], v[222:223] neg_lo:[0,1] neg_hi:[0,1]
	v_pk_add_f32 v[204:205], v[246:247], v[212:213]
	v_pk_add_f32 v[222:223], v[208:209], v[220:221]
	v_pk_add_f32 v[208:209], v[208:209], v[220:221] neg_lo:[0,1] neg_hi:[0,1]
	v_pk_add_f32 v[212:213], v[246:247], v[212:213] neg_lo:[0,1] neg_hi:[0,1]
	v_xor_b32_e32 v220, 0x80000000, v209
	v_mov_b32_e32 v221, v208
	v_pk_add_f32 v[208:209], v[204:205], v[222:223]
	v_pk_add_f32 v[204:205], v[204:205], v[222:223] neg_lo:[0,1] neg_hi:[0,1]
	v_pk_add_f32 v[222:223], v[242:243], v[228:229]
	v_pk_add_f32 v[228:229], v[242:243], v[228:229] neg_lo:[0,1] neg_hi:[0,1]
	v_pk_add_f32 v[226:227], v[212:213], v[220:221]
	v_pk_add_f32 v[212:213], v[212:213], v[220:221] neg_lo:[0,1] neg_hi:[0,1]
	v_pk_add_f32 v[220:221], v[244:245], v[218:219]
	v_pk_add_f32 v[218:219], v[244:245], v[218:219] neg_lo:[0,1] neg_hi:[0,1]
	v_xor_b32_e32 v230, 0x80000000, v229
	v_mov_b32_e32 v231, v228
	v_pk_add_f32 v[238:239], v[218:219], v[230:231]
	v_pk_add_f32 v[218:219], v[218:219], v[230:231] neg_lo:[0,1] neg_hi:[0,1]
	v_pk_add_f32 v[230:231], v[210:211], v[206:207]
	v_pk_add_f32 v[206:207], v[210:211], v[206:207] neg_lo:[0,1] neg_hi:[0,1]
	v_pk_add_f32 v[228:229], v[220:221], v[222:223]
	v_pk_add_f32 v[220:221], v[220:221], v[222:223] neg_lo:[0,1] neg_hi:[0,1]
	v_pk_add_f32 v[222:223], v[248:249], v[216:217]
	v_pk_add_f32 v[216:217], v[248:249], v[216:217] neg_lo:[0,1] neg_hi:[0,1]
	v_xor_b32_e32 v210, 0x80000000, v207
	v_mov_b32_e32 v211, v206
	v_pk_add_f32 v[242:243], v[216:217], v[210:211]
	v_pk_add_f32 v[210:211], v[216:217], v[210:211] neg_lo:[0,1] neg_hi:[0,1]
	v_pk_mul_f32 v[216:217], v[226:227], s[24:25] op_sel_hi:[1,0]
	v_pk_add_f32 v[206:207], v[222:223], v[230:231]
	v_pk_add_f32 v[222:223], v[222:223], v[230:231] neg_lo:[0,1] neg_hi:[0,1]
	v_pk_fma_f32 v[230:231], v[226:227], s[26:27], v[216:217] op_sel:[0,0,1] op_sel_hi:[1,0,0] neg_lo:[0,0,1]
	s_nop 0
	v_pk_mul_f32 v[216:217], v[204:205], s[28:29] op_sel_hi:[1,0]
	s_nop 0
	v_pk_fma_f32 v[226:227], v[204:205], s[28:29], v[216:217] op_sel:[0,0,1] op_sel_hi:[1,0,0] neg_lo:[0,0,1]
	v_pk_mul_f32 v[216:217], v[212:213], s[26:27] op_sel_hi:[1,0]
	v_pk_fma_f32 v[244:245], v[212:213], s[24:25], v[216:217] op_sel:[0,0,1] op_sel_hi:[1,0,0] neg_lo:[0,0,1]
	s_nop 0
	v_pk_mul_f32 v[212:213], v[238:239], s[28:29] op_sel_hi:[1,0]
	s_nop 0
	v_pk_fma_f32 v[216:217], v[238:239], s[28:29], v[212:213] op_sel:[0,0,1] op_sel_hi:[1,0,0] neg_lo:[0,0,1]
	s_nop 0
	v_pk_fma_f32 v[212:213], v[220:221], 0, v[220:221] op_sel:[0,0,1] op_sel_hi:[1,0,0] neg_lo:[0,0,1]
	s_nop 0
	v_pk_mul_f32 v[220:221], v[218:219], s[30:31] op_sel_hi:[1,0]
	s_nop 0
	v_pk_fma_f32 v[238:239], v[218:219], s[30:31], v[220:221] op_sel:[0,0,1] op_sel_hi:[1,0,0] neg_hi:[0,0,1]
	v_pk_mul_f32 v[220:221], v[242:243], s[26:27] op_sel_hi:[1,0]
	v_pk_fma_f32 v[246:247], v[242:243], s[24:25], v[220:221] op_sel:[0,0,1] op_sel_hi:[1,0,0] neg_lo:[0,0,1]
	s_mov_b32 s25, s34
	v_pk_mul_f32 v[220:221], v[222:223], s[30:31] op_sel_hi:[1,0]
	v_pk_add_f32 v[218:219], v[200:201], v[238:239]
	v_pk_fma_f32 v[242:243], v[222:223], s[30:31], v[220:221] op_sel:[0,0,1] op_sel_hi:[1,0,0] neg_hi:[0,0,1]
	v_pk_add_f32 v[222:223], v[208:209], v[206:207]
	v_pk_mul_f32 v[220:221], v[210:211], s[34:35] op_sel_hi:[0,1]
	v_pk_add_f32 v[206:207], v[208:209], v[206:207] neg_lo:[0,1] neg_hi:[0,1]
	v_pk_fma_f32 v[210:211], v[210:211], s[24:25], v[220:221] op_sel:[1,0,0]
	v_pk_add_f32 v[220:221], v[214:215], v[228:229]
	v_pk_add_f32 v[214:215], v[214:215], v[228:229] neg_lo:[0,1] neg_hi:[0,1]
	v_xor_b32_e32 v208, 0x80000000, v207
	v_mov_b32_e32 v209, v206
	v_pk_add_f32 v[206:207], v[220:221], v[222:223]
	v_pk_add_f32 v[228:229], v[214:215], v[208:209]
	v_pk_add_f32 v[220:221], v[220:221], v[222:223] neg_lo:[0,1] neg_hi:[0,1]
	v_pk_add_f32 v[208:209], v[214:215], v[208:209] neg_lo:[0,1] neg_hi:[0,1]
	v_pk_add_f32 v[214:215], v[224:225], v[216:217]
	v_pk_add_f32 v[216:217], v[224:225], v[216:217] neg_lo:[0,1] neg_hi:[0,1]
	v_pk_add_f32 v[222:223], v[230:231], v[246:247]
	v_pk_add_f32 v[224:225], v[230:231], v[246:247] neg_lo:[0,1] neg_hi:[0,1]
	v_pk_add_f32 v[204:205], v[226:227], v[242:243]
	v_xor_b32_e32 v230, 0x80000000, v225
	v_mov_b32_e32 v231, v224
	v_pk_add_f32 v[224:225], v[214:215], v[222:223]
	v_pk_add_f32 v[214:215], v[214:215], v[222:223] neg_lo:[0,1] neg_hi:[0,1]
	v_pk_add_f32 v[222:223], v[202:203], v[212:213]
	v_pk_add_f32 v[202:203], v[202:203], v[212:213] neg_lo:[0,1] neg_hi:[0,1]
	v_pk_add_f32 v[212:213], v[226:227], v[242:243] neg_lo:[0,1] neg_hi:[0,1]
	v_pk_add_f32 v[246:247], v[216:217], v[230:231]
	v_xor_b32_e32 v226, 0x80000000, v213
	v_mov_b32_e32 v227, v212
	v_pk_add_f32 v[212:213], v[222:223], v[204:205]
	v_pk_add_f32 v[204:205], v[222:223], v[204:205] neg_lo:[0,1] neg_hi:[0,1]
	v_pk_add_f32 v[222:223], v[244:245], v[210:211]
	v_pk_add_f32 v[210:211], v[244:245], v[210:211] neg_lo:[0,1] neg_hi:[0,1]
	v_pk_add_f32 v[216:217], v[216:217], v[230:231] neg_lo:[0,1] neg_hi:[0,1]
	v_pk_add_f32 v[230:231], v[202:203], v[226:227]
	v_pk_add_f32 v[202:203], v[202:203], v[226:227] neg_lo:[0,1] neg_hi:[0,1]
	v_pk_add_f32 v[200:201], v[200:201], v[238:239] neg_lo:[0,1] neg_hi:[0,1]
	v_xor_b32_e32 v226, 0x80000000, v211
	v_mov_b32_e32 v227, v210
	v_pk_add_f32 v[210:211], v[218:219], v[222:223]
	v_pk_add_f32 v[238:239], v[200:201], v[226:227]
	v_pk_add_f32 v[218:219], v[218:219], v[222:223] neg_lo:[0,1] neg_hi:[0,1]
	v_pk_add_f32 v[200:201], v[200:201], v[226:227] neg_lo:[0,1] neg_hi:[0,1]
	ds_write_b64 v181, v[206:207] offset:6272
	ds_write_b64 v181, v[224:225] offset:8448
	ds_write_b64 v181, v[212:213] offset:10624
	ds_write_b64 v181, v[210:211] offset:12800
	ds_write_b64 v181, v[228:229] offset:14976
	ds_write_b64 v181, v[246:247] offset:17152
	ds_write_b64 v181, v[230:231] offset:19328
	ds_write_b64 v181, v[238:239] offset:21504
	ds_write_b64 v181, v[220:221] offset:23680
	ds_write_b64 v181, v[214:215] offset:25856
	ds_write_b64 v181, v[204:205] offset:28032
	ds_write_b64 v181, v[218:219] offset:30208
	ds_write_b64 v181, v[208:209] offset:32384
	ds_write_b64 v181, v[216:217] offset:34560
	ds_write_b64 v181, v[202:203] offset:36736
	ds_write_b64 v181, v[200:201] offset:38912

.LBB0_431:
	s_or_b64 exec, exec, s[2:3]
	v_mov_b32_e32 v8, v180
	s_waitcnt lgkmcnt(0)
	s_barrier
	s_add_u32 s2, s0, s62
	v_ashrrev_i32_e32 v0, 31, v8
	v_add_u32_sdwa v0, v8, v0 dst_sel:DWORD dst_unused:UNUSED_PAD src0_sel:DWORD src1_sel:BYTE_3
	v_ashrrev_i32_e32 v0, 8, v0
	v_mul_i32_i24_e32 v1, 0x100, v0
	v_sub_u32_e32 v10, v8, v1
	v_mul_i32_i24_e32 v46, 0x220, v0
	v_add_u32_e32 v0, 0x100, v10
	v_lshrrev_b32_e32 v47, 4, v0
	v_add3_u32 v0, v46, v0, v47
	v_ashrrev_i32_e32 v4, 4, v10
	v_lshl_add_u32 v0, v0, 3, s18
	v_lshl_add_u32 v2, v10, 3, 0
	ds_read_b64 v[0:1], v0
	ds_read_b64 v[2:3], v2 offset:4224
	v_add_u32_e32 v4, v4, v10
	v_add_lshl_u32 v48, v4, v46, 3
	v_add_u32_e32 v4, s18, v48
	ds_read_b64 v[4:5], v4
	s_waitcnt lgkmcnt(1)
	v_pk_mul_f32 v[6:7], v[0:1], v[2:3] op_sel:[1,1] op_sel_hi:[0,1]
	v_pk_fma_f32 v[44:45], v[0:1], v[2:3], v[6:7] op_sel_hi:[1,0,1] neg_hi:[0,0,1]
	v_add_u32_e32 v2, 0, v48
	s_waitcnt lgkmcnt(0)
	v_pk_add_f32 v[0:1], v[4:5], v[44:45]
	ds_write_b64 v2, v[0:1] offset:6272
	v_add3_u32 v2, v46, v10, v47
	v_pk_add_f32 v[0:1], v[4:5], v[44:45] neg_lo:[0,1] neg_hi:[0,1]
	v_lshl_add_u32 v2, v2, 3, 0
	ds_write_b64 v2, v[0:1] offset:8320
	v_add_u32_e32 v0, 0x200, v8
	v_ashrrev_i32_e32 v1, 31, v0
	v_add_u32_sdwa v1, v0, v1 dst_sel:DWORD dst_unused:UNUSED_PAD src0_sel:DWORD src1_sel:BYTE_3
	v_ashrrev_i32_e32 v1, 8, v1
	v_mul_i32_i24_e32 v2, 0x100, v1
	v_sub_u32_e32 v10, v0, v2
	v_add_u32_e32 v0, 0x100, v10
	v_mul_i32_i24_e32 v46, 0x220, v1
	v_lshrrev_b32_e32 v47, 4, v0
	v_add3_u32 v0, v46, v0, v47
	v_ashrrev_i32_e32 v4, 4, v10
	v_lshl_add_u32 v0, v0, 3, s18
	v_lshl_add_u32 v2, v10, 3, 0
	ds_read_b64 v[0:1], v0
	ds_read_b64 v[2:3], v2 offset:4224
	v_add_u32_e32 v4, v4, v10
	v_add_lshl_u32 v48, v4, v46, 3
	v_add_u32_e32 v4, s18, v48
	ds_read_b64 v[4:5], v4
	s_waitcnt lgkmcnt(1)
	v_pk_mul_f32 v[6:7], v[0:1], v[2:3] op_sel:[1,1] op_sel_hi:[0,1]
	v_pk_fma_f32 v[44:45], v[0:1], v[2:3], v[6:7] op_sel_hi:[1,0,1] neg_hi:[0,0,1]
	v_add_u32_e32 v2, 0, v48
	s_waitcnt lgkmcnt(0)
	v_pk_add_f32 v[0:1], v[4:5], v[44:45]
	ds_write_b64 v2, v[0:1] offset:6272
	v_add3_u32 v2, v46, v10, v47
	v_pk_add_f32 v[0:1], v[4:5], v[44:45] neg_lo:[0,1] neg_hi:[0,1]
	v_lshl_add_u32 v2, v2, 3, 0
	ds_write_b64 v2, v[0:1] offset:8320
	v_add_u32_e32 v0, 0x400, v8
	v_ashrrev_i32_e32 v1, 31, v0
	v_add_u32_sdwa v1, v0, v1 dst_sel:DWORD dst_unused:UNUSED_PAD src0_sel:DWORD src1_sel:BYTE_3
	v_ashrrev_i32_e32 v1, 8, v1
	v_mul_i32_i24_e32 v2, 0x100, v1
	v_sub_u32_e32 v10, v0, v2
	v_add_u32_e32 v0, 0x100, v10
	v_mul_i32_i24_e32 v46, 0x220, v1
	v_lshrrev_b32_e32 v47, 4, v0
	v_add3_u32 v0, v46, v0, v47
	v_ashrrev_i32_e32 v4, 4, v10
	v_lshl_add_u32 v0, v0, 3, s18
	v_lshl_add_u32 v2, v10, 3, 0
	ds_read_b64 v[0:1], v0
	ds_read_b64 v[2:3], v2 offset:4224
	v_add_u32_e32 v4, v4, v10
	v_add_lshl_u32 v48, v4, v46, 3
	v_add_u32_e32 v4, s18, v48
	ds_read_b64 v[4:5], v4
	s_waitcnt lgkmcnt(1)
	v_pk_mul_f32 v[6:7], v[0:1], v[2:3] op_sel:[1,1] op_sel_hi:[0,1]
	v_pk_fma_f32 v[44:45], v[0:1], v[2:3], v[6:7] op_sel_hi:[1,0,1] neg_hi:[0,0,1]
	v_add_u32_e32 v2, 0, v48
	s_waitcnt lgkmcnt(0)
	v_pk_add_f32 v[0:1], v[4:5], v[44:45]
	ds_write_b64 v2, v[0:1] offset:6272
	v_add3_u32 v2, v46, v10, v47
	v_pk_add_f32 v[0:1], v[4:5], v[44:45] neg_lo:[0,1] neg_hi:[0,1]
	v_lshl_add_u32 v2, v2, 3, 0
	ds_write_b64 v2, v[0:1] offset:8320
	v_add_u32_e32 v0, 0x600, v8
	v_ashrrev_i32_e32 v1, 31, v0
	v_add_u32_sdwa v1, v0, v1 dst_sel:DWORD dst_unused:UNUSED_PAD src0_sel:DWORD src1_sel:BYTE_3
	v_ashrrev_i32_e32 v1, 8, v1
	v_mul_i32_i24_e32 v2, 0x100, v1
	v_sub_u32_e32 v10, v0, v2
	v_add_u32_e32 v0, 0x100, v10
	v_mul_i32_i24_e32 v46, 0x220, v1
	v_lshrrev_b32_e32 v47, 4, v0
	v_add3_u32 v0, v46, v0, v47
	v_ashrrev_i32_e32 v4, 4, v10
	v_lshl_add_u32 v0, v0, 3, s18
	v_lshl_add_u32 v2, v10, 3, 0
	ds_read_b64 v[0:1], v0
	ds_read_b64 v[2:3], v2 offset:4224
	v_add_u32_e32 v4, v4, v10
	v_add_lshl_u32 v48, v4, v46, 3
	v_add_u32_e32 v4, s18, v48
	ds_read_b64 v[4:5], v4
	s_waitcnt lgkmcnt(1)
	v_pk_mul_f32 v[6:7], v[0:1], v[2:3] op_sel:[1,1] op_sel_hi:[0,1]
	v_pk_fma_f32 v[44:45], v[0:1], v[2:3], v[6:7] op_sel_hi:[1,0,1] neg_hi:[0,0,1]
	v_add_u32_e32 v2, 0, v48
	s_waitcnt lgkmcnt(0)
	v_pk_add_f32 v[0:1], v[4:5], v[44:45]
	ds_write_b64 v2, v[0:1] offset:6272
	v_add3_u32 v2, v46, v10, v47
	v_pk_add_f32 v[0:1], v[4:5], v[44:45] neg_lo:[0,1] neg_hi:[0,1]
	v_lshl_add_u32 v2, v2, 3, 0
	ds_write_b64 v2, v[0:1] offset:8320
	v_add_u32_e32 v0, 0x800, v8
	v_ashrrev_i32_e32 v1, 31, v0
	v_add_u32_sdwa v1, v0, v1 dst_sel:DWORD dst_unused:UNUSED_PAD src0_sel:DWORD src1_sel:BYTE_3
	v_ashrrev_i32_e32 v1, 8, v1
	v_mul_i32_i24_e32 v2, 0x100, v1
	v_sub_u32_e32 v10, v0, v2
	v_add_u32_e32 v0, 0x100, v10
	v_mul_i32_i24_e32 v46, 0x220, v1
	v_lshrrev_b32_e32 v47, 4, v0
	v_add3_u32 v0, v46, v0, v47
	v_ashrrev_i32_e32 v4, 4, v10
	v_lshl_add_u32 v0, v0, 3, s18
	v_lshl_add_u32 v2, v10, 3, 0
	ds_read_b64 v[0:1], v0
	ds_read_b64 v[2:3], v2 offset:4224
	v_add_u32_e32 v4, v4, v10
	v_add_lshl_u32 v48, v4, v46, 3
	v_add_u32_e32 v4, s18, v48
	ds_read_b64 v[4:5], v4
	s_waitcnt lgkmcnt(1)
	v_pk_mul_f32 v[6:7], v[0:1], v[2:3] op_sel:[1,1] op_sel_hi:[0,1]
	v_pk_fma_f32 v[44:45], v[0:1], v[2:3], v[6:7] op_sel_hi:[1,0,1] neg_hi:[0,0,1]
	v_add_u32_e32 v2, 0, v48
	s_waitcnt lgkmcnt(0)
	v_pk_add_f32 v[0:1], v[4:5], v[44:45]
	ds_write_b64 v2, v[0:1] offset:6272
	v_add3_u32 v2, v46, v10, v47
	v_pk_add_f32 v[0:1], v[4:5], v[44:45] neg_lo:[0,1] neg_hi:[0,1]
	v_lshl_add_u32 v2, v2, 3, 0
	ds_write_b64 v2, v[0:1] offset:8320
	v_add_u32_e32 v0, 0xa00, v8
	v_ashrrev_i32_e32 v1, 31, v0
	v_add_u32_sdwa v1, v0, v1 dst_sel:DWORD dst_unused:UNUSED_PAD src0_sel:DWORD src1_sel:BYTE_3
	v_ashrrev_i32_e32 v1, 8, v1
	v_mul_i32_i24_e32 v2, 0x100, v1
	v_sub_u32_e32 v10, v0, v2
	v_add_u32_e32 v0, 0x100, v10
	v_mul_i32_i24_e32 v46, 0x220, v1
	v_lshrrev_b32_e32 v47, 4, v0
	v_add3_u32 v0, v46, v0, v47
	v_ashrrev_i32_e32 v4, 4, v10
	v_lshl_add_u32 v0, v0, 3, s18
	v_lshl_add_u32 v2, v10, 3, 0
	ds_read_b64 v[0:1], v0
	ds_read_b64 v[2:3], v2 offset:4224
	v_add_u32_e32 v4, v4, v10
	v_add_lshl_u32 v48, v4, v46, 3
	v_add_u32_e32 v4, s18, v48
	ds_read_b64 v[4:5], v4
	s_waitcnt lgkmcnt(1)
	v_pk_mul_f32 v[6:7], v[0:1], v[2:3] op_sel:[1,1] op_sel_hi:[0,1]
	v_pk_fma_f32 v[44:45], v[0:1], v[2:3], v[6:7] op_sel_hi:[1,0,1] neg_hi:[0,0,1]
	v_add_u32_e32 v2, 0, v48
	s_waitcnt lgkmcnt(0)
	v_pk_add_f32 v[0:1], v[4:5], v[44:45]
	ds_write_b64 v2, v[0:1] offset:6272
	v_add3_u32 v2, v46, v10, v47
	v_pk_add_f32 v[0:1], v[4:5], v[44:45] neg_lo:[0,1] neg_hi:[0,1]
	v_lshl_add_u32 v2, v2, 3, 0
	ds_write_b64 v2, v[0:1] offset:8320
	v_add_u32_e32 v0, 0xc00, v8
	v_ashrrev_i32_e32 v1, 31, v0
	v_add_u32_sdwa v1, v0, v1 dst_sel:DWORD dst_unused:UNUSED_PAD src0_sel:DWORD src1_sel:BYTE_3
	v_ashrrev_i32_e32 v1, 8, v1
	v_mul_i32_i24_e32 v2, 0x100, v1
	v_sub_u32_e32 v10, v0, v2
	v_add_u32_e32 v0, 0x100, v10
	v_mul_i32_i24_e32 v46, 0x220, v1
	v_lshrrev_b32_e32 v47, 4, v0
	v_add3_u32 v0, v46, v0, v47
	v_ashrrev_i32_e32 v4, 4, v10
	v_lshl_add_u32 v0, v0, 3, s18
	v_lshl_add_u32 v2, v10, 3, 0
	ds_read_b64 v[0:1], v0
	ds_read_b64 v[2:3], v2 offset:4224
	v_add_u32_e32 v4, v4, v10
	v_add_lshl_u32 v48, v4, v46, 3
	v_add_u32_e32 v4, s18, v48
	ds_read_b64 v[4:5], v4
	s_waitcnt lgkmcnt(1)
	v_pk_mul_f32 v[6:7], v[0:1], v[2:3] op_sel:[1,1] op_sel_hi:[0,1]
	v_pk_fma_f32 v[44:45], v[0:1], v[2:3], v[6:7] op_sel_hi:[1,0,1] neg_hi:[0,0,1]
	v_add_u32_e32 v2, 0, v48
	s_waitcnt lgkmcnt(0)
	v_pk_add_f32 v[0:1], v[4:5], v[44:45]
	ds_write_b64 v2, v[0:1] offset:6272
	v_add3_u32 v2, v46, v10, v47
	v_pk_add_f32 v[0:1], v[4:5], v[44:45] neg_lo:[0,1] neg_hi:[0,1]
	v_lshl_add_u32 v2, v2, 3, 0
	ds_write_b64 v2, v[0:1] offset:8320
	v_add_u32_e32 v0, 0xe00, v8
	v_ashrrev_i32_e32 v1, 31, v0
	v_add_u32_sdwa v1, v0, v1 dst_sel:DWORD dst_unused:UNUSED_PAD src0_sel:DWORD src1_sel:BYTE_3
	v_ashrrev_i32_e32 v1, 8, v1
	v_mul_i32_i24_e32 v2, 0x100, v1
	v_sub_u32_e32 v8, v0, v2
	v_add_u32_e32 v0, 0x100, v8
	v_mul_i32_i24_e32 v10, 0x220, v1
	v_lshrrev_b32_e32 v46, 4, v0
	v_add3_u32 v0, v10, v0, v46
	v_ashrrev_i32_e32 v4, 4, v8
	v_lshl_add_u32 v0, v0, 3, s18
	v_lshl_add_u32 v2, v8, 3, 0
	ds_read_b64 v[0:1], v0
	ds_read_b64 v[2:3], v2 offset:4224
	v_add_u32_e32 v4, v4, v8
	v_add_lshl_u32 v47, v4, v10, 3
	v_add_u32_e32 v4, s18, v47
	ds_read_b64 v[4:5], v4
	s_waitcnt lgkmcnt(1)
	v_pk_mul_f32 v[6:7], v[0:1], v[2:3] op_sel:[1,1] op_sel_hi:[0,1]
	v_pk_fma_f32 v[44:45], v[0:1], v[2:3], v[6:7] op_sel_hi:[1,0,1] neg_hi:[0,0,1]
	v_add_u32_e32 v2, 0, v47
	s_waitcnt lgkmcnt(0)
	v_pk_add_f32 v[0:1], v[4:5], v[44:45]
	ds_write_b64 v2, v[0:1] offset:6272
	v_add3_u32 v2, v10, v8, v46
	v_pk_add_f32 v[0:1], v[4:5], v[44:45] neg_lo:[0,1] neg_hi:[0,1]
	v_lshl_add_u32 v2, v2, 3, 0
	ds_write_b64 v2, v[0:1] offset:8320
	s_waitcnt lgkmcnt(0)
	s_barrier
	ds_read2_b64 v[0:3], v22 offset1:1
	ds_read2_b64 v[4:7], v42 offset1:1
	ds_read2_b64 v[44:47], v27 offset1:1
	ds_read2_b64 v[48:51], v38 offset1:1
	s_waitcnt vmcnt(0)
	v_and_b32_e32 v42, 0xffff0000, v41
	v_pk_mul_f32 v[52:53], v[24:25], v[42:43]
	s_waitcnt lgkmcnt(2)
	v_fma_f32 v8, v23, v87, v7
	v_lshlrev_b32_e32 v7, 16, v41
	v_fma_f32 v22, v26, v7, v52
	v_add_f32_e32 v22, v22, v53
	v_add_f32_e32 v22, v17, v22
	v_fma_f32 v10, v23, v86, v6
	v_and_b32_e32 v6, 0xffff0000, v40
	v_mul_f32_e32 v56, v22, v8
	v_mov_b32_e32 v27, v24
	v_mul_f32_e32 v8, v24, v7
	v_pk_fma_f32 v[52:53], v[26:27], v[6:7], v[8:9] op_sel_hi:[1,1,0]
	v_mov_b32_e32 v22, v25
	v_mov_b32_e32 v43, v85
	v_mov_b32_e32 v53, v5
	v_pk_fma_f32 v[42:43], v[22:23], v[42:43], v[52:53]
	v_and_b32_e32 v38, 0xffff0000, v37
	v_add_f32_e32 v5, v17, v42
	v_pk_mul_f32 v[54:55], v[24:25], v[38:39]
	v_mul_f32_e32 v57, v5, v43
	v_lshlrev_b32_e32 v43, 16, v37
	v_and_b32_e32 v42, 0xffff0000, v36
	v_fma_f32 v5, v26, v43, v54
	v_mul_f32_e32 v8, v24, v43
	v_add_f32_e32 v5, v5, v55
	v_pk_fma_f32 v[52:53], v[26:27], v[42:43], v[8:9] op_sel_hi:[1,1,0]
	v_add_f32_e32 v5, v17, v5
	v_mov_b32_e32 v39, v84
	v_mov_b32_e32 v53, v4
	v_mul_f32_e32 v54, v5, v10
	v_pk_fma_f32 v[4:5], v[22:23], v[38:39], v[52:53]
	v_mul_f32_e32 v8, v24, v6
	v_add_f32_e32 v4, v17, v4
	v_mul_f32_e32 v52, v4, v5
	v_lshlrev_b32_e32 v4, 16, v40
	v_mov_b32_e32 v5, v6
	v_pk_fma_f32 v[38:39], v[26:27], v[4:5], v[8:9] op_sel_hi:[1,1,0]
	v_mov_b32_e32 v40, v7
	v_mov_b32_e32 v41, v91
	v_mov_b32_e32 v39, v3
	v_pk_fma_f32 v[38:39], v[22:23], v[40:41], v[38:39]
	v_lshlrev_b32_e32 v36, 16, v36
	v_add_f32_e32 v3, v17, v38
	v_mov_b32_e32 v37, v42
	v_mul_f32_e32 v8, v24, v42
	v_mul_f32_e32 v53, v3, v39
	v_pk_fma_f32 v[38:39], v[26:27], v[36:37], v[8:9] op_sel_hi:[1,1,0]
	v_pk_mov_b32 v[40:41], v[42:43], v[90:91] op_sel:[1,0]
	v_mov_b32_e32 v39, v2
	v_pk_fma_f32 v[2:3], v[22:23], v[40:41], v[38:39]
	v_mov_b32_e32 v25, v26
	v_add_f32_e32 v2, v17, v2
	v_mul_f32_e32 v27, v2, v3
	v_mov_b32_e32 v5, v34
	v_mul_f32_e32 v2, v26, v34
	v_pk_fma_f32 v[2:3], v[24:25], v[4:5], v[2:3] op_sel_hi:[1,1,0]
	v_mov_b32_e32 v7, v89
	v_mov_b32_e32 v3, v1
	v_pk_fma_f32 v[2:3], v[22:23], v[6:7], v[2:3]
	v_mov_b32_e32 v37, v30
	v_add_f32_e32 v1, v17, v2
	v_mul_f32_e32 v2, v26, v30
	v_mul_f32_e32 v38, v1, v3
	v_pk_fma_f32 v[2:3], v[24:25], v[36:37], v[2:3] op_sel_hi:[1,1,0]
	v_mov_b32_e32 v43, v88
	v_mov_b32_e32 v3, v0
	v_pk_fma_f32 v[0:1], v[22:23], v[42:43], v[2:3]
	v_and_b32_e32 v34, 0xffff0000, v33
	v_add_f32_e32 v0, v17, v0
	v_mul_f32_e32 v26, v0, v1
	v_pk_mul_f32 v[0:1], v[14:15], v[34:35]
	v_lshlrev_b32_e32 v5, 16, v33
	v_fma_f32 v0, v16, v5, v0
	v_add_f32_e32 v0, v0, v1
	s_waitcnt lgkmcnt(0)
	v_fma_f32 v6, v11, v83, v51
	v_add_f32_e32 v0, v177, v0
	v_and_b32_e32 v4, 0xffff0000, v32
	v_mul_f32_e32 v33, v0, v6
	v_mov_b32_e32 v17, v14
	v_mul_f32_e32 v0, v14, v5
	v_pk_fma_f32 v[0:1], v[16:17], v[4:5], v[0:1] op_sel_hi:[1,1,0]
	v_mov_b32_e32 v10, v15
	v_mov_b32_e32 v35, v81
	v_mov_b32_e32 v1, v49
	v_pk_fma_f32 v[0:1], v[10:11], v[34:35], v[0:1]
	v_and_b32_e32 v30, 0xffff0000, v29
	v_add_f32_e32 v0, v177, v0
	v_pk_mul_f32 v[2:3], v[14:15], v[30:31]
	v_mul_f32_e32 v34, v0, v1
	v_lshlrev_b32_e32 v1, 16, v29
	v_fma_f32 v2, v16, v1, v2
	v_add_f32_e32 v2, v2, v3
	v_fma_f32 v7, v11, v82, v50
	v_add_f32_e32 v2, v177, v2
	v_and_b32_e32 v0, 0xffff0000, v28
	v_mul_f32_e32 v29, v2, v7
	v_mul_f32_e32 v2, v14, v1
	v_pk_fma_f32 v[2:3], v[16:17], v[0:1], v[2:3] op_sel_hi:[1,1,0]
	v_mov_b32_e32 v31, v80
	v_mov_b32_e32 v3, v48
	v_pk_fma_f32 v[2:3], v[10:11], v[30:31], v[2:3]
	v_mul_f32_e32 v6, v14, v4
	v_add_f32_e32 v2, v177, v2
	v_mul_f32_e32 v30, v2, v3
	v_lshlrev_b32_e32 v2, 16, v32
	v_mov_b32_e32 v3, v4
	v_pk_fma_f32 v[6:7], v[16:17], v[2:3], v[6:7] op_sel_hi:[1,1,0]
	v_mov_b32_e32 v22, v5
	v_mov_b32_e32 v23, v79
	v_mov_b32_e32 v7, v47
	v_pk_fma_f32 v[6:7], v[10:11], v[22:23], v[6:7]
	v_mul_f32_e32 v8, v14, v0
	v_add_f32_e32 v3, v177, v6
	v_mul_f32_e32 v31, v3, v7
	v_lshlrev_b32_e32 v6, 16, v28
	v_mov_b32_e32 v7, v0
	v_pk_fma_f32 v[22:23], v[16:17], v[6:7], v[8:9] op_sel_hi:[1,1,0]
	v_mov_b32_e32 v15, v16
	v_mov_b32_e32 v3, v179
	v_mul_f32_e32 v8, v16, v179
	v_pk_mov_b32 v[24:25], v[0:1], v[78:79] op_sel:[1,0]
	v_mov_b32_e32 v23, v46
	v_pk_fma_f32 v[2:3], v[14:15], v[2:3], v[8:9] op_sel_hi:[1,1,0]
	v_pk_fma_f32 v[22:23], v[10:11], v[24:25], v[22:23]
	v_mov_b32_e32 v5, v69
	v_mov_b32_e32 v3, v45
	v_add_f32_e32 v1, v177, v22
	v_pk_fma_f32 v[2:3], v[10:11], v[4:5], v[2:3]
	v_mul_f32_e32 v17, v1, v23
	v_add_f32_e32 v1, v177, v2
	v_mov_b32_e32 v7, v178
	v_mul_f32_e32 v2, v16, v178
	v_mul_f32_e32 v8, v1, v3
	v_pk_fma_f32 v[2:3], v[14:15], v[6:7], v[2:3] op_sel_hi:[1,1,0]
	v_mov_b32_e32 v1, v68
	v_mov_b32_e32 v3, v44
	v_pk_fma_f32 v[0:1], v[10:11], v[0:1], v[2:3]
	s_addc_u32 s3, s1, s63
	v_add_f32_e32 v0, v177, v0
	v_lshl_add_u64 v[2:3], s[2:3], 0, v[12:13]
	v_lshlrev_b64 v[4:5], 1, v[18:19]
	v_mul_f32_e32 v0, v0, v1
	v_lshl_add_u64 v[2:3], v[2:3], 0, v[4:5]
	s_barrier
	v_cvt_pk_bf16_f32 v0, v0, v17
	v_cvt_pk_bf16_f32 v1, v30, v29
	global_store_dwordx2 v[2:3], v[0:1], off
	v_lshl_add_u64 v[2:3], s[2:3], 0, v[20:21]
	s_add_u32 s2, s0, s64
	v_lshl_add_u64 v[2:3], v[2:3], 0, v[4:5]
	s_addc_u32 s3, s1, s65
	v_cvt_pk_bf16_f32 v0, v8, v31
	v_cvt_pk_bf16_f32 v1, v34, v33
	global_store_dwordx2 v[2:3], v[0:1], off
	v_lshl_add_u64 v[2:3], s[2:3], 0, v[12:13]
	v_lshl_add_u64 v[2:3], v[2:3], 0, v[4:5]
	v_cvt_pk_bf16_f32 v0, v26, v27
	v_cvt_pk_bf16_f32 v1, v52, v54
	global_store_dwordx2 v[2:3], v[0:1], off
	v_lshl_add_u64 v[2:3], s[2:3], 0, v[20:21]
	v_readlane_b32 s2, v254, 3
	s_add_i32 s60, s60, s2
	s_add_i32 s6, s6, s2
	s_add_i32 s8, s8, s2
	s_add_i32 s10, s10, s2
	v_lshl_add_u64 v[2:3], v[2:3], 0, v[4:5]
	s_cmpk_lt_i32 s60, 0x400
	v_cvt_pk_bf16_f32 v0, v38, v53
	v_cvt_pk_bf16_f32 v1, v57, v56
	v_readlane_b32 s3, v254, 4
	global_store_dwordx2 v[2:3], v[0:1], off
	s_cbranch_scc0 .LBB0_505

.LBB0_485:
	s_or_b64 exec, exec, s[2:3]
	v_mov_b32_e32 v0, v180
	s_waitcnt lgkmcnt(0)
	s_barrier
	s_nop 0
	v_cmp_gt_i32_e32 vcc, s16, v0
	s_and_saveexec_b64 s[2:3], vcc
	s_xor_b64 s[2:3], exec, s[2:3]
	s_cbranch_execz .LBB0_487
	v_ashrrev_i32_e32 v1, 31, v0
	v_lshrrev_b32_e32 v1, 27, v1
	v_add_u32_e32 v1, v0, v1
	v_lshrrev_b32_e32 v2, 5, v1
	v_and_b32_e32 v1, 0xffffffe0, v1
	v_sub_u32_e32 v8, v0, v1
	v_mul_lo_u32 v91, v2, s17
	v_ashrrev_i32_e32 v1, 4, v8
	v_add_u32_e32 v0, 0, v91
	v_lshlrev_b32_e32 v112, 3, v8
	v_lshlrev_b32_e32 v1, 3, v1
	v_add3_u32 v66, v0, v112, v1
	v_add_u32_e32 v58, 0x1800, v66
	v_add_u32_e32 v67, 0x2000, v66
	ds_read2_b64 v[0:3], v58 offset0:16 offset1:50
	ds_read2_b64 v[4:7], v58 offset0:84 offset1:118
	ds_read2_b64 v[54:57], v58 offset0:152 offset1:186
	ds_read2_b64 v[58:61], v58 offset0:220 offset1:254
	ds_read2_b64 v[62:65], v67 offset0:32 offset1:66
	ds_read2_b64 v[70:73], v67 offset0:100 offset1:134
	ds_read2_b64 v[74:77], v67 offset0:168 offset1:202
	v_add_u32_e32 v66, 0x2400, v66
	ds_read2_b64 v[84:87], v66 offset0:108 offset1:142
	s_waitcnt lgkmcnt(3)
	v_pk_add_f32 v[66:67], v[0:1], v[62:63]
	v_pk_add_f32 v[0:1], v[0:1], v[62:63] neg_lo:[0,1] neg_hi:[0,1]
	s_waitcnt lgkmcnt(1)
	v_pk_add_f32 v[62:63], v[54:55], v[74:75]
	v_pk_add_f32 v[54:55], v[54:55], v[74:75] neg_lo:[0,1] neg_hi:[0,1]
	s_mov_b32 s31, s28
	v_xor_b32_e32 v75, 0x80000000, v54
	v_mov_b32_e32 v74, v55
	v_pk_add_f32 v[54:55], v[66:67], v[62:63]
	v_pk_add_f32 v[62:63], v[66:67], v[62:63] neg_lo:[0,1] neg_hi:[0,1]
	v_pk_add_f32 v[66:67], v[2:3], v[64:65]
	v_pk_add_f32 v[2:3], v[2:3], v[64:65] neg_lo:[0,1] neg_hi:[0,1]
	v_pk_add_f32 v[64:65], v[56:57], v[76:77]
	v_pk_add_f32 v[56:57], v[56:57], v[76:77] neg_lo:[0,1] neg_hi:[0,1]
	v_pk_add_f32 v[106:107], v[0:1], v[74:75]
	v_pk_add_f32 v[0:1], v[0:1], v[74:75] neg_lo:[0,1] neg_hi:[0,1]
	v_xor_b32_e32 v75, 0x80000000, v56
	v_mov_b32_e32 v74, v57
	v_pk_add_f32 v[56:57], v[66:67], v[64:65]
	v_pk_add_f32 v[64:65], v[66:67], v[64:65] neg_lo:[0,1] neg_hi:[0,1]
	v_pk_add_f32 v[66:67], v[4:5], v[70:71]
	v_pk_add_f32 v[4:5], v[4:5], v[70:71] neg_lo:[0,1] neg_hi:[0,1]
	s_waitcnt lgkmcnt(0)
	v_pk_add_f32 v[70:71], v[58:59], v[84:85]
	v_pk_add_f32 v[58:59], v[58:59], v[84:85] neg_lo:[0,1] neg_hi:[0,1]
	v_pk_add_f32 v[76:77], v[2:3], v[74:75]
	v_pk_add_f32 v[2:3], v[2:3], v[74:75] neg_lo:[0,1] neg_hi:[0,1]
	v_xor_b32_e32 v75, 0x80000000, v58
	v_mov_b32_e32 v74, v59
	v_pk_add_f32 v[58:59], v[66:67], v[70:71]
	v_pk_add_f32 v[66:67], v[66:67], v[70:71] neg_lo:[0,1] neg_hi:[0,1]
	v_pk_add_f32 v[70:71], v[6:7], v[72:73]
	v_pk_add_f32 v[6:7], v[6:7], v[72:73] neg_lo:[0,1] neg_hi:[0,1]
	v_pk_add_f32 v[72:73], v[60:61], v[86:87]
	v_pk_add_f32 v[60:61], v[60:61], v[86:87] neg_lo:[0,1] neg_hi:[0,1]
	v_pk_add_f32 v[84:85], v[4:5], v[74:75]
	v_pk_add_f32 v[4:5], v[4:5], v[74:75] neg_lo:[0,1] neg_hi:[0,1]
	v_xor_b32_e32 v75, 0x80000000, v60
	v_mov_b32_e32 v74, v61
	v_pk_add_f32 v[60:61], v[70:71], v[72:73]
	v_pk_add_f32 v[70:71], v[70:71], v[72:73] neg_lo:[0,1] neg_hi:[0,1]
	v_pk_mul_f32 v[72:73], v[76:77], s[14:15] op_sel_hi:[1,0]
	v_pk_add_f32 v[86:87], v[6:7], v[74:75]
	v_pk_add_f32 v[6:7], v[6:7], v[74:75] neg_lo:[0,1] neg_hi:[0,1]
	v_pk_fma_f32 v[74:75], v[76:77], s[22:23], v[72:73] op_sel:[0,0,1] op_sel_hi:[1,0,0] neg_hi:[0,0,1]
	s_mov_b32 s29, s14
	v_pk_mul_f32 v[72:73], v[64:65], s[24:25] op_sel_hi:[1,0]
	v_lshlrev_b32_e32 v8, 7, v8
	v_pk_fma_f32 v[76:77], v[64:65], s[24:25], v[72:73] op_sel:[0,0,1] op_sel_hi:[1,0,0] neg_hi:[0,0,1]
	v_pk_mul_f32 v[72:73], v[2:3], s[22:23] op_sel_hi:[1,0]
	v_pk_fma_f32 v[108:109], v[2:3], s[14:15], v[72:73] op_sel:[0,0,1] op_sel_hi:[1,0,0] neg_hi:[0,0,1]
	s_nop 0
	v_pk_mul_f32 v[2:3], v[84:85], s[24:25] op_sel_hi:[1,0]
	s_nop 0
	v_pk_fma_f32 v[72:73], v[84:85], s[24:25], v[2:3] op_sel:[0,0,1] op_sel_hi:[1,0,0] neg_hi:[0,0,1]
	s_nop 0
	v_pk_fma_f32 v[2:3], v[66:67], 0, v[66:67] op_sel:[0,0,1] op_sel_hi:[1,0,0] neg_hi:[0,0,1]
	s_nop 0
	v_pk_mul_f32 v[66:67], v[4:5], s[26:27] op_sel_hi:[1,0]
	s_nop 0
	v_pk_fma_f32 v[84:85], v[4:5], s[26:27], v[66:67] op_sel:[0,0,1] op_sel_hi:[1,0,0] neg_lo:[0,0,1]
	v_pk_mul_f32 v[66:67], v[86:87], s[22:23] op_sel_hi:[1,0]
	v_pk_fma_f32 v[110:111], v[86:87], s[14:15], v[66:67] op_sel:[0,0,1] op_sel_hi:[1,0,0] neg_hi:[0,0,1]
	v_pk_add_f32 v[4:5], v[0:1], v[84:85]
	v_pk_mul_f32 v[66:67], v[70:71], s[26:27] op_sel_hi:[1,0]
	v_pk_add_f32 v[0:1], v[0:1], v[84:85] neg_lo:[0,1] neg_hi:[0,1]
	v_pk_fma_f32 v[86:87], v[70:71], s[26:27], v[66:67] op_sel:[0,0,1] op_sel_hi:[1,0,0] neg_lo:[0,0,1]
	s_nop 0
	v_pk_mul_f32 v[66:67], v[6:7], s[30:31] op_sel:[1,0]
	v_pk_add_f32 v[64:65], v[76:77], v[86:87] neg_lo:[0,1] neg_hi:[0,1]
	v_pk_fma_f32 v[6:7], v[6:7], s[28:29], v[66:67] op_sel_hi:[0,1,1]
	v_pk_add_f32 v[66:67], v[54:55], v[58:59]
	v_pk_add_f32 v[54:55], v[54:55], v[58:59] neg_lo:[0,1] neg_hi:[0,1]
	v_pk_add_f32 v[58:59], v[56:57], v[60:61]
	v_pk_add_f32 v[56:57], v[56:57], v[60:61] neg_lo:[0,1] neg_hi:[0,1]
	s_nop 0
	v_xor_b32_e32 v61, 0x80000000, v56
	v_mov_b32_e32 v60, v57
	v_pk_add_f32 v[56:57], v[66:67], v[58:59]
	v_pk_add_f32 v[70:71], v[54:55], v[60:61]
	v_pk_add_f32 v[58:59], v[66:67], v[58:59] neg_lo:[0,1] neg_hi:[0,1]
	v_pk_add_f32 v[54:55], v[54:55], v[60:61] neg_lo:[0,1] neg_hi:[0,1]
	v_pk_add_f32 v[60:61], v[106:107], v[72:73]
	v_pk_add_f32 v[66:67], v[106:107], v[72:73] neg_lo:[0,1] neg_hi:[0,1]
	v_pk_add_f32 v[72:73], v[74:75], v[110:111]
	v_pk_add_f32 v[74:75], v[74:75], v[110:111] neg_lo:[0,1] neg_hi:[0,1]
	s_nop 0
	v_xor_b32_e32 v107, 0x80000000, v74
	v_mov_b32_e32 v106, v75
	v_pk_add_f32 v[74:75], v[60:61], v[72:73]
	v_pk_add_f32 v[60:61], v[60:61], v[72:73] neg_lo:[0,1] neg_hi:[0,1]
	v_pk_add_f32 v[72:73], v[62:63], v[2:3]
	v_pk_add_f32 v[2:3], v[62:63], v[2:3] neg_lo:[0,1] neg_hi:[0,1]
	v_pk_add_f32 v[62:63], v[76:77], v[86:87]
	v_xor_b32_e32 v77, 0x80000000, v64
	v_mov_b32_e32 v76, v65
	v_pk_add_f32 v[64:65], v[72:73], v[62:63]
	v_pk_add_f32 v[62:63], v[72:73], v[62:63] neg_lo:[0,1] neg_hi:[0,1]
	v_pk_add_f32 v[72:73], v[108:109], v[6:7]
	v_pk_add_f32 v[6:7], v[108:109], v[6:7] neg_lo:[0,1] neg_hi:[0,1]
	v_pk_add_f32 v[86:87], v[2:3], v[76:77]
	v_pk_add_f32 v[2:3], v[2:3], v[76:77] neg_lo:[0,1] neg_hi:[0,1]
	v_xor_b32_e32 v77, 0x80000000, v6
	v_mov_b32_e32 v76, v7
	v_pk_add_f32 v[6:7], v[4:5], v[72:73]
	v_pk_add_f32 v[4:5], v[4:5], v[72:73] neg_lo:[0,1] neg_hi:[0,1]
	v_add_u32_e32 v72, s18, v91
	v_add3_u32 v8, v72, v8, v112
	v_pk_add_f32 v[110:111], v[66:67], v[106:107]
	v_pk_add_f32 v[66:67], v[66:67], v[106:107] neg_lo:[0,1] neg_hi:[0,1]
	v_pk_add_f32 v[84:85], v[0:1], v[76:77]
	v_pk_add_f32 v[0:1], v[0:1], v[76:77] neg_lo:[0,1] neg_hi:[0,1]
	ds_write2_b64 v8, v[56:57], v[74:75] offset1:1
	ds_write2_b64 v8, v[64:65], v[6:7] offset0:2 offset1:3
	ds_write2_b64 v8, v[70:71], v[110:111] offset0:4 offset1:5
	ds_write2_b64 v8, v[86:87], v[84:85] offset0:6 offset1:7
	ds_write2_b64 v8, v[58:59], v[60:61] offset0:8 offset1:9
	ds_write2_b64 v8, v[62:63], v[4:5] offset0:10 offset1:11
	ds_write2_b64 v8, v[54:55], v[66:67] offset0:12 offset1:13
	ds_write2_b64 v8, v[2:3], v[0:1] offset0:14 offset1:15
.LBB0_487:
	s_or_b64 exec, exec, s[2:3]
	v_mov_b32_e32 v0, v180
	s_waitcnt lgkmcnt(0)
	s_barrier
	s_nop 0
	v_cmp_gt_i32_e32 vcc, s16, v0
	s_and_saveexec_b64 s[2:3], vcc
	s_cbranch_execz .LBB0_489
	v_ashrrev_i32_e32 v1, 31, v0
	v_lshrrev_b32_e32 v1, 27, v1
	v_add_u32_e32 v1, v0, v1
	v_lshrrev_b32_e32 v2, 5, v1
	v_and_b32_e32 v1, 0xffffffe0, v1
	v_sub_u32_e32 v0, v0, v1
	v_lshrrev_b16_sdwa v1, v175, sext(v0) dst_sel:DWORD dst_unused:UNUSED_PAD src0_sel:DWORD src1_sel:BYTE_0
	v_and_b32_e32 v1, 15, v1
	v_add_u16_e32 v1, v0, v1
	v_ashrrev_i16_sdwa v8, v176, sext(v1) dst_sel:DWORD dst_unused:UNUSED_PAD src0_sel:DWORD src1_sel:BYTE_0
	v_and_b32_e32 v1, 0xf0, v1
	v_sub_u16_e32 v54, v0, v1
	v_mul_lo_u32 v91, v2, s17
	v_lshlrev_b32_e32 v2, 3, v0
	v_ashrrev_i32_e32 v0, 4, v0
	v_add_u32_e32 v1, s18, v91
	v_lshlrev_b32_e32 v0, 3, v0
	v_bfe_i32 v106, v54, 0, 8
	v_add3_u32 v4, v1, v2, v0
	v_mad_i32_i24 v107, v106, s19, 0
	ds_read2_b64 v[0:3], v4 offset1:34
	ds_read2_b64 v[58:61], v4 offset0:68 offset1:102
	ds_read2_b64 v[70:73], v4 offset0:136 offset1:170
	ds_read2_b64 v[74:77], v4 offset0:204 offset1:238
	v_add_u32_e32 v4, 0x800, v4
	v_add_u32_e32 v54, 0x808, v107
	ds_read2_b64 v[84:87], v4 offset0:16 offset1:50
	ds_read2_b64 v[108:111], v4 offset0:84 offset1:118
	ds_read2_b64 v[112:115], v4 offset0:152 offset1:186
	ds_read2_b64 v[4:7], v4 offset0:220 offset1:254
	ds_read2_b64 v[62:65], v54 offset1:1
	s_mov_b32 s31, s28
	s_mov_b32 s29, s14
	v_bfe_i32 v8, v8, 0, 16
	v_lshl_add_u32 v8, v8, 8, v106
	s_waitcnt lgkmcnt(0)
	v_pk_mul_f32 v[54:55], v[2:3], v[62:63] op_sel:[1,1] op_sel_hi:[1,0]
	s_nop 0
	v_pk_fma_f32 v[56:57], v[2:3], v[62:63], v[54:55] op_sel_hi:[0,1,1] neg_lo:[0,0,1]
	v_pk_mul_f32 v[2:3], v[58:59], v[64:65] op_sel:[1,1] op_sel_hi:[1,0]
	s_nop 0
	v_pk_fma_f32 v[54:55], v[58:59], v[64:65], v[2:3] neg_lo:[0,0,1] neg_hi:[0,0,1]
	v_pk_fma_f32 v[2:3], v[58:59], v[64:65], v[2:3] op_sel_hi:[0,1,1]
	v_add_u32_e32 v2, 0x818, v107
	ds_read2_b64 v[64:67], v2 offset1:1
	v_mov_b32_e32 v55, v3
	s_waitcnt lgkmcnt(0)
	v_pk_mul_f32 v[58:59], v[60:61], v[64:65] op_sel:[1,1] op_sel_hi:[1,0]
	s_nop 0
	v_pk_fma_f32 v[2:3], v[60:61], v[64:65], v[58:59] op_sel_hi:[0,1,1] neg_lo:[0,0,1]
	v_pk_mul_f32 v[58:59], v[70:71], v[66:67] op_sel:[1,1] op_sel_hi:[1,0]
	s_nop 0
	v_pk_fma_f32 v[64:65], v[70:71], v[66:67], v[58:59] neg_lo:[0,0,1] neg_hi:[0,0,1]
	v_pk_fma_f32 v[58:59], v[70:71], v[66:67], v[58:59] op_sel_hi:[0,1,1]
	v_add_u32_e32 v58, 0x828, v107
	ds_read2_b64 v[116:119], v58 offset1:1
	v_mov_b32_e32 v65, v59
	s_waitcnt lgkmcnt(0)
	v_pk_mul_f32 v[58:59], v[72:73], v[116:117] op_sel:[1,1] op_sel_hi:[1,0]
	s_nop 0
	v_pk_fma_f32 v[62:63], v[72:73], v[116:117], v[58:59] op_sel_hi:[0,1,1] neg_lo:[0,0,1]
	v_pk_mul_f32 v[58:59], v[74:75], v[118:119] op_sel:[1,1] op_sel_hi:[1,0]
	s_nop 0
	v_pk_fma_f32 v[60:61], v[74:75], v[118:119], v[58:59] neg_lo:[0,0,1] neg_hi:[0,0,1]
	v_pk_fma_f32 v[58:59], v[74:75], v[118:119], v[58:59] op_sel_hi:[0,1,1]
	v_add_u32_e32 v58, 0x838, v107
	ds_read2_b64 v[70:73], v58 offset1:1
	v_mov_b32_e32 v61, v59
	s_waitcnt lgkmcnt(0)
	v_pk_mul_f32 v[66:67], v[76:77], v[70:71] op_sel:[1,1] op_sel_hi:[1,0]
	s_nop 0
	v_pk_fma_f32 v[58:59], v[76:77], v[70:71], v[66:67] op_sel_hi:[0,1,1] neg_lo:[0,0,1]
	v_pk_mul_f32 v[66:67], v[84:85], v[72:73] op_sel:[1,1] op_sel_hi:[1,0]
	s_nop 0
	v_pk_fma_f32 v[74:75], v[84:85], v[72:73], v[66:67] neg_lo:[0,0,1] neg_hi:[0,0,1]
	v_pk_fma_f32 v[66:67], v[84:85], v[72:73], v[66:67] op_sel_hi:[0,1,1]
	v_add_u32_e32 v66, 0x848, v107
	ds_read2_b64 v[116:119], v66 offset1:1
	v_mov_b32_e32 v75, v67
	s_waitcnt lgkmcnt(0)
	v_pk_mul_f32 v[66:67], v[86:87], v[116:117] op_sel:[1,1] op_sel_hi:[1,0]
	s_nop 0
	v_pk_fma_f32 v[72:73], v[86:87], v[116:117], v[66:67] op_sel_hi:[0,1,1] neg_lo:[0,0,1]
	v_pk_mul_f32 v[66:67], v[108:109], v[118:119] op_sel:[1,1] op_sel_hi:[1,0]
	s_nop 0
	v_pk_fma_f32 v[70:71], v[108:109], v[118:119], v[66:67] neg_lo:[0,0,1] neg_hi:[0,0,1]
	v_pk_fma_f32 v[66:67], v[108:109], v[118:119], v[66:67] op_sel_hi:[0,1,1]
	v_add_u32_e32 v66, 0x858, v107
	ds_read2_b64 v[116:119], v66 offset1:1
	v_mov_b32_e32 v71, v67
	s_waitcnt lgkmcnt(0)
	v_pk_mul_f32 v[76:77], v[110:111], v[116:117] op_sel:[1,1] op_sel_hi:[1,0]
	s_nop 0
	v_pk_fma_f32 v[66:67], v[110:111], v[116:117], v[76:77] op_sel_hi:[0,1,1] neg_lo:[0,0,1]
	v_pk_mul_f32 v[76:77], v[112:113], v[118:119] op_sel:[1,1] op_sel_hi:[1,0]
	s_nop 0
	v_pk_fma_f32 v[86:87], v[112:113], v[118:119], v[76:77] neg_lo:[0,0,1] neg_hi:[0,0,1]
	v_pk_fma_f32 v[76:77], v[112:113], v[118:119], v[76:77] op_sel_hi:[0,1,1]
	v_add_u32_e32 v76, 0x868, v107
	ds_read2_b64 v[108:111], v76 offset1:1
	v_mov_b32_e32 v87, v77
	s_waitcnt lgkmcnt(0)
	v_pk_mul_f32 v[76:77], v[114:115], v[108:109] op_sel:[1,1] op_sel_hi:[1,0]
	s_nop 0
	v_pk_fma_f32 v[84:85], v[114:115], v[108:109], v[76:77] op_sel_hi:[0,1,1] neg_lo:[0,0,1]
	v_pk_mul_f32 v[108:109], v[4:5], v[110:111] op_sel:[1,1] op_sel_hi:[1,0]
	v_pk_fma_f32 v[76:77], v[4:5], v[110:111], v[108:109] op_sel_hi:[0,1,1] neg_lo:[0,0,1]
	ds_read_b64 v[4:5], v107 offset:2168
	s_waitcnt lgkmcnt(0)
	v_pk_mul_f32 v[108:109], v[6:7], v[4:5] op_sel:[1,1] op_sel_hi:[1,0]
	s_nop 0
	v_pk_fma_f32 v[110:111], v[6:7], v[4:5], v[108:109] op_sel_hi:[0,1,1] neg_lo:[0,0,1]
	v_pk_add_f32 v[4:5], v[0:1], v[74:75]
	v_pk_add_f32 v[6:7], v[64:65], v[86:87]
	v_pk_add_f32 v[64:65], v[64:65], v[86:87] neg_lo:[0,1] neg_hi:[0,1]
	v_pk_add_f32 v[0:1], v[0:1], v[74:75] neg_lo:[0,1] neg_hi:[0,1]
	v_xor_b32_e32 v75, 0x80000000, v64
	v_mov_b32_e32 v74, v65
	v_pk_add_f32 v[64:65], v[4:5], v[6:7]
	v_pk_add_f32 v[4:5], v[4:5], v[6:7] neg_lo:[0,1] neg_hi:[0,1]
	v_pk_add_f32 v[6:7], v[56:57], v[72:73]
	v_pk_add_f32 v[56:57], v[56:57], v[72:73] neg_lo:[0,1] neg_hi:[0,1]
	v_pk_add_f32 v[72:73], v[62:63], v[84:85]
	v_pk_add_f32 v[62:63], v[62:63], v[84:85] neg_lo:[0,1] neg_hi:[0,1]
	v_pk_add_f32 v[86:87], v[0:1], v[74:75]
	v_pk_add_f32 v[0:1], v[0:1], v[74:75] neg_lo:[0,1] neg_hi:[0,1]
	v_xor_b32_e32 v75, 0x80000000, v62
	v_mov_b32_e32 v74, v63
	v_pk_add_f32 v[62:63], v[6:7], v[72:73]
	v_pk_add_f32 v[6:7], v[6:7], v[72:73] neg_lo:[0,1] neg_hi:[0,1]
	v_pk_add_f32 v[72:73], v[54:55], v[70:71]
	v_pk_add_f32 v[54:55], v[54:55], v[70:71] neg_lo:[0,1] neg_hi:[0,1]
	v_pk_add_f32 v[70:71], v[60:61], v[76:77]
	v_pk_add_f32 v[60:61], v[60:61], v[76:77] neg_lo:[0,1] neg_hi:[0,1]
	v_pk_add_f32 v[84:85], v[56:57], v[74:75]
	v_pk_add_f32 v[56:57], v[56:57], v[74:75] neg_lo:[0,1] neg_hi:[0,1]
	v_xor_b32_e32 v75, 0x80000000, v60
	v_mov_b32_e32 v74, v61
	v_pk_add_f32 v[60:61], v[72:73], v[70:71]
	v_pk_add_f32 v[70:71], v[72:73], v[70:71] neg_lo:[0,1] neg_hi:[0,1]
	v_pk_add_f32 v[72:73], v[2:3], v[66:67]
	v_pk_add_f32 v[2:3], v[2:3], v[66:67] neg_lo:[0,1] neg_hi:[0,1]
	v_pk_add_f32 v[66:67], v[58:59], v[110:111]
	v_pk_add_f32 v[58:59], v[58:59], v[110:111] neg_lo:[0,1] neg_hi:[0,1]
	v_pk_add_f32 v[76:77], v[54:55], v[74:75]
	v_pk_add_f32 v[54:55], v[54:55], v[74:75] neg_lo:[0,1] neg_hi:[0,1]
	v_xor_b32_e32 v75, 0x80000000, v58
	v_mov_b32_e32 v74, v59
	v_pk_add_f32 v[58:59], v[72:73], v[66:67]
	v_pk_add_f32 v[66:67], v[72:73], v[66:67] neg_lo:[0,1] neg_hi:[0,1]
	v_pk_mul_f32 v[72:73], v[84:85], s[14:15] op_sel_hi:[1,0]
	v_pk_add_f32 v[108:109], v[2:3], v[74:75]
	v_pk_add_f32 v[2:3], v[2:3], v[74:75] neg_lo:[0,1] neg_hi:[0,1]
	v_pk_fma_f32 v[74:75], v[84:85], s[22:23], v[72:73] op_sel:[0,0,1] op_sel_hi:[1,0,0] neg_hi:[0,0,1]
	s_nop 0
	v_pk_mul_f32 v[72:73], v[6:7], s[24:25] op_sel_hi:[1,0]
	s_nop 0
	v_pk_fma_f32 v[84:85], v[6:7], s[24:25], v[72:73] op_sel:[0,0,1] op_sel_hi:[1,0,0] neg_hi:[0,0,1]
	v_pk_mul_f32 v[72:73], v[56:57], s[22:23] op_sel_hi:[1,0]
	v_pk_fma_f32 v[110:111], v[56:57], s[14:15], v[72:73] op_sel:[0,0,1] op_sel_hi:[1,0,0] neg_hi:[0,0,1]
	s_nop 0
	v_pk_mul_f32 v[56:57], v[76:77], s[24:25] op_sel_hi:[1,0]
	s_nop 0
	v_pk_fma_f32 v[72:73], v[76:77], s[24:25], v[56:57] op_sel:[0,0,1] op_sel_hi:[1,0,0] neg_hi:[0,0,1]
	s_nop 0
	v_pk_fma_f32 v[56:57], v[70:71], 0, v[70:71] op_sel:[0,0,1] op_sel_hi:[1,0,0] neg_hi:[0,0,1]
	s_nop 0
	v_pk_mul_f32 v[70:71], v[54:55], s[26:27] op_sel_hi:[1,0]
	s_nop 0
	v_pk_fma_f32 v[76:77], v[54:55], s[26:27], v[70:71] op_sel:[0,0,1] op_sel_hi:[1,0,0] neg_lo:[0,0,1]
	v_pk_mul_f32 v[70:71], v[108:109], s[22:23] op_sel_hi:[1,0]
	v_pk_fma_f32 v[112:113], v[108:109], s[14:15], v[70:71] op_sel:[0,0,1] op_sel_hi:[1,0,0] neg_hi:[0,0,1]
	v_pk_add_f32 v[54:55], v[0:1], v[76:77]
	v_pk_mul_f32 v[70:71], v[66:67], s[26:27] op_sel_hi:[1,0]
	v_pk_add_f32 v[0:1], v[0:1], v[76:77] neg_lo:[0,1] neg_hi:[0,1]
	v_pk_fma_f32 v[108:109], v[66:67], s[26:27], v[70:71] op_sel:[0,0,1] op_sel_hi:[1,0,0] neg_lo:[0,0,1]
	s_nop 0
	v_pk_mul_f32 v[66:67], v[2:3], s[30:31] op_sel:[1,0]
	v_pk_add_f32 v[6:7], v[84:85], v[108:109]
	v_pk_fma_f32 v[2:3], v[2:3], s[28:29], v[66:67] op_sel_hi:[0,1,1]
	v_pk_add_f32 v[66:67], v[64:65], v[60:61]
	v_pk_add_f32 v[60:61], v[64:65], v[60:61] neg_lo:[0,1] neg_hi:[0,1]
	v_pk_add_f32 v[64:65], v[62:63], v[58:59]
	v_pk_add_f32 v[58:59], v[62:63], v[58:59] neg_lo:[0,1] neg_hi:[0,1]
	s_nop 0
	v_xor_b32_e32 v63, 0x80000000, v58
	v_mov_b32_e32 v62, v59
	v_pk_add_f32 v[58:59], v[66:67], v[64:65]
	v_pk_add_f32 v[70:71], v[60:61], v[62:63]
	v_pk_add_f32 v[64:65], v[66:67], v[64:65] neg_lo:[0,1] neg_hi:[0,1]
	v_pk_add_f32 v[60:61], v[60:61], v[62:63] neg_lo:[0,1] neg_hi:[0,1]
	v_pk_add_f32 v[62:63], v[86:87], v[72:73]
	v_pk_add_f32 v[66:67], v[86:87], v[72:73] neg_lo:[0,1] neg_hi:[0,1]
	v_pk_add_f32 v[72:73], v[74:75], v[112:113]
	v_pk_add_f32 v[74:75], v[74:75], v[112:113] neg_lo:[0,1] neg_hi:[0,1]
	s_nop 0
	v_xor_b32_e32 v87, 0x80000000, v74
	v_mov_b32_e32 v86, v75
	v_pk_add_f32 v[74:75], v[62:63], v[72:73]
	v_pk_add_f32 v[62:63], v[62:63], v[72:73] neg_lo:[0,1] neg_hi:[0,1]
	v_pk_add_f32 v[72:73], v[4:5], v[56:57]
	v_pk_add_f32 v[4:5], v[4:5], v[56:57] neg_lo:[0,1] neg_hi:[0,1]
	v_pk_add_f32 v[56:57], v[84:85], v[108:109] neg_lo:[0,1] neg_hi:[0,1]
	v_pk_add_f32 v[112:113], v[66:67], v[86:87]
	v_xor_b32_e32 v85, 0x80000000, v56
	v_mov_b32_e32 v84, v57
	v_pk_add_f32 v[56:57], v[72:73], v[6:7]
	v_pk_add_f32 v[6:7], v[72:73], v[6:7] neg_lo:[0,1] neg_hi:[0,1]
	v_pk_add_f32 v[72:73], v[110:111], v[2:3]
	v_pk_add_f32 v[2:3], v[110:111], v[2:3] neg_lo:[0,1] neg_hi:[0,1]
	v_pk_add_f32 v[66:67], v[66:67], v[86:87] neg_lo:[0,1] neg_hi:[0,1]
	v_xor_b32_e32 v77, 0x80000000, v2
	v_mov_b32_e32 v76, v3
	v_pk_add_f32 v[2:3], v[54:55], v[72:73]
	v_pk_add_f32 v[54:55], v[54:55], v[72:73] neg_lo:[0,1] neg_hi:[0,1]
	v_lshlrev_b32_e32 v73, 3, v8
	v_ashrrev_i32_e32 v8, 4, v8
	v_add_u32_e32 v72, 0, v91
	v_lshlrev_b32_e32 v8, 3, v8
	v_add3_u32 v8, v72, v73, v8
	v_add_u32_e32 v72, 0x1800, v8
	v_pk_add_f32 v[86:87], v[4:5], v[84:85]
	v_pk_add_f32 v[4:5], v[4:5], v[84:85] neg_lo:[0,1] neg_hi:[0,1]
	v_pk_add_f32 v[84:85], v[0:1], v[76:77]
	v_pk_add_f32 v[0:1], v[0:1], v[76:77] neg_lo:[0,1] neg_hi:[0,1]
	ds_write2_b64 v72, v[58:59], v[74:75] offset0:16 offset1:33
	ds_write2_b64 v72, v[56:57], v[2:3] offset0:50 offset1:67
	ds_write2_b64 v72, v[70:71], v[112:113] offset0:84 offset1:101
	ds_write2_b64 v72, v[86:87], v[84:85] offset0:118 offset1:135
	ds_write2_b64 v72, v[64:65], v[62:63] offset0:152 offset1:169
	ds_write2_b64 v72, v[6:7], v[54:55] offset0:186 offset1:203
	ds_write2_b64 v72, v[60:61], v[66:67] offset0:220 offset1:237
	v_add_u32_e32 v2, 0x1c00, v8
	ds_write2_b64 v2, v[4:5], v[0:1] offset0:126 offset1:143
